# v61 + P11 rebalanced: sample row blocks of rw_post as 64 one-batch pieces on workgroups 0..63, reversed tile map for the FFN2 weight transposes
# baseline (speedup 1.0000x reference)
; #define LAS __attribute__((address_space(3)))
; __device__ __forceinline__ float bf2f(bf16 x) { return __uint_as_float(((unsigned)x) << 16); }
; __device__ __forceinline__ unsigned f2bf(float f) { return cvt_pk_bf16(f, 0.f) & 0xffffu; }
; #define POST_LD(Y_, V_, G_, R_, C_, t) do { _Pragma("unroll") for (int q = 0; q < 8; ++q) { const size_t o_ = (size_t)((t) + q) * DH; Y_[q] = yp[o_]; V_[q] = vp[o_]; G_[q] = gp[o_]; R_[q] = rp[((t) + q) * 32]; C_[q] = cp[o_]; } } while (0)
; __device__ __forceinline__ void rw_post(Frame& F) {
;     ...
;         POST_LD(y, vv, gg, rk, cc, 0);
;         for (int t0 = 0; t0 < 64; t0 += 8) {
;             float ny[8], nv[8], nr[8], nc[8]; bf16 ng[8];
;             const int tn = t0 + 8 < 64 ? t0 + 8 : t0;
;             POST_LD(ny, nv, ng, nr, nc, tn);
;             if (k > 0) {
;                 LAS float* cs = (LAS float*)(F.lds + 131072 + F.wave * 1024);
; #pragma unroll
;                 for (int hf = 0; hf < 2; ++hf) {
; #pragma unroll
;                     for (int q = 0; q < 4; ++q) cs[q * 64 + lane] = cc[4 * hf + q];
;                     asm volatile("s_waitcnt lgkmcnt(0)" ::: "memory");
; #pragma unroll
;                     for (int q = 0; q < 4; ++q) { f32x4 a = (f32x4){0.f, 0.f, 0.f, 0.f};
; #pragma unroll
;                         for (int i = 0; i < 16; ++i) a = __builtin_elementwise_fma(Sr[i], *(const LAS f32x4*)(cs + q * 64 + 4 * i), a);
;                         y[4 * hf + q] += (a[0] + a[1]) + (a[2] + a[3]); }
;                     asm volatile("s_waitcnt lgkmcnt(0)" ::: "memory"); }
;             }
; #pragma unroll
;             for (int q = 0; q < 8; ++q) { const int row = rb0 + t0 + q;
;                 const float mean = wsum(y[q]) * (1.f / 64.f); const float dv = y[q] - mean; const float var = wsum(dv * dv) * (1.f / 64.f);
;                 const float yn = dv * (1.f / sqrtf(var + 64e-5f)) * g_ + b_;
;                 OB[(size_t)row * DH + col] = (bf16)f2bf((yn + rk[q] * vv[q]) * bf2f(gg[q])); }
.Lpo_s1done:
	s_barrier
	global_load_dwordx4 v[120:123], v11, s[6:7]
	global_load_dwordx4 v[124:127], v11, s[6:7] offset:1024
	global_load_dwordx4 v[128:131], v11, s[8:9]
	global_load_dwordx4 v[132:135], v11, s[8:9] offset:1024
	global_load_dwordx4 v[136:139], v11, s[10:11]
	global_load_dword v159, v158, s[12:13]
	s_add_u32 s6, s6, 0x10000
	s_addc_u32 s7, s7, 0
	s_add_u32 s8, s8, 0x10000
	s_addc_u32 s9, s9, 0
	s_add_u32 s10, s10, 0x8000
	s_addc_u32 s11, s11, 0
	s_add_u32 s12, s12, 0x400
	s_addc_u32 s13, s13, 0
	s_waitcnt vmcnt(0)
	s_waitcnt vmcnt(8)
	ds_write_b128 v12, v[120:123] offset:0
	ds_write_b128 v12, v[124:127] offset:1024
	ds_write_b128 v12, v[128:131] offset:16384
	ds_write_b128 v12, v[132:135] offset:17408
	ds_write_b128 v14, v[136:139]
	v_readlane_b32 s69, v159, 0
	v_readlane_b32 s70, v159, 1
	v_readlane_b32 s71, v159, 2
	v_readlane_b32 s72, v159, 3
	v_readlane_b32 s73, v159, 4
	v_readlane_b32 s26, v159, 5
	v_readlane_b32 s27, v159, 6
	v_readlane_b32 s32, v159, 7
	global_load_dwordx4 v[120:123], v11, s[6:7]
	global_load_dwordx4 v[124:127], v11, s[6:7] offset:1024
	global_load_dwordx4 v[128:131], v11, s[8:9]
	global_load_dwordx4 v[132:135], v11, s[8:9] offset:1024
	global_load_dwordx4 v[136:139], v11, s[10:11]
	global_load_dword v159, v158, s[12:13]
	s_add_u32 s6, s6, 0x10000
	s_addc_u32 s7, s7, 0
	s_add_u32 s8, s8, 0x10000
	s_addc_u32 s9, s9, 0
	s_add_u32 s10, s10, 0x8000
	s_addc_u32 s11, s11, 0
	s_add_u32 s12, s12, 0x400
	s_addc_u32 s13, s13, 0
	s_waitcnt lgkmcnt(0)
	s_barrier
	ds_read_b32 v80, v154 offset:0
	ds_read_b32 v81, v154 offset:16384
	ds_read_u16 v83, v156 offset:0
	ds_read_b32 v85, v154 offset:2048
	ds_read_b32 v86, v154 offset:18432
	ds_read_u16 v88, v156 offset:1024
	ds_read_b32 v90, v154 offset:4096
	ds_read_b32 v91, v154 offset:20480
	ds_read_u16 v93, v156 offset:2048
	ds_read_b32 v95, v154 offset:6144
	ds_read_b32 v96, v154 offset:22528
	ds_read_u16 v98, v156 offset:3072
	ds_read_b32 v100, v154 offset:8192
	ds_read_b32 v101, v154 offset:24576
	ds_read_u16 v103, v156 offset:4096
	ds_read_b32 v105, v154 offset:10240
	ds_read_b32 v106, v154 offset:26624
	ds_read_u16 v108, v156 offset:5120
	ds_read_b32 v110, v154 offset:12288
	ds_read_b32 v111, v154 offset:28672
	ds_read_u16 v113, v156 offset:6144
	ds_read_b32 v115, v154 offset:14336
	ds_read_b32 v116, v154 offset:30720
	ds_read_u16 v118, v156 offset:7168
	s_waitcnt lgkmcnt(0)
	v_add_f32_e32 v80, v80, v16
	v_add_f32_e32 v85, v85, v17
	v_add_f32_e32 v90, v90, v18
	v_add_f32_e32 v95, v95, v19
	v_add_f32_dpp v168, v80, v80 quad_perm:[1,0,3,2] row_mask:0xf bank_mask:0xf bound_ctrl:1
	v_add_f32_dpp v174, v85, v85 quad_perm:[1,0,3,2] row_mask:0xf bank_mask:0xf bound_ctrl:1
	v_add_f32_dpp v241, v90, v90 quad_perm:[1,0,3,2] row_mask:0xf bank_mask:0xf bound_ctrl:1
	v_add_f32_dpp v247, v95, v95 quad_perm:[1,0,3,2] row_mask:0xf bank_mask:0xf bound_ctrl:1
	v_add_f32_dpp v168, v168, v168 quad_perm:[2,3,0,1] row_mask:0xf bank_mask:0xf bound_ctrl:1
	v_add_f32_dpp v174, v174, v174 quad_perm:[2,3,0,1] row_mask:0xf bank_mask:0xf bound_ctrl:1
	v_add_f32_dpp v241, v241, v241 quad_perm:[2,3,0,1] row_mask:0xf bank_mask:0xf bound_ctrl:1
	v_add_f32_dpp v247, v247, v247 quad_perm:[2,3,0,1] row_mask:0xf bank_mask:0xf bound_ctrl:1
	v_add_f32_dpp v168, v168, v168 row_half_mirror row_mask:0xf bank_mask:0xf bound_ctrl:1
	v_add_f32_dpp v174, v174, v174 row_half_mirror row_mask:0xf bank_mask:0xf bound_ctrl:1
	v_add_f32_dpp v241, v241, v241 row_half_mirror row_mask:0xf bank_mask:0xf bound_ctrl:1
	v_add_f32_dpp v247, v247, v247 row_half_mirror row_mask:0xf bank_mask:0xf bound_ctrl:1
	v_add_f32_dpp v168, v168, v168 row_mirror row_mask:0xf bank_mask:0xf bound_ctrl:1
	v_add_f32_dpp v174, v174, v174 row_mirror row_mask:0xf bank_mask:0xf bound_ctrl:1
	v_add_f32_dpp v241, v241, v241 row_mirror row_mask:0xf bank_mask:0xf bound_ctrl:1
	v_add_f32_dpp v247, v247, v247 row_mirror row_mask:0xf bank_mask:0xf bound_ctrl:1
	v_readlane_b32 s36, v168, 16
	v_readlane_b32 s40, v174, 16
	v_readlane_b32 s44, v241, 16
	v_readlane_b32 s48, v247, 16
	v_readlane_b32 s37, v168, 48
	v_readlane_b32 s41, v174, 48
	v_readlane_b32 s45, v241, 48
	v_readlane_b32 s49, v247, 48
	v_readlane_b32 s38, v168, 0
	v_readlane_b32 s42, v174, 0
	v_readlane_b32 s46, v241, 0
	v_readlane_b32 s50, v247, 0
	v_readlane_b32 s39, v168, 32
	v_readlane_b32 s43, v174, 32
	v_readlane_b32 s47, v241, 32
	v_readlane_b32 s51, v247, 32
	v_mov_b32_e32 v168, s36
	v_mov_b32_e32 v174, s40
	v_mov_b32_e32 v241, s44
	v_mov_b32_e32 v247, s48
	v_mov_b32_e32 v169, s37
	v_mov_b32_e32 v175, s41
	v_mov_b32_e32 v242, s45
	v_mov_b32_e32 v248, s49
	v_add_f32_e32 v168, s38, v168
	v_add_f32_e32 v174, s42, v174
	v_add_f32_e32 v241, s46, v241
	v_add_f32_e32 v247, s50, v247
	v_add_f32_e32 v169, s39, v169
	v_add_f32_e32 v175, s43, v175
	v_add_f32_e32 v242, s47, v242
	v_add_f32_e32 v248, s51, v248
	v_add_f32_e32 v168, v168, v169
	v_add_f32_e32 v174, v174, v175
	v_add_f32_e32 v241, v241, v242
	v_add_f32_e32 v247, v247, v248
	v_fmamk_f32 v80, v168, 0xbc800000, v80
	v_fmamk_f32 v85, v174, 0xbc800000, v85
	v_fmamk_f32 v90, v241, 0xbc800000, v90
	v_fmamk_f32 v95, v247, 0xbc800000, v95
	v_mul_f32_e32 v168, v80, v80
	v_mul_f32_e32 v174, v85, v85
	v_mul_f32_e32 v241, v90, v90
	v_mul_f32_e32 v247, v95, v95
	v_mov_b32_dpp v168, v168 quad_perm:[1,0,3,2] row_mask:0xf bank_mask:0xf bound_ctrl:1
	v_mov_b32_dpp v174, v174 quad_perm:[1,0,3,2] row_mask:0xf bank_mask:0xf bound_ctrl:1
	v_mov_b32_dpp v241, v241 quad_perm:[1,0,3,2] row_mask:0xf bank_mask:0xf bound_ctrl:1
	v_mov_b32_dpp v247, v247 quad_perm:[1,0,3,2] row_mask:0xf bank_mask:0xf bound_ctrl:1
	v_fmac_f32_e32 v168, v80, v80
; __device__ __forceinline__ float bf2f(bf16 x) { return __uint_as_float(((unsigned)x) << 16); }
; __device__ __forceinline__ unsigned f2bf(float f) { return cvt_pk_bf16(f, 0.f) & 0xffffu; }
; __device__ __forceinline__ float dpp_xor1(float x) { return __builtin_bit_cast(float, __builtin_amdgcn_update_dpp(0, __builtin_bit_cast(int, x), 0xB1, 0xF, 0xF, true)); }
; __device__ __forceinline__ float dpp_xor2(float x) { return __builtin_bit_cast(float, __builtin_amdgcn_update_dpp(0, __builtin_bit_cast(int, x), 0x4E, 0xF, 0xF, true)); }
; __device__ __forceinline__ float dpp_hmir(float x) { return __builtin_bit_cast(float, __builtin_amdgcn_update_dpp(0, __builtin_bit_cast(int, x), 0x141, 0xF, 0xF, true)); }
; __device__ __forceinline__ float dpp_mir(float x)  { return __builtin_bit_cast(float, __builtin_amdgcn_update_dpp(0, __builtin_bit_cast(int, x), 0x140, 0xF, 0xF, true)); }
; __device__ __forceinline__ float red16(float x) { x += dpp_xor1(x); x += dpp_xor2(x); x += dpp_hmir(x); x += dpp_mir(x); return x; }
; __device__ __forceinline__ float wsum(float x) {
;     x = red16(x); const int xi = __builtin_bit_cast(int, x);
;     const float r0 = __builtin_bit_cast(float, __builtin_amdgcn_readlane(xi, 0)), r1 = __builtin_bit_cast(float, __builtin_amdgcn_readlane(xi, 16));
;     const float r2 = __builtin_bit_cast(float, __builtin_amdgcn_readlane(xi, 32)), r3 = __builtin_bit_cast(float, __builtin_amdgcn_readlane(xi, 48));
;     return (r0 + r1) + (r2 + r3);
; }
; __device__ __forceinline__ void rw_post(Frame& F) {
;     ...
;             for (int q = 0; q < 8; ++q) { const int row = rb0 + t0 + q;
;                 const float mean = wsum(y[q]) * (1.f / 64.f); const float dv = y[q] - mean; const float var = wsum(dv * dv) * (1.f / 64.f);
;                 const float yn = dv * (1.f / sqrtf(var + 64e-5f)) * g_ + b_;
;                 OB[(size_t)row * DH + col] = (bf16)f2bf((yn + rk[q] * vv[q]) * bf2f(gg[q])); }
	v_fmac_f32_e32 v174, v85, v85
	v_fmac_f32_e32 v241, v90, v90
	v_fmac_f32_e32 v247, v95, v95
	v_add_f32_dpp v168, v168, v168 quad_perm:[2,3,0,1] row_mask:0xf bank_mask:0xf bound_ctrl:1
	v_add_f32_dpp v174, v174, v174 quad_perm:[2,3,0,1] row_mask:0xf bank_mask:0xf bound_ctrl:1
	v_add_f32_dpp v241, v241, v241 quad_perm:[2,3,0,1] row_mask:0xf bank_mask:0xf bound_ctrl:1
	v_add_f32_dpp v247, v247, v247 quad_perm:[2,3,0,1] row_mask:0xf bank_mask:0xf bound_ctrl:1
	v_add_f32_dpp v168, v168, v168 row_half_mirror row_mask:0xf bank_mask:0xf bound_ctrl:1
	v_add_f32_dpp v174, v174, v174 row_half_mirror row_mask:0xf bank_mask:0xf bound_ctrl:1
	v_add_f32_dpp v241, v241, v241 row_half_mirror row_mask:0xf bank_mask:0xf bound_ctrl:1
	v_add_f32_dpp v247, v247, v247 row_half_mirror row_mask:0xf bank_mask:0xf bound_ctrl:1
	v_add_f32_dpp v168, v168, v168 row_mirror row_mask:0xf bank_mask:0xf bound_ctrl:1
	v_add_f32_dpp v174, v174, v174 row_mirror row_mask:0xf bank_mask:0xf bound_ctrl:1
	v_add_f32_dpp v241, v241, v241 row_mirror row_mask:0xf bank_mask:0xf bound_ctrl:1
	v_add_f32_dpp v247, v247, v247 row_mirror row_mask:0xf bank_mask:0xf bound_ctrl:1
	v_readlane_b32 s36, v168, 16
	v_readlane_b32 s40, v174, 16
	v_readlane_b32 s44, v241, 16
	v_readlane_b32 s48, v247, 16
	v_readlane_b32 s37, v168, 48
	v_readlane_b32 s41, v174, 48
	v_readlane_b32 s45, v241, 48
	v_readlane_b32 s49, v247, 48
	v_readlane_b32 s38, v168, 0
	v_readlane_b32 s42, v174, 0
	v_readlane_b32 s46, v241, 0
	v_readlane_b32 s50, v247, 0
	v_readlane_b32 s39, v168, 32
	v_readlane_b32 s43, v174, 32
	v_readlane_b32 s47, v241, 32
	v_readlane_b32 s51, v247, 32
	v_mov_b32_e32 v168, s36
	v_mov_b32_e32 v174, s40
	v_mov_b32_e32 v241, s44
	v_mov_b32_e32 v247, s48
	v_mov_b32_e32 v169, s37
	v_mov_b32_e32 v175, s41
	v_mov_b32_e32 v242, s45
	v_mov_b32_e32 v248, s49
	v_add_f32_e32 v168, s38, v168
	v_add_f32_e32 v174, s42, v174
	v_add_f32_e32 v241, s46, v241
	v_add_f32_e32 v247, s50, v247
	v_add_f32_e32 v169, s39, v169
	v_add_f32_e32 v175, s43, v175
	v_add_f32_e32 v242, s47, v242
	v_add_f32_e32 v248, s51, v248
	v_add_f32_e32 v168, v168, v169
	v_add_f32_e32 v174, v174, v175
	v_add_f32_e32 v241, v241, v242
	v_add_f32_e32 v247, v247, v248
	v_fmamk_f32 v168, v168, 0x3c800000, v9
	v_fmamk_f32 v174, v174, 0x3c800000, v9
	v_fmamk_f32 v241, v241, 0x3c800000, v9
	v_fmamk_f32 v247, v247, 0x3c800000, v9
	v_readfirstlane_b32 s40, v174
	v_readfirstlane_b32 s44, v241
	v_readfirstlane_b32 s48, v247
	v_writelane_b32 v168, s40, 1
	v_writelane_b32 v168, s44, 2
	v_writelane_b32 v168, s48, 3
	v_mul_f32_e32 v169, 0x4f800000, v168
	v_cmp_gt_f32_e64 s[52:53], s68, v168
	v_mov_b32_e32 v170, v168
	s_nop 1
	v_cndmask_b32_e64 v168, v170, v169, s[52:53]
	v_sqrt_f32_e32 v169, v168
	s_nop 0
	v_add_u32_e32 v170, -1, v169
	v_fma_f32 v171, -v170, v169, v168
	v_cmp_ge_f32_e64 s[60:61], 0, v171
	v_add_u32_e32 v171, 1, v169
	s_nop 1
	v_cndmask_b32_e64 v170, v169, v170, s[60:61]
	v_fma_f32 v169, -v171, v169, v168
	v_cmp_lt_f32_e64 s[60:61], 0, v169
	s_nop 1
	v_cndmask_b32_e64 v169, v170, v171, s[60:61]
	v_mul_f32_e32 v170, 0x37800000, v169
	v_cndmask_b32_e64 v169, v169, v170, s[52:53]
	v_cmp_class_f32_e64 s[60:61], v168, v8
	s_nop 1
	v_cndmask_b32_e64 v168, v169, v168, s[60:61]
	v_div_scale_f32 v169, s[60:61], v168, v168, 1.0
	v_rcp_f32_e32 v170, v169
	s_nop 0
	v_fma_f32 v171, -v169, v170, 1.0
	v_fmac_f32_e32 v170, v171, v170
	v_div_scale_f32 v171, vcc, 1.0, v168, 1.0
	v_mul_f32_e32 v172, v171, v170
	v_fma_f32 v173, -v169, v172, v171
	v_fmac_f32_e32 v172, v173, v170
	v_fma_f32 v169, -v169, v172, v171
	v_div_fmas_f32 v169, v169, v170, v172
	v_div_fixup_f32 v168, v169, v168, 1.0
	s_nop 0
	v_readlane_b32 s37, v168, 0
	v_readlane_b32 s41, v168, 1
	v_readlane_b32 s45, v168, 2
	v_readlane_b32 s49, v168, 3
	v_mul_f32_e32 v80, s37, v80
	v_mul_f32_e32 v85, s41, v85
	v_mul_f32_e32 v90, s45, v90
	v_mul_f32_e32 v95, s49, v95
	v_lshlrev_b32_e32 v83, 16, v83
	v_lshlrev_b32_e32 v88, 16, v88
	v_lshlrev_b32_e32 v93, 16, v93
	v_lshlrev_b32_e32 v98, 16, v98
	v_fma_f32 v80, v6, v80, v7
	v_fma_f32 v85, v6, v85, v7
	v_fma_f32 v90, v6, v90, v7
	v_fma_f32 v95, v6, v95, v7
	v_fmac_f32_e32 v80, s69, v81
	v_fmac_f32_e32 v85, s70, v86
	v_fmac_f32_e32 v90, s71, v91
	v_fmac_f32_e32 v95, s72, v96
	v_mul_f32_e32 v80, v80, v83
	v_mul_f32_e32 v85, v85, v88
	v_mul_f32_e32 v90, v90, v93
	v_mul_f32_e32 v95, v95, v98
	v_cvt_pk_bf16_f32 v169, v80, v80
	v_cvt_pk_bf16_f32 v175, v85, v85
	v_cvt_pk_bf16_f32 v242, v90, v90
	v_cvt_pk_bf16_f32 v248, v95, v95
	global_store_short v2, v169, s[28:29]
	s_add_u32 s28, s28, 0x1000
	s_addc_u32 s29, s29, 0
	global_store_short v2, v175, s[28:29]
	s_add_u32 s28, s28, 0x1000
	s_addc_u32 s29, s29, 0
	global_store_short v2, v242, s[28:29]
	s_add_u32 s28, s28, 0x1000
	s_addc_u32 s29, s29, 0
	global_store_short v2, v248, s[28:29]
	s_add_u32 s28, s28, 0x1000
	s_addc_u32 s29, s29, 0
	v_add_f32_e32 v100, v100, v32
	v_add_f32_e32 v105, v105, v33
	v_add_f32_e32 v110, v110, v34
	v_add_f32_e32 v115, v115, v35
	v_add_f32_dpp v168, v100, v100 quad_perm:[1,0,3,2] row_mask:0xf bank_mask:0xf bound_ctrl:1
	v_add_f32_dpp v174, v105, v105 quad_perm:[1,0,3,2] row_mask:0xf bank_mask:0xf bound_ctrl:1
	v_add_f32_dpp v241, v110, v110 quad_perm:[1,0,3,2] row_mask:0xf bank_mask:0xf bound_ctrl:1
	v_add_f32_dpp v247, v115, v115 quad_perm:[1,0,3,2] row_mask:0xf bank_mask:0xf bound_ctrl:1
	v_add_f32_dpp v168, v168, v168 quad_perm:[2,3,0,1] row_mask:0xf bank_mask:0xf bound_ctrl:1
	v_add_f32_dpp v174, v174, v174 quad_perm:[2,3,0,1] row_mask:0xf bank_mask:0xf bound_ctrl:1
	v_add_f32_dpp v241, v241, v241 quad_perm:[2,3,0,1] row_mask:0xf bank_mask:0xf bound_ctrl:1
; __device__ __forceinline__ float dpp_xor1(float x) { return __builtin_bit_cast(float, __builtin_amdgcn_update_dpp(0, __builtin_bit_cast(int, x), 0xB1, 0xF, 0xF, true)); }
; __device__ __forceinline__ float dpp_xor2(float x) { return __builtin_bit_cast(float, __builtin_amdgcn_update_dpp(0, __builtin_bit_cast(int, x), 0x4E, 0xF, 0xF, true)); }
; __device__ __forceinline__ float dpp_hmir(float x) { return __builtin_bit_cast(float, __builtin_amdgcn_update_dpp(0, __builtin_bit_cast(int, x), 0x141, 0xF, 0xF, true)); }
; __device__ __forceinline__ float dpp_mir(float x)  { return __builtin_bit_cast(float, __builtin_amdgcn_update_dpp(0, __builtin_bit_cast(int, x), 0x140, 0xF, 0xF, true)); }
; __device__ __forceinline__ float red16(float x) { x += dpp_xor1(x); x += dpp_xor2(x); x += dpp_hmir(x); x += dpp_mir(x); return x; }
; __device__ __forceinline__ float wsum(float x) {
;     x = red16(x); const int xi = __builtin_bit_cast(int, x);
;     const float r0 = __builtin_bit_cast(float, __builtin_amdgcn_readlane(xi, 0)), r1 = __builtin_bit_cast(float, __builtin_amdgcn_readlane(xi, 16));
;     const float r2 = __builtin_bit_cast(float, __builtin_amdgcn_readlane(xi, 32)), r3 = __builtin_bit_cast(float, __builtin_amdgcn_readlane(xi, 48));
;     return (r0 + r1) + (r2 + r3);
; }
; __device__ __forceinline__ void rw_post(Frame& F) {
;     ...
;             for (int q = 0; q < 8; ++q) { const int row = rb0 + t0 + q;
;                 const float mean = wsum(y[q]) * (1.f / 64.f); const float dv = y[q] - mean; const float var = wsum(dv * dv) * (1.f / 64.f);
;                 const float yn = dv * (1.f / sqrtf(var + 64e-5f)) * g_ + b_;
	v_add_f32_dpp v247, v247, v247 quad_perm:[2,3,0,1] row_mask:0xf bank_mask:0xf bound_ctrl:1
	v_add_f32_dpp v168, v168, v168 row_half_mirror row_mask:0xf bank_mask:0xf bound_ctrl:1
	v_add_f32_dpp v174, v174, v174 row_half_mirror row_mask:0xf bank_mask:0xf bound_ctrl:1
	v_add_f32_dpp v241, v241, v241 row_half_mirror row_mask:0xf bank_mask:0xf bound_ctrl:1
	v_add_f32_dpp v247, v247, v247 row_half_mirror row_mask:0xf bank_mask:0xf bound_ctrl:1
	v_add_f32_dpp v168, v168, v168 row_mirror row_mask:0xf bank_mask:0xf bound_ctrl:1
	v_add_f32_dpp v174, v174, v174 row_mirror row_mask:0xf bank_mask:0xf bound_ctrl:1
	v_add_f32_dpp v241, v241, v241 row_mirror row_mask:0xf bank_mask:0xf bound_ctrl:1
	v_add_f32_dpp v247, v247, v247 row_mirror row_mask:0xf bank_mask:0xf bound_ctrl:1
	v_readlane_b32 s36, v168, 16
	v_readlane_b32 s40, v174, 16
	v_readlane_b32 s44, v241, 16
	v_readlane_b32 s48, v247, 16
	v_readlane_b32 s37, v168, 48
	v_readlane_b32 s41, v174, 48
	v_readlane_b32 s45, v241, 48
	v_readlane_b32 s49, v247, 48
	v_readlane_b32 s38, v168, 0
	v_readlane_b32 s42, v174, 0
	v_readlane_b32 s46, v241, 0
	v_readlane_b32 s50, v247, 0
	v_readlane_b32 s39, v168, 32
	v_readlane_b32 s43, v174, 32
	v_readlane_b32 s47, v241, 32
	v_readlane_b32 s51, v247, 32
	v_mov_b32_e32 v168, s36
	v_mov_b32_e32 v174, s40
	v_mov_b32_e32 v241, s44
	v_mov_b32_e32 v247, s48
	v_mov_b32_e32 v169, s37
	v_mov_b32_e32 v175, s41
	v_mov_b32_e32 v242, s45
	v_mov_b32_e32 v248, s49
	v_add_f32_e32 v168, s38, v168
	v_add_f32_e32 v174, s42, v174
	v_add_f32_e32 v241, s46, v241
	v_add_f32_e32 v247, s50, v247
	v_add_f32_e32 v169, s39, v169
	v_add_f32_e32 v175, s43, v175
	v_add_f32_e32 v242, s47, v242
	v_add_f32_e32 v248, s51, v248
	v_add_f32_e32 v168, v168, v169
	v_add_f32_e32 v174, v174, v175
	v_add_f32_e32 v241, v241, v242
	v_add_f32_e32 v247, v247, v248
	v_fmamk_f32 v100, v168, 0xbc800000, v100
	v_fmamk_f32 v105, v174, 0xbc800000, v105
	v_fmamk_f32 v110, v241, 0xbc800000, v110
	v_fmamk_f32 v115, v247, 0xbc800000, v115
	v_mul_f32_e32 v168, v100, v100
	v_mul_f32_e32 v174, v105, v105
	v_mul_f32_e32 v241, v110, v110
	v_mul_f32_e32 v247, v115, v115
	v_mov_b32_dpp v168, v168 quad_perm:[1,0,3,2] row_mask:0xf bank_mask:0xf bound_ctrl:1
	v_mov_b32_dpp v174, v174 quad_perm:[1,0,3,2] row_mask:0xf bank_mask:0xf bound_ctrl:1
	v_mov_b32_dpp v241, v241 quad_perm:[1,0,3,2] row_mask:0xf bank_mask:0xf bound_ctrl:1
	v_mov_b32_dpp v247, v247 quad_perm:[1,0,3,2] row_mask:0xf bank_mask:0xf bound_ctrl:1
	v_fmac_f32_e32 v168, v100, v100
	v_fmac_f32_e32 v174, v105, v105
	v_fmac_f32_e32 v241, v110, v110
	v_fmac_f32_e32 v247, v115, v115
	v_add_f32_dpp v168, v168, v168 quad_perm:[2,3,0,1] row_mask:0xf bank_mask:0xf bound_ctrl:1
	v_add_f32_dpp v174, v174, v174 quad_perm:[2,3,0,1] row_mask:0xf bank_mask:0xf bound_ctrl:1
	v_add_f32_dpp v241, v241, v241 quad_perm:[2,3,0,1] row_mask:0xf bank_mask:0xf bound_ctrl:1
	v_add_f32_dpp v247, v247, v247 quad_perm:[2,3,0,1] row_mask:0xf bank_mask:0xf bound_ctrl:1
	v_add_f32_dpp v168, v168, v168 row_half_mirror row_mask:0xf bank_mask:0xf bound_ctrl:1
	v_add_f32_dpp v174, v174, v174 row_half_mirror row_mask:0xf bank_mask:0xf bound_ctrl:1
	v_add_f32_dpp v241, v241, v241 row_half_mirror row_mask:0xf bank_mask:0xf bound_ctrl:1
	v_add_f32_dpp v247, v247, v247 row_half_mirror row_mask:0xf bank_mask:0xf bound_ctrl:1
	v_add_f32_dpp v168, v168, v168 row_mirror row_mask:0xf bank_mask:0xf bound_ctrl:1
	v_add_f32_dpp v174, v174, v174 row_mirror row_mask:0xf bank_mask:0xf bound_ctrl:1
	v_add_f32_dpp v241, v241, v241 row_mirror row_mask:0xf bank_mask:0xf bound_ctrl:1
	v_add_f32_dpp v247, v247, v247 row_mirror row_mask:0xf bank_mask:0xf bound_ctrl:1
	v_readlane_b32 s36, v168, 16
	v_readlane_b32 s40, v174, 16
	v_readlane_b32 s44, v241, 16
	v_readlane_b32 s48, v247, 16
	v_readlane_b32 s37, v168, 48
	v_readlane_b32 s41, v174, 48
	v_readlane_b32 s45, v241, 48
	v_readlane_b32 s49, v247, 48
	v_readlane_b32 s38, v168, 0
	v_readlane_b32 s42, v174, 0
	v_readlane_b32 s46, v241, 0
	v_readlane_b32 s50, v247, 0
	v_readlane_b32 s39, v168, 32
	v_readlane_b32 s43, v174, 32
	v_readlane_b32 s47, v241, 32
	v_readlane_b32 s51, v247, 32
	v_mov_b32_e32 v168, s36
	v_mov_b32_e32 v174, s40
	v_mov_b32_e32 v241, s44
	v_mov_b32_e32 v247, s48
	v_mov_b32_e32 v169, s37
	v_mov_b32_e32 v175, s41
	v_mov_b32_e32 v242, s45
	v_mov_b32_e32 v248, s49
	v_add_f32_e32 v168, s38, v168
	v_add_f32_e32 v174, s42, v174
	v_add_f32_e32 v241, s46, v241
	v_add_f32_e32 v247, s50, v247
	v_add_f32_e32 v169, s39, v169
	v_add_f32_e32 v175, s43, v175
	v_add_f32_e32 v242, s47, v242
	v_add_f32_e32 v248, s51, v248
	v_add_f32_e32 v168, v168, v169
	v_add_f32_e32 v174, v174, v175
	v_add_f32_e32 v241, v241, v242
	v_add_f32_e32 v247, v247, v248
	v_fmamk_f32 v168, v168, 0x3c800000, v9
	v_fmamk_f32 v174, v174, 0x3c800000, v9
	v_fmamk_f32 v241, v241, 0x3c800000, v9
	v_fmamk_f32 v247, v247, 0x3c800000, v9
	v_readfirstlane_b32 s40, v174
	v_readfirstlane_b32 s44, v241
	v_readfirstlane_b32 s48, v247
	v_writelane_b32 v168, s40, 1
	v_writelane_b32 v168, s44, 2
	v_writelane_b32 v168, s48, 3
	v_mul_f32_e32 v169, 0x4f800000, v168
	v_cmp_gt_f32_e64 s[52:53], s68, v168
	v_mov_b32_e32 v170, v168
	s_nop 1
	v_cndmask_b32_e64 v168, v170, v169, s[52:53]
	v_sqrt_f32_e32 v169, v168
	s_nop 0
	v_add_u32_e32 v170, -1, v169
	v_fma_f32 v171, -v170, v169, v168
	v_cmp_ge_f32_e64 s[60:61], 0, v171
	v_add_u32_e32 v171, 1, v169
	s_nop 1
	v_cndmask_b32_e64 v170, v169, v170, s[60:61]
	v_fma_f32 v169, -v171, v169, v168
	v_cmp_lt_f32_e64 s[60:61], 0, v169
	s_nop 1
	v_cndmask_b32_e64 v169, v170, v171, s[60:61]
	v_mul_f32_e32 v170, 0x37800000, v169
	v_cndmask_b32_e64 v169, v169, v170, s[52:53]
; __device__ __forceinline__ float bf2f(bf16 x) { return __uint_as_float(((unsigned)x) << 16); }
; __device__ __forceinline__ unsigned f2bf(float f) { return cvt_pk_bf16(f, 0.f) & 0xffffu; }
; #define POST_LD(Y_, V_, G_, R_, C_, t) do { _Pragma("unroll") for (int q = 0; q < 8; ++q) { const size_t o_ = (size_t)((t) + q) * DH; Y_[q] = yp[o_]; V_[q] = vp[o_]; G_[q] = gp[o_]; R_[q] = rp[((t) + q) * 32]; C_[q] = cp[o_]; } } while (0)
; __device__ __forceinline__ void rw_post(Frame& F) {
;     ...
;         POST_LD(y, vv, gg, rk, cc, 0);
;         for (int t0 = 0; t0 < 64; t0 += 8) {
;             float ny[8], nv[8], nr[8], nc[8]; bf16 ng[8];
;             const int tn = t0 + 8 < 64 ? t0 + 8 : t0;
;             POST_LD(ny, nv, ng, nr, nc, tn);
;     ...
;             for (int q = 0; q < 8; ++q) { const int row = rb0 + t0 + q;
;                 const float mean = wsum(y[q]) * (1.f / 64.f); const float dv = y[q] - mean; const float var = wsum(dv * dv) * (1.f / 64.f);
;                 const float yn = dv * (1.f / sqrtf(var + 64e-5f)) * g_ + b_;
;                 OB[(size_t)row * DH + col] = (bf16)f2bf((yn + rk[q] * vv[q]) * bf2f(gg[q])); }
; #pragma unroll
;             for (int q = 0; q < 8; ++q) { y[q] = ny[q]; vv[q] = nv[q]; gg[q] = ng[q]; rk[q] = nr[q]; cc[q] = nc[q]; }
	v_cmp_class_f32_e64 s[60:61], v168, v8
	s_nop 1
	v_cndmask_b32_e64 v168, v169, v168, s[60:61]
	v_div_scale_f32 v169, s[60:61], v168, v168, 1.0
	v_rcp_f32_e32 v170, v169
	s_nop 0
	v_fma_f32 v171, -v169, v170, 1.0
	v_fmac_f32_e32 v170, v171, v170
	v_div_scale_f32 v171, vcc, 1.0, v168, 1.0
	v_mul_f32_e32 v172, v171, v170
	v_fma_f32 v173, -v169, v172, v171
	v_fmac_f32_e32 v172, v173, v170
	v_fma_f32 v169, -v169, v172, v171
	v_div_fmas_f32 v169, v169, v170, v172
	v_div_fixup_f32 v168, v169, v168, 1.0
	s_nop 0
	v_readlane_b32 s37, v168, 0
	v_readlane_b32 s41, v168, 1
	v_readlane_b32 s45, v168, 2
	v_readlane_b32 s49, v168, 3
	v_mul_f32_e32 v100, s37, v100
	v_mul_f32_e32 v105, s41, v105
	v_mul_f32_e32 v110, s45, v110
	v_mul_f32_e32 v115, s49, v115
	v_lshlrev_b32_e32 v103, 16, v103
	v_lshlrev_b32_e32 v108, 16, v108
	v_lshlrev_b32_e32 v113, 16, v113
	v_lshlrev_b32_e32 v118, 16, v118
	v_fma_f32 v100, v6, v100, v7
	v_fma_f32 v105, v6, v105, v7
	v_fma_f32 v110, v6, v110, v7
	v_fma_f32 v115, v6, v115, v7
	v_fmac_f32_e32 v100, s73, v101
	v_fmac_f32_e32 v105, s26, v106
	v_fmac_f32_e32 v110, s27, v111
	v_fmac_f32_e32 v115, s32, v116
	v_mul_f32_e32 v100, v100, v103
	v_mul_f32_e32 v105, v105, v108
	v_mul_f32_e32 v110, v110, v113
	v_mul_f32_e32 v115, v115, v118
	v_cvt_pk_bf16_f32 v169, v100, v100
	v_cvt_pk_bf16_f32 v175, v105, v105
	v_cvt_pk_bf16_f32 v242, v110, v110
	v_cvt_pk_bf16_f32 v248, v115, v115
	global_store_short v2, v169, s[28:29]
	s_add_u32 s28, s28, 0x1000
	s_addc_u32 s29, s29, 0
	global_store_short v2, v175, s[28:29]
	s_add_u32 s28, s28, 0x1000
	s_addc_u32 s29, s29, 0
	global_store_short v2, v242, s[28:29]
	s_add_u32 s28, s28, 0x1000
	s_addc_u32 s29, s29, 0
	global_store_short v2, v248, s[28:29]
	s_add_u32 s28, s28, 0x1000
	s_addc_u32 s29, s29, 0
	s_waitcnt vmcnt(8)
	ds_write_b128 v13, v[120:123] offset:0
	ds_write_b128 v13, v[124:127] offset:1024
	ds_write_b128 v13, v[128:131] offset:16384
	ds_write_b128 v13, v[132:135] offset:17408
	ds_write_b128 v15, v[136:139]
	v_readlane_b32 s69, v159, 0
	v_readlane_b32 s70, v159, 1
	v_readlane_b32 s71, v159, 2
	v_readlane_b32 s72, v159, 3
	v_readlane_b32 s73, v159, 4
	v_readlane_b32 s26, v159, 5
	v_readlane_b32 s27, v159, 6
	v_readlane_b32 s32, v159, 7
	global_load_dwordx4 v[120:123], v11, s[6:7]
	global_load_dwordx4 v[124:127], v11, s[6:7] offset:1024
	global_load_dwordx4 v[128:131], v11, s[8:9]
	global_load_dwordx4 v[132:135], v11, s[8:9] offset:1024
	global_load_dwordx4 v[136:139], v11, s[10:11]
	global_load_dword v159, v158, s[12:13]
	s_add_u32 s6, s6, 0x10000
	s_addc_u32 s7, s7, 0
	s_add_u32 s8, s8, 0x10000
	s_addc_u32 s9, s9, 0
	s_add_u32 s10, s10, 0x8000
	s_addc_u32 s11, s11, 0
	s_add_u32 s12, s12, 0x400
	s_addc_u32 s13, s13, 0
	s_waitcnt lgkmcnt(0)
	s_barrier
	ds_read_b32 v80, v155 offset:0
	ds_read_b32 v81, v155 offset:16384
	ds_read_u16 v83, v157 offset:0
	ds_read_b32 v85, v155 offset:2048
	ds_read_b32 v86, v155 offset:18432
	ds_read_u16 v88, v157 offset:1024
	ds_read_b32 v90, v155 offset:4096
	ds_read_b32 v91, v155 offset:20480
	ds_read_u16 v93, v157 offset:2048
	ds_read_b32 v95, v155 offset:6144
	ds_read_b32 v96, v155 offset:22528
	ds_read_u16 v98, v157 offset:3072
	ds_read_b32 v100, v155 offset:8192
	ds_read_b32 v101, v155 offset:24576
	ds_read_u16 v103, v157 offset:4096
	ds_read_b32 v105, v155 offset:10240
	ds_read_b32 v106, v155 offset:26624
	ds_read_u16 v108, v157 offset:5120
	ds_read_b32 v110, v155 offset:12288
	ds_read_b32 v111, v155 offset:28672
	ds_read_u16 v113, v157 offset:6144
	ds_read_b32 v115, v155 offset:14336
	ds_read_b32 v116, v155 offset:30720
	ds_read_u16 v118, v157 offset:7168
	s_waitcnt lgkmcnt(0)
	v_add_f32_e32 v80, v80, v20
	v_add_f32_e32 v85, v85, v21
	v_add_f32_e32 v90, v90, v22
	v_add_f32_e32 v95, v95, v23
	v_add_f32_dpp v168, v80, v80 quad_perm:[1,0,3,2] row_mask:0xf bank_mask:0xf bound_ctrl:1
	v_add_f32_dpp v174, v85, v85 quad_perm:[1,0,3,2] row_mask:0xf bank_mask:0xf bound_ctrl:1
	v_add_f32_dpp v241, v90, v90 quad_perm:[1,0,3,2] row_mask:0xf bank_mask:0xf bound_ctrl:1
	v_add_f32_dpp v247, v95, v95 quad_perm:[1,0,3,2] row_mask:0xf bank_mask:0xf bound_ctrl:1
	v_add_f32_dpp v168, v168, v168 quad_perm:[2,3,0,1] row_mask:0xf bank_mask:0xf bound_ctrl:1
	v_add_f32_dpp v174, v174, v174 quad_perm:[2,3,0,1] row_mask:0xf bank_mask:0xf bound_ctrl:1
	v_add_f32_dpp v241, v241, v241 quad_perm:[2,3,0,1] row_mask:0xf bank_mask:0xf bound_ctrl:1
	v_add_f32_dpp v247, v247, v247 quad_perm:[2,3,0,1] row_mask:0xf bank_mask:0xf bound_ctrl:1
	v_add_f32_dpp v168, v168, v168 row_half_mirror row_mask:0xf bank_mask:0xf bound_ctrl:1
	v_add_f32_dpp v174, v174, v174 row_half_mirror row_mask:0xf bank_mask:0xf bound_ctrl:1
	v_add_f32_dpp v241, v241, v241 row_half_mirror row_mask:0xf bank_mask:0xf bound_ctrl:1
	v_add_f32_dpp v247, v247, v247 row_half_mirror row_mask:0xf bank_mask:0xf bound_ctrl:1
	v_add_f32_dpp v168, v168, v168 row_mirror row_mask:0xf bank_mask:0xf bound_ctrl:1
	v_add_f32_dpp v174, v174, v174 row_mirror row_mask:0xf bank_mask:0xf bound_ctrl:1
	v_add_f32_dpp v241, v241, v241 row_mirror row_mask:0xf bank_mask:0xf bound_ctrl:1
	v_add_f32_dpp v247, v247, v247 row_mirror row_mask:0xf bank_mask:0xf bound_ctrl:1
	v_readlane_b32 s36, v168, 16
	v_readlane_b32 s40, v174, 16
	v_readlane_b32 s44, v241, 16
	v_readlane_b32 s48, v247, 16
	v_readlane_b32 s37, v168, 48
	v_readlane_b32 s41, v174, 48
	v_readlane_b32 s45, v241, 48
	v_readlane_b32 s49, v247, 48
	v_readlane_b32 s38, v168, 0
	v_readlane_b32 s42, v174, 0
	v_readlane_b32 s46, v241, 0
	v_readlane_b32 s50, v247, 0
	v_readlane_b32 s39, v168, 32
	v_readlane_b32 s43, v174, 32
	v_readlane_b32 s47, v241, 32
	v_readlane_b32 s51, v247, 32
; __device__ __forceinline__ float bf2f(bf16 x) { return __uint_as_float(((unsigned)x) << 16); }
; __device__ __forceinline__ unsigned f2bf(float f) { return cvt_pk_bf16(f, 0.f) & 0xffffu; }
; __device__ __forceinline__ float dpp_xor1(float x) { return __builtin_bit_cast(float, __builtin_amdgcn_update_dpp(0, __builtin_bit_cast(int, x), 0xB1, 0xF, 0xF, true)); }
; __device__ __forceinline__ float dpp_xor2(float x) { return __builtin_bit_cast(float, __builtin_amdgcn_update_dpp(0, __builtin_bit_cast(int, x), 0x4E, 0xF, 0xF, true)); }
; __device__ __forceinline__ float dpp_hmir(float x) { return __builtin_bit_cast(float, __builtin_amdgcn_update_dpp(0, __builtin_bit_cast(int, x), 0x141, 0xF, 0xF, true)); }
; __device__ __forceinline__ float dpp_mir(float x)  { return __builtin_bit_cast(float, __builtin_amdgcn_update_dpp(0, __builtin_bit_cast(int, x), 0x140, 0xF, 0xF, true)); }
; __device__ __forceinline__ float red16(float x) { x += dpp_xor1(x); x += dpp_xor2(x); x += dpp_hmir(x); x += dpp_mir(x); return x; }
; __device__ __forceinline__ float wsum(float x) {
;     x = red16(x); const int xi = __builtin_bit_cast(int, x);
;     const float r0 = __builtin_bit_cast(float, __builtin_amdgcn_readlane(xi, 0)), r1 = __builtin_bit_cast(float, __builtin_amdgcn_readlane(xi, 16));
;     const float r2 = __builtin_bit_cast(float, __builtin_amdgcn_readlane(xi, 32)), r3 = __builtin_bit_cast(float, __builtin_amdgcn_readlane(xi, 48));
;     return (r0 + r1) + (r2 + r3);
; }
; __device__ __forceinline__ void rw_post(Frame& F) {
;     ...
;             for (int q = 0; q < 8; ++q) { const int row = rb0 + t0 + q;
;                 const float mean = wsum(y[q]) * (1.f / 64.f); const float dv = y[q] - mean; const float var = wsum(dv * dv) * (1.f / 64.f);
;                 const float yn = dv * (1.f / sqrtf(var + 64e-5f)) * g_ + b_;
;                 OB[(size_t)row * DH + col] = (bf16)f2bf((yn + rk[q] * vv[q]) * bf2f(gg[q])); }
	v_mov_b32_e32 v168, s36
	v_mov_b32_e32 v174, s40
	v_mov_b32_e32 v241, s44
	v_mov_b32_e32 v247, s48
	v_mov_b32_e32 v169, s37
	v_mov_b32_e32 v175, s41
	v_mov_b32_e32 v242, s45
	v_mov_b32_e32 v248, s49
	v_add_f32_e32 v168, s38, v168
	v_add_f32_e32 v174, s42, v174
	v_add_f32_e32 v241, s46, v241
	v_add_f32_e32 v247, s50, v247
	v_add_f32_e32 v169, s39, v169
	v_add_f32_e32 v175, s43, v175
	v_add_f32_e32 v242, s47, v242
	v_add_f32_e32 v248, s51, v248
	v_add_f32_e32 v168, v168, v169
	v_add_f32_e32 v174, v174, v175
	v_add_f32_e32 v241, v241, v242
	v_add_f32_e32 v247, v247, v248
	v_fmamk_f32 v80, v168, 0xbc800000, v80
	v_fmamk_f32 v85, v174, 0xbc800000, v85
	v_fmamk_f32 v90, v241, 0xbc800000, v90
	v_fmamk_f32 v95, v247, 0xbc800000, v95
	v_mul_f32_e32 v168, v80, v80
	v_mul_f32_e32 v174, v85, v85
	v_mul_f32_e32 v241, v90, v90
	v_mul_f32_e32 v247, v95, v95
	v_mov_b32_dpp v168, v168 quad_perm:[1,0,3,2] row_mask:0xf bank_mask:0xf bound_ctrl:1
	v_mov_b32_dpp v174, v174 quad_perm:[1,0,3,2] row_mask:0xf bank_mask:0xf bound_ctrl:1
	v_mov_b32_dpp v241, v241 quad_perm:[1,0,3,2] row_mask:0xf bank_mask:0xf bound_ctrl:1
	v_mov_b32_dpp v247, v247 quad_perm:[1,0,3,2] row_mask:0xf bank_mask:0xf bound_ctrl:1
	v_fmac_f32_e32 v168, v80, v80
	v_fmac_f32_e32 v174, v85, v85
	v_fmac_f32_e32 v241, v90, v90
	v_fmac_f32_e32 v247, v95, v95
	v_add_f32_dpp v168, v168, v168 quad_perm:[2,3,0,1] row_mask:0xf bank_mask:0xf bound_ctrl:1
	v_add_f32_dpp v174, v174, v174 quad_perm:[2,3,0,1] row_mask:0xf bank_mask:0xf bound_ctrl:1
	v_add_f32_dpp v241, v241, v241 quad_perm:[2,3,0,1] row_mask:0xf bank_mask:0xf bound_ctrl:1
	v_add_f32_dpp v247, v247, v247 quad_perm:[2,3,0,1] row_mask:0xf bank_mask:0xf bound_ctrl:1
	v_add_f32_dpp v168, v168, v168 row_half_mirror row_mask:0xf bank_mask:0xf bound_ctrl:1
	v_add_f32_dpp v174, v174, v174 row_half_mirror row_mask:0xf bank_mask:0xf bound_ctrl:1
	v_add_f32_dpp v241, v241, v241 row_half_mirror row_mask:0xf bank_mask:0xf bound_ctrl:1
	v_add_f32_dpp v247, v247, v247 row_half_mirror row_mask:0xf bank_mask:0xf bound_ctrl:1
	v_add_f32_dpp v168, v168, v168 row_mirror row_mask:0xf bank_mask:0xf bound_ctrl:1
	v_add_f32_dpp v174, v174, v174 row_mirror row_mask:0xf bank_mask:0xf bound_ctrl:1
	v_add_f32_dpp v241, v241, v241 row_mirror row_mask:0xf bank_mask:0xf bound_ctrl:1
	v_add_f32_dpp v247, v247, v247 row_mirror row_mask:0xf bank_mask:0xf bound_ctrl:1
	v_readlane_b32 s36, v168, 16
	v_readlane_b32 s40, v174, 16
	v_readlane_b32 s44, v241, 16
	v_readlane_b32 s48, v247, 16
	v_readlane_b32 s37, v168, 48
	v_readlane_b32 s41, v174, 48
	v_readlane_b32 s45, v241, 48
	v_readlane_b32 s49, v247, 48
	v_readlane_b32 s38, v168, 0
	v_readlane_b32 s42, v174, 0
	v_readlane_b32 s46, v241, 0
	v_readlane_b32 s50, v247, 0
	v_readlane_b32 s39, v168, 32
	v_readlane_b32 s43, v174, 32
	v_readlane_b32 s47, v241, 32
	v_readlane_b32 s51, v247, 32
	v_mov_b32_e32 v168, s36
	v_mov_b32_e32 v174, s40
	v_mov_b32_e32 v241, s44
	v_mov_b32_e32 v247, s48
	v_mov_b32_e32 v169, s37
	v_mov_b32_e32 v175, s41
	v_mov_b32_e32 v242, s45
	v_mov_b32_e32 v248, s49
	v_add_f32_e32 v168, s38, v168
	v_add_f32_e32 v174, s42, v174
	v_add_f32_e32 v241, s46, v241
	v_add_f32_e32 v247, s50, v247
	v_add_f32_e32 v169, s39, v169
	v_add_f32_e32 v175, s43, v175
	v_add_f32_e32 v242, s47, v242
	v_add_f32_e32 v248, s51, v248
	v_add_f32_e32 v168, v168, v169
	v_add_f32_e32 v174, v174, v175
	v_add_f32_e32 v241, v241, v242
	v_add_f32_e32 v247, v247, v248
	v_fmamk_f32 v168, v168, 0x3c800000, v9
	v_fmamk_f32 v174, v174, 0x3c800000, v9
	v_fmamk_f32 v241, v241, 0x3c800000, v9
	v_fmamk_f32 v247, v247, 0x3c800000, v9
	v_readfirstlane_b32 s40, v174
	v_readfirstlane_b32 s44, v241
	v_readfirstlane_b32 s48, v247
	v_writelane_b32 v168, s40, 1
	v_writelane_b32 v168, s44, 2
	v_writelane_b32 v168, s48, 3
	v_mul_f32_e32 v169, 0x4f800000, v168
	v_cmp_gt_f32_e64 s[52:53], s68, v168
	v_mov_b32_e32 v170, v168
	s_nop 1
	v_cndmask_b32_e64 v168, v170, v169, s[52:53]
	v_sqrt_f32_e32 v169, v168
	s_nop 0
	v_add_u32_e32 v170, -1, v169
	v_fma_f32 v171, -v170, v169, v168
	v_cmp_ge_f32_e64 s[60:61], 0, v171
	v_add_u32_e32 v171, 1, v169
	s_nop 1
	v_cndmask_b32_e64 v170, v169, v170, s[60:61]
	v_fma_f32 v169, -v171, v169, v168
	v_cmp_lt_f32_e64 s[60:61], 0, v169
	s_nop 1
	v_cndmask_b32_e64 v169, v170, v171, s[60:61]
	v_mul_f32_e32 v170, 0x37800000, v169
	v_cndmask_b32_e64 v169, v169, v170, s[52:53]
	v_cmp_class_f32_e64 s[60:61], v168, v8
	s_nop 1
	v_cndmask_b32_e64 v168, v169, v168, s[60:61]
	v_div_scale_f32 v169, s[60:61], v168, v168, 1.0
	v_rcp_f32_e32 v170, v169
	s_nop 0
	v_fma_f32 v171, -v169, v170, 1.0
	v_fmac_f32_e32 v170, v171, v170
	v_div_scale_f32 v171, vcc, 1.0, v168, 1.0
	v_mul_f32_e32 v172, v171, v170
	v_fma_f32 v173, -v169, v172, v171
	v_fmac_f32_e32 v172, v173, v170
	v_fma_f32 v169, -v169, v172, v171
	v_div_fmas_f32 v169, v169, v170, v172
	v_div_fixup_f32 v168, v169, v168, 1.0
	s_nop 0
	v_readlane_b32 s37, v168, 0
	v_readlane_b32 s41, v168, 1
	v_readlane_b32 s45, v168, 2
	v_readlane_b32 s49, v168, 3
	v_mul_f32_e32 v80, s37, v80
	v_mul_f32_e32 v85, s41, v85
	v_mul_f32_e32 v90, s45, v90
	v_mul_f32_e32 v95, s49, v95
	v_lshlrev_b32_e32 v83, 16, v83
	v_lshlrev_b32_e32 v88, 16, v88
	v_lshlrev_b32_e32 v93, 16, v93
	v_lshlrev_b32_e32 v98, 16, v98
	v_fma_f32 v80, v6, v80, v7
	v_fma_f32 v85, v6, v85, v7
	v_fma_f32 v90, v6, v90, v7
	v_fma_f32 v95, v6, v95, v7
	v_fmac_f32_e32 v80, s69, v81
	v_fmac_f32_e32 v85, s70, v86
	v_fmac_f32_e32 v90, s71, v91
	v_fmac_f32_e32 v95, s72, v96
	v_mul_f32_e32 v80, v80, v83
	v_mul_f32_e32 v85, v85, v88
	v_mul_f32_e32 v90, v90, v93
	v_mul_f32_e32 v95, v95, v98
	v_cvt_pk_bf16_f32 v169, v80, v80
	v_cvt_pk_bf16_f32 v175, v85, v85
; __device__ __forceinline__ float bf2f(bf16 x) { return __uint_as_float(((unsigned)x) << 16); }
; __device__ __forceinline__ unsigned f2bf(float f) { return cvt_pk_bf16(f, 0.f) & 0xffffu; }
; __device__ __forceinline__ float dpp_xor1(float x) { return __builtin_bit_cast(float, __builtin_amdgcn_update_dpp(0, __builtin_bit_cast(int, x), 0xB1, 0xF, 0xF, true)); }
; __device__ __forceinline__ float dpp_xor2(float x) { return __builtin_bit_cast(float, __builtin_amdgcn_update_dpp(0, __builtin_bit_cast(int, x), 0x4E, 0xF, 0xF, true)); }
; __device__ __forceinline__ float dpp_hmir(float x) { return __builtin_bit_cast(float, __builtin_amdgcn_update_dpp(0, __builtin_bit_cast(int, x), 0x141, 0xF, 0xF, true)); }
; __device__ __forceinline__ float dpp_mir(float x)  { return __builtin_bit_cast(float, __builtin_amdgcn_update_dpp(0, __builtin_bit_cast(int, x), 0x140, 0xF, 0xF, true)); }
; __device__ __forceinline__ float red16(float x) { x += dpp_xor1(x); x += dpp_xor2(x); x += dpp_hmir(x); x += dpp_mir(x); return x; }
; __device__ __forceinline__ float wsum(float x) {
;     x = red16(x); const int xi = __builtin_bit_cast(int, x);
;     const float r0 = __builtin_bit_cast(float, __builtin_amdgcn_readlane(xi, 0)), r1 = __builtin_bit_cast(float, __builtin_amdgcn_readlane(xi, 16));
;     const float r2 = __builtin_bit_cast(float, __builtin_amdgcn_readlane(xi, 32)), r3 = __builtin_bit_cast(float, __builtin_amdgcn_readlane(xi, 48));
;     return (r0 + r1) + (r2 + r3);
; }
; __device__ __forceinline__ void rw_post(Frame& F) {
;     ...
;             for (int q = 0; q < 8; ++q) { const int row = rb0 + t0 + q;
;                 const float mean = wsum(y[q]) * (1.f / 64.f); const float dv = y[q] - mean; const float var = wsum(dv * dv) * (1.f / 64.f);
;                 const float yn = dv * (1.f / sqrtf(var + 64e-5f)) * g_ + b_;
;                 OB[(size_t)row * DH + col] = (bf16)f2bf((yn + rk[q] * vv[q]) * bf2f(gg[q])); }
	v_cvt_pk_bf16_f32 v242, v90, v90
	v_cvt_pk_bf16_f32 v248, v95, v95
	global_store_short v2, v169, s[28:29]
	s_add_u32 s28, s28, 0x1000
	s_addc_u32 s29, s29, 0
	global_store_short v2, v175, s[28:29]
	s_add_u32 s28, s28, 0x1000
	s_addc_u32 s29, s29, 0
	global_store_short v2, v242, s[28:29]
	s_add_u32 s28, s28, 0x1000
	s_addc_u32 s29, s29, 0
	global_store_short v2, v248, s[28:29]
	s_add_u32 s28, s28, 0x1000
	s_addc_u32 s29, s29, 0
	v_add_f32_e32 v100, v100, v36
	v_add_f32_e32 v105, v105, v37
	v_add_f32_e32 v110, v110, v38
	v_add_f32_e32 v115, v115, v39
	v_add_f32_dpp v168, v100, v100 quad_perm:[1,0,3,2] row_mask:0xf bank_mask:0xf bound_ctrl:1
	v_add_f32_dpp v174, v105, v105 quad_perm:[1,0,3,2] row_mask:0xf bank_mask:0xf bound_ctrl:1
	v_add_f32_dpp v241, v110, v110 quad_perm:[1,0,3,2] row_mask:0xf bank_mask:0xf bound_ctrl:1
	v_add_f32_dpp v247, v115, v115 quad_perm:[1,0,3,2] row_mask:0xf bank_mask:0xf bound_ctrl:1
	v_add_f32_dpp v168, v168, v168 quad_perm:[2,3,0,1] row_mask:0xf bank_mask:0xf bound_ctrl:1
	v_add_f32_dpp v174, v174, v174 quad_perm:[2,3,0,1] row_mask:0xf bank_mask:0xf bound_ctrl:1
	v_add_f32_dpp v241, v241, v241 quad_perm:[2,3,0,1] row_mask:0xf bank_mask:0xf bound_ctrl:1
	v_add_f32_dpp v247, v247, v247 quad_perm:[2,3,0,1] row_mask:0xf bank_mask:0xf bound_ctrl:1
	v_add_f32_dpp v168, v168, v168 row_half_mirror row_mask:0xf bank_mask:0xf bound_ctrl:1
	v_add_f32_dpp v174, v174, v174 row_half_mirror row_mask:0xf bank_mask:0xf bound_ctrl:1
	v_add_f32_dpp v241, v241, v241 row_half_mirror row_mask:0xf bank_mask:0xf bound_ctrl:1
	v_add_f32_dpp v247, v247, v247 row_half_mirror row_mask:0xf bank_mask:0xf bound_ctrl:1
	v_add_f32_dpp v168, v168, v168 row_mirror row_mask:0xf bank_mask:0xf bound_ctrl:1
	v_add_f32_dpp v174, v174, v174 row_mirror row_mask:0xf bank_mask:0xf bound_ctrl:1
	v_add_f32_dpp v241, v241, v241 row_mirror row_mask:0xf bank_mask:0xf bound_ctrl:1
	v_add_f32_dpp v247, v247, v247 row_mirror row_mask:0xf bank_mask:0xf bound_ctrl:1
	v_readlane_b32 s36, v168, 16
	v_readlane_b32 s40, v174, 16
	v_readlane_b32 s44, v241, 16
	v_readlane_b32 s48, v247, 16
	v_readlane_b32 s37, v168, 48
	v_readlane_b32 s41, v174, 48
	v_readlane_b32 s45, v241, 48
	v_readlane_b32 s49, v247, 48
	v_readlane_b32 s38, v168, 0
	v_readlane_b32 s42, v174, 0
	v_readlane_b32 s46, v241, 0
	v_readlane_b32 s50, v247, 0
	v_readlane_b32 s39, v168, 32
	v_readlane_b32 s43, v174, 32
	v_readlane_b32 s47, v241, 32
	v_readlane_b32 s51, v247, 32
	v_mov_b32_e32 v168, s36
	v_mov_b32_e32 v174, s40
	v_mov_b32_e32 v241, s44
	v_mov_b32_e32 v247, s48
	v_mov_b32_e32 v169, s37
	v_mov_b32_e32 v175, s41
	v_mov_b32_e32 v242, s45
	v_mov_b32_e32 v248, s49
	v_add_f32_e32 v168, s38, v168
	v_add_f32_e32 v174, s42, v174
	v_add_f32_e32 v241, s46, v241
	v_add_f32_e32 v247, s50, v247
	v_add_f32_e32 v169, s39, v169
	v_add_f32_e32 v175, s43, v175
	v_add_f32_e32 v242, s47, v242
	v_add_f32_e32 v248, s51, v248
	v_add_f32_e32 v168, v168, v169
	v_add_f32_e32 v174, v174, v175
	v_add_f32_e32 v241, v241, v242
	v_add_f32_e32 v247, v247, v248
	v_fmamk_f32 v100, v168, 0xbc800000, v100
	v_fmamk_f32 v105, v174, 0xbc800000, v105
	v_fmamk_f32 v110, v241, 0xbc800000, v110
	v_fmamk_f32 v115, v247, 0xbc800000, v115
	v_mul_f32_e32 v168, v100, v100
	v_mul_f32_e32 v174, v105, v105
	v_mul_f32_e32 v241, v110, v110
	v_mul_f32_e32 v247, v115, v115
	v_mov_b32_dpp v168, v168 quad_perm:[1,0,3,2] row_mask:0xf bank_mask:0xf bound_ctrl:1
	v_mov_b32_dpp v174, v174 quad_perm:[1,0,3,2] row_mask:0xf bank_mask:0xf bound_ctrl:1
	v_mov_b32_dpp v241, v241 quad_perm:[1,0,3,2] row_mask:0xf bank_mask:0xf bound_ctrl:1
	v_mov_b32_dpp v247, v247 quad_perm:[1,0,3,2] row_mask:0xf bank_mask:0xf bound_ctrl:1
	v_fmac_f32_e32 v168, v100, v100
	v_fmac_f32_e32 v174, v105, v105
	v_fmac_f32_e32 v241, v110, v110
	v_fmac_f32_e32 v247, v115, v115
	v_add_f32_dpp v168, v168, v168 quad_perm:[2,3,0,1] row_mask:0xf bank_mask:0xf bound_ctrl:1
	v_add_f32_dpp v174, v174, v174 quad_perm:[2,3,0,1] row_mask:0xf bank_mask:0xf bound_ctrl:1
	v_add_f32_dpp v241, v241, v241 quad_perm:[2,3,0,1] row_mask:0xf bank_mask:0xf bound_ctrl:1
	v_add_f32_dpp v247, v247, v247 quad_perm:[2,3,0,1] row_mask:0xf bank_mask:0xf bound_ctrl:1
	v_add_f32_dpp v168, v168, v168 row_half_mirror row_mask:0xf bank_mask:0xf bound_ctrl:1
	v_add_f32_dpp v174, v174, v174 row_half_mirror row_mask:0xf bank_mask:0xf bound_ctrl:1
	v_add_f32_dpp v241, v241, v241 row_half_mirror row_mask:0xf bank_mask:0xf bound_ctrl:1
	v_add_f32_dpp v247, v247, v247 row_half_mirror row_mask:0xf bank_mask:0xf bound_ctrl:1
	v_add_f32_dpp v168, v168, v168 row_mirror row_mask:0xf bank_mask:0xf bound_ctrl:1
	v_add_f32_dpp v174, v174, v174 row_mirror row_mask:0xf bank_mask:0xf bound_ctrl:1
	v_add_f32_dpp v241, v241, v241 row_mirror row_mask:0xf bank_mask:0xf bound_ctrl:1
	v_add_f32_dpp v247, v247, v247 row_mirror row_mask:0xf bank_mask:0xf bound_ctrl:1
	v_readlane_b32 s36, v168, 16
	v_readlane_b32 s40, v174, 16
	v_readlane_b32 s44, v241, 16
	v_readlane_b32 s48, v247, 16
	v_readlane_b32 s37, v168, 48
	v_readlane_b32 s41, v174, 48
	v_readlane_b32 s45, v241, 48
	v_readlane_b32 s49, v247, 48
	v_readlane_b32 s38, v168, 0
	v_readlane_b32 s42, v174, 0
	v_readlane_b32 s46, v241, 0
	v_readlane_b32 s50, v247, 0
	v_readlane_b32 s39, v168, 32
	v_readlane_b32 s43, v174, 32
	v_readlane_b32 s47, v241, 32
	v_readlane_b32 s51, v247, 32
	v_mov_b32_e32 v168, s36
	v_mov_b32_e32 v174, s40
	v_mov_b32_e32 v241, s44
	v_mov_b32_e32 v247, s48
	v_mov_b32_e32 v169, s37
	v_mov_b32_e32 v175, s41
	v_mov_b32_e32 v242, s45
	v_mov_b32_e32 v248, s49
	v_add_f32_e32 v168, s38, v168
	v_add_f32_e32 v174, s42, v174
	v_add_f32_e32 v241, s46, v241
	v_add_f32_e32 v247, s50, v247
; __device__ __forceinline__ float bf2f(bf16 x) { return __uint_as_float(((unsigned)x) << 16); }
; __device__ __forceinline__ unsigned f2bf(float f) { return cvt_pk_bf16(f, 0.f) & 0xffffu; }
; #define POST_LD(Y_, V_, G_, R_, C_, t) do { _Pragma("unroll") for (int q = 0; q < 8; ++q) { const size_t o_ = (size_t)((t) + q) * DH; Y_[q] = yp[o_]; V_[q] = vp[o_]; G_[q] = gp[o_]; R_[q] = rp[((t) + q) * 32]; C_[q] = cp[o_]; } } while (0)
; __device__ __forceinline__ void rw_post(Frame& F) {
;     ...
;         POST_LD(y, vv, gg, rk, cc, 0);
;         for (int t0 = 0; t0 < 64; t0 += 8) {
;             float ny[8], nv[8], nr[8], nc[8]; bf16 ng[8];
;             const int tn = t0 + 8 < 64 ? t0 + 8 : t0;
;             POST_LD(ny, nv, ng, nr, nc, tn);
;     ...
;             for (int q = 0; q < 8; ++q) { const int row = rb0 + t0 + q;
;                 const float mean = wsum(y[q]) * (1.f / 64.f); const float dv = y[q] - mean; const float var = wsum(dv * dv) * (1.f / 64.f);
;                 const float yn = dv * (1.f / sqrtf(var + 64e-5f)) * g_ + b_;
;                 OB[(size_t)row * DH + col] = (bf16)f2bf((yn + rk[q] * vv[q]) * bf2f(gg[q])); }
; #pragma unroll
;             for (int q = 0; q < 8; ++q) { y[q] = ny[q]; vv[q] = nv[q]; gg[q] = ng[q]; rk[q] = nr[q]; cc[q] = nc[q]; }
	v_add_f32_e32 v169, s39, v169
	v_add_f32_e32 v175, s43, v175
	v_add_f32_e32 v242, s47, v242
	v_add_f32_e32 v248, s51, v248
	v_add_f32_e32 v168, v168, v169
	v_add_f32_e32 v174, v174, v175
	v_add_f32_e32 v241, v241, v242
	v_add_f32_e32 v247, v247, v248
	v_fmamk_f32 v168, v168, 0x3c800000, v9
	v_fmamk_f32 v174, v174, 0x3c800000, v9
	v_fmamk_f32 v241, v241, 0x3c800000, v9
	v_fmamk_f32 v247, v247, 0x3c800000, v9
	v_readfirstlane_b32 s40, v174
	v_readfirstlane_b32 s44, v241
	v_readfirstlane_b32 s48, v247
	v_writelane_b32 v168, s40, 1
	v_writelane_b32 v168, s44, 2
	v_writelane_b32 v168, s48, 3
	v_mul_f32_e32 v169, 0x4f800000, v168
	v_cmp_gt_f32_e64 s[52:53], s68, v168
	v_mov_b32_e32 v170, v168
	s_nop 1
	v_cndmask_b32_e64 v168, v170, v169, s[52:53]
	v_sqrt_f32_e32 v169, v168
	s_nop 0
	v_add_u32_e32 v170, -1, v169
	v_fma_f32 v171, -v170, v169, v168
	v_cmp_ge_f32_e64 s[60:61], 0, v171
	v_add_u32_e32 v171, 1, v169
	s_nop 1
	v_cndmask_b32_e64 v170, v169, v170, s[60:61]
	v_fma_f32 v169, -v171, v169, v168
	v_cmp_lt_f32_e64 s[60:61], 0, v169
	s_nop 1
	v_cndmask_b32_e64 v169, v170, v171, s[60:61]
	v_mul_f32_e32 v170, 0x37800000, v169
	v_cndmask_b32_e64 v169, v169, v170, s[52:53]
	v_cmp_class_f32_e64 s[60:61], v168, v8
	s_nop 1
	v_cndmask_b32_e64 v168, v169, v168, s[60:61]
	v_div_scale_f32 v169, s[60:61], v168, v168, 1.0
	v_rcp_f32_e32 v170, v169
	s_nop 0
	v_fma_f32 v171, -v169, v170, 1.0
	v_fmac_f32_e32 v170, v171, v170
	v_div_scale_f32 v171, vcc, 1.0, v168, 1.0
	v_mul_f32_e32 v172, v171, v170
	v_fma_f32 v173, -v169, v172, v171
	v_fmac_f32_e32 v172, v173, v170
	v_fma_f32 v169, -v169, v172, v171
	v_div_fmas_f32 v169, v169, v170, v172
	v_div_fixup_f32 v168, v169, v168, 1.0
	s_nop 0
	v_readlane_b32 s37, v168, 0
	v_readlane_b32 s41, v168, 1
	v_readlane_b32 s45, v168, 2
	v_readlane_b32 s49, v168, 3
	v_mul_f32_e32 v100, s37, v100
	v_mul_f32_e32 v105, s41, v105
	v_mul_f32_e32 v110, s45, v110
	v_mul_f32_e32 v115, s49, v115
	v_lshlrev_b32_e32 v103, 16, v103
	v_lshlrev_b32_e32 v108, 16, v108
	v_lshlrev_b32_e32 v113, 16, v113
	v_lshlrev_b32_e32 v118, 16, v118
	v_fma_f32 v100, v6, v100, v7
	v_fma_f32 v105, v6, v105, v7
	v_fma_f32 v110, v6, v110, v7
	v_fma_f32 v115, v6, v115, v7
	v_fmac_f32_e32 v100, s73, v101
	v_fmac_f32_e32 v105, s26, v106
	v_fmac_f32_e32 v110, s27, v111
	v_fmac_f32_e32 v115, s32, v116
	v_mul_f32_e32 v100, v100, v103
	v_mul_f32_e32 v105, v105, v108
	v_mul_f32_e32 v110, v110, v113
	v_mul_f32_e32 v115, v115, v118
	v_cvt_pk_bf16_f32 v169, v100, v100
	v_cvt_pk_bf16_f32 v175, v105, v105
	v_cvt_pk_bf16_f32 v242, v110, v110
	v_cvt_pk_bf16_f32 v248, v115, v115
	global_store_short v2, v169, s[28:29]
	s_add_u32 s28, s28, 0x1000
	s_addc_u32 s29, s29, 0
	global_store_short v2, v175, s[28:29]
	s_add_u32 s28, s28, 0x1000
	s_addc_u32 s29, s29, 0
	global_store_short v2, v242, s[28:29]
	s_add_u32 s28, s28, 0x1000
	s_addc_u32 s29, s29, 0
	global_store_short v2, v248, s[28:29]
	s_add_u32 s28, s28, 0x1000
	s_addc_u32 s29, s29, 0
	s_waitcnt vmcnt(8)
	ds_write_b128 v12, v[120:123] offset:0
	ds_write_b128 v12, v[124:127] offset:1024
	ds_write_b128 v12, v[128:131] offset:16384
	ds_write_b128 v12, v[132:135] offset:17408
	ds_write_b128 v14, v[136:139]
	v_readlane_b32 s69, v159, 0
	v_readlane_b32 s70, v159, 1
	v_readlane_b32 s71, v159, 2
	v_readlane_b32 s72, v159, 3
	v_readlane_b32 s73, v159, 4
	v_readlane_b32 s26, v159, 5
	v_readlane_b32 s27, v159, 6
	v_readlane_b32 s32, v159, 7
	global_load_dwordx4 v[120:123], v11, s[6:7]
	global_load_dwordx4 v[124:127], v11, s[6:7] offset:1024
	global_load_dwordx4 v[128:131], v11, s[8:9]
	global_load_dwordx4 v[132:135], v11, s[8:9] offset:1024
	global_load_dwordx4 v[136:139], v11, s[10:11]
	global_load_dword v159, v158, s[12:13]
	s_add_u32 s6, s6, 0x10000
	s_addc_u32 s7, s7, 0
	s_add_u32 s8, s8, 0x10000
	s_addc_u32 s9, s9, 0
	s_add_u32 s10, s10, 0x8000
	s_addc_u32 s11, s11, 0
	s_add_u32 s12, s12, 0x400
	s_addc_u32 s13, s13, 0
	s_waitcnt lgkmcnt(0)
	s_barrier
	ds_read_b32 v80, v154 offset:0
	ds_read_b32 v81, v154 offset:16384
	ds_read_u16 v83, v156 offset:0
	ds_read_b32 v85, v154 offset:2048
	ds_read_b32 v86, v154 offset:18432
	ds_read_u16 v88, v156 offset:1024
	ds_read_b32 v90, v154 offset:4096
	ds_read_b32 v91, v154 offset:20480
	ds_read_u16 v93, v156 offset:2048
	ds_read_b32 v95, v154 offset:6144
	ds_read_b32 v96, v154 offset:22528
	ds_read_u16 v98, v156 offset:3072
	ds_read_b32 v100, v154 offset:8192
	ds_read_b32 v101, v154 offset:24576
	ds_read_u16 v103, v156 offset:4096
	ds_read_b32 v105, v154 offset:10240
	ds_read_b32 v106, v154 offset:26624
	ds_read_u16 v108, v156 offset:5120
	ds_read_b32 v110, v154 offset:12288
	ds_read_b32 v111, v154 offset:28672
	ds_read_u16 v113, v156 offset:6144
	ds_read_b32 v115, v154 offset:14336
	ds_read_b32 v116, v154 offset:30720
	ds_read_u16 v118, v156 offset:7168
	s_waitcnt lgkmcnt(0)
; __device__ __forceinline__ float dpp_xor1(float x) { return __builtin_bit_cast(float, __builtin_amdgcn_update_dpp(0, __builtin_bit_cast(int, x), 0xB1, 0xF, 0xF, true)); }
; __device__ __forceinline__ float dpp_xor2(float x) { return __builtin_bit_cast(float, __builtin_amdgcn_update_dpp(0, __builtin_bit_cast(int, x), 0x4E, 0xF, 0xF, true)); }
; __device__ __forceinline__ float dpp_hmir(float x) { return __builtin_bit_cast(float, __builtin_amdgcn_update_dpp(0, __builtin_bit_cast(int, x), 0x141, 0xF, 0xF, true)); }
; __device__ __forceinline__ float dpp_mir(float x)  { return __builtin_bit_cast(float, __builtin_amdgcn_update_dpp(0, __builtin_bit_cast(int, x), 0x140, 0xF, 0xF, true)); }
; __device__ __forceinline__ float red16(float x) { x += dpp_xor1(x); x += dpp_xor2(x); x += dpp_hmir(x); x += dpp_mir(x); return x; }
; __device__ __forceinline__ float wsum(float x) {
;     x = red16(x); const int xi = __builtin_bit_cast(int, x);
;     const float r0 = __builtin_bit_cast(float, __builtin_amdgcn_readlane(xi, 0)), r1 = __builtin_bit_cast(float, __builtin_amdgcn_readlane(xi, 16));
;     const float r2 = __builtin_bit_cast(float, __builtin_amdgcn_readlane(xi, 32)), r3 = __builtin_bit_cast(float, __builtin_amdgcn_readlane(xi, 48));
;     return (r0 + r1) + (r2 + r3);
; }
; __device__ __forceinline__ void rw_post(Frame& F) {
;     ...
;             for (int q = 0; q < 8; ++q) { const int row = rb0 + t0 + q;
;                 const float mean = wsum(y[q]) * (1.f / 64.f); const float dv = y[q] - mean; const float var = wsum(dv * dv) * (1.f / 64.f);
;                 const float yn = dv * (1.f / sqrtf(var + 64e-5f)) * g_ + b_;
	v_add_f32_e32 v80, v80, v24
	v_add_f32_e32 v85, v85, v25
	v_add_f32_e32 v90, v90, v26
	v_add_f32_e32 v95, v95, v27
	v_add_f32_dpp v168, v80, v80 quad_perm:[1,0,3,2] row_mask:0xf bank_mask:0xf bound_ctrl:1
	v_add_f32_dpp v174, v85, v85 quad_perm:[1,0,3,2] row_mask:0xf bank_mask:0xf bound_ctrl:1
	v_add_f32_dpp v241, v90, v90 quad_perm:[1,0,3,2] row_mask:0xf bank_mask:0xf bound_ctrl:1
	v_add_f32_dpp v247, v95, v95 quad_perm:[1,0,3,2] row_mask:0xf bank_mask:0xf bound_ctrl:1
	v_add_f32_dpp v168, v168, v168 quad_perm:[2,3,0,1] row_mask:0xf bank_mask:0xf bound_ctrl:1
	v_add_f32_dpp v174, v174, v174 quad_perm:[2,3,0,1] row_mask:0xf bank_mask:0xf bound_ctrl:1
	v_add_f32_dpp v241, v241, v241 quad_perm:[2,3,0,1] row_mask:0xf bank_mask:0xf bound_ctrl:1
	v_add_f32_dpp v247, v247, v247 quad_perm:[2,3,0,1] row_mask:0xf bank_mask:0xf bound_ctrl:1
	v_add_f32_dpp v168, v168, v168 row_half_mirror row_mask:0xf bank_mask:0xf bound_ctrl:1
	v_add_f32_dpp v174, v174, v174 row_half_mirror row_mask:0xf bank_mask:0xf bound_ctrl:1
	v_add_f32_dpp v241, v241, v241 row_half_mirror row_mask:0xf bank_mask:0xf bound_ctrl:1
	v_add_f32_dpp v247, v247, v247 row_half_mirror row_mask:0xf bank_mask:0xf bound_ctrl:1
	v_add_f32_dpp v168, v168, v168 row_mirror row_mask:0xf bank_mask:0xf bound_ctrl:1
	v_add_f32_dpp v174, v174, v174 row_mirror row_mask:0xf bank_mask:0xf bound_ctrl:1
	v_add_f32_dpp v241, v241, v241 row_mirror row_mask:0xf bank_mask:0xf bound_ctrl:1
	v_add_f32_dpp v247, v247, v247 row_mirror row_mask:0xf bank_mask:0xf bound_ctrl:1
	v_readlane_b32 s36, v168, 16
	v_readlane_b32 s40, v174, 16
	v_readlane_b32 s44, v241, 16
	v_readlane_b32 s48, v247, 16
	v_readlane_b32 s37, v168, 48
	v_readlane_b32 s41, v174, 48
	v_readlane_b32 s45, v241, 48
	v_readlane_b32 s49, v247, 48
	v_readlane_b32 s38, v168, 0
	v_readlane_b32 s42, v174, 0
	v_readlane_b32 s46, v241, 0
	v_readlane_b32 s50, v247, 0
	v_readlane_b32 s39, v168, 32
	v_readlane_b32 s43, v174, 32
	v_readlane_b32 s47, v241, 32
	v_readlane_b32 s51, v247, 32
	v_mov_b32_e32 v168, s36
	v_mov_b32_e32 v174, s40
	v_mov_b32_e32 v241, s44
	v_mov_b32_e32 v247, s48
	v_mov_b32_e32 v169, s37
	v_mov_b32_e32 v175, s41
	v_mov_b32_e32 v242, s45
	v_mov_b32_e32 v248, s49
	v_add_f32_e32 v168, s38, v168
	v_add_f32_e32 v174, s42, v174
	v_add_f32_e32 v241, s46, v241
	v_add_f32_e32 v247, s50, v247
	v_add_f32_e32 v169, s39, v169
	v_add_f32_e32 v175, s43, v175
	v_add_f32_e32 v242, s47, v242
	v_add_f32_e32 v248, s51, v248
	v_add_f32_e32 v168, v168, v169
	v_add_f32_e32 v174, v174, v175
	v_add_f32_e32 v241, v241, v242
	v_add_f32_e32 v247, v247, v248
	v_fmamk_f32 v80, v168, 0xbc800000, v80
	v_fmamk_f32 v85, v174, 0xbc800000, v85
	v_fmamk_f32 v90, v241, 0xbc800000, v90
	v_fmamk_f32 v95, v247, 0xbc800000, v95
	v_mul_f32_e32 v168, v80, v80
	v_mul_f32_e32 v174, v85, v85
	v_mul_f32_e32 v241, v90, v90
	v_mul_f32_e32 v247, v95, v95
	v_mov_b32_dpp v168, v168 quad_perm:[1,0,3,2] row_mask:0xf bank_mask:0xf bound_ctrl:1
	v_mov_b32_dpp v174, v174 quad_perm:[1,0,3,2] row_mask:0xf bank_mask:0xf bound_ctrl:1
	v_mov_b32_dpp v241, v241 quad_perm:[1,0,3,2] row_mask:0xf bank_mask:0xf bound_ctrl:1
	v_mov_b32_dpp v247, v247 quad_perm:[1,0,3,2] row_mask:0xf bank_mask:0xf bound_ctrl:1
	v_fmac_f32_e32 v168, v80, v80
	v_fmac_f32_e32 v174, v85, v85
	v_fmac_f32_e32 v241, v90, v90
	v_fmac_f32_e32 v247, v95, v95
	v_add_f32_dpp v168, v168, v168 quad_perm:[2,3,0,1] row_mask:0xf bank_mask:0xf bound_ctrl:1
	v_add_f32_dpp v174, v174, v174 quad_perm:[2,3,0,1] row_mask:0xf bank_mask:0xf bound_ctrl:1
	v_add_f32_dpp v241, v241, v241 quad_perm:[2,3,0,1] row_mask:0xf bank_mask:0xf bound_ctrl:1
	v_add_f32_dpp v247, v247, v247 quad_perm:[2,3,0,1] row_mask:0xf bank_mask:0xf bound_ctrl:1
	v_add_f32_dpp v168, v168, v168 row_half_mirror row_mask:0xf bank_mask:0xf bound_ctrl:1
	v_add_f32_dpp v174, v174, v174 row_half_mirror row_mask:0xf bank_mask:0xf bound_ctrl:1
	v_add_f32_dpp v241, v241, v241 row_half_mirror row_mask:0xf bank_mask:0xf bound_ctrl:1
	v_add_f32_dpp v247, v247, v247 row_half_mirror row_mask:0xf bank_mask:0xf bound_ctrl:1
	v_add_f32_dpp v168, v168, v168 row_mirror row_mask:0xf bank_mask:0xf bound_ctrl:1
	v_add_f32_dpp v174, v174, v174 row_mirror row_mask:0xf bank_mask:0xf bound_ctrl:1
	v_add_f32_dpp v241, v241, v241 row_mirror row_mask:0xf bank_mask:0xf bound_ctrl:1
	v_add_f32_dpp v247, v247, v247 row_mirror row_mask:0xf bank_mask:0xf bound_ctrl:1
	v_readlane_b32 s36, v168, 16
	v_readlane_b32 s40, v174, 16
	v_readlane_b32 s44, v241, 16
	v_readlane_b32 s48, v247, 16
	v_readlane_b32 s37, v168, 48
	v_readlane_b32 s41, v174, 48
	v_readlane_b32 s45, v241, 48
	v_readlane_b32 s49, v247, 48
	v_readlane_b32 s38, v168, 0
	v_readlane_b32 s42, v174, 0
	v_readlane_b32 s46, v241, 0
	v_readlane_b32 s50, v247, 0
	v_readlane_b32 s39, v168, 32
	v_readlane_b32 s43, v174, 32
	v_readlane_b32 s47, v241, 32
	v_readlane_b32 s51, v247, 32
	v_mov_b32_e32 v168, s36
	v_mov_b32_e32 v174, s40
	v_mov_b32_e32 v241, s44
	v_mov_b32_e32 v247, s48
	v_mov_b32_e32 v169, s37
	v_mov_b32_e32 v175, s41
	v_mov_b32_e32 v242, s45
	v_mov_b32_e32 v248, s49
	v_add_f32_e32 v168, s38, v168
	v_add_f32_e32 v174, s42, v174
	v_add_f32_e32 v241, s46, v241
	v_add_f32_e32 v247, s50, v247
	v_add_f32_e32 v169, s39, v169
	v_add_f32_e32 v175, s43, v175
	v_add_f32_e32 v242, s47, v242
	v_add_f32_e32 v248, s51, v248
	v_add_f32_e32 v168, v168, v169
	v_add_f32_e32 v174, v174, v175
	v_add_f32_e32 v241, v241, v242
	v_add_f32_e32 v247, v247, v248
	v_fmamk_f32 v168, v168, 0x3c800000, v9
	v_fmamk_f32 v174, v174, 0x3c800000, v9
	v_fmamk_f32 v241, v241, 0x3c800000, v9
	v_fmamk_f32 v247, v247, 0x3c800000, v9
	v_readfirstlane_b32 s40, v174
	v_readfirstlane_b32 s44, v241
; __device__ __forceinline__ float bf2f(bf16 x) { return __uint_as_float(((unsigned)x) << 16); }
; __device__ __forceinline__ unsigned f2bf(float f) { return cvt_pk_bf16(f, 0.f) & 0xffffu; }
; __device__ __forceinline__ float dpp_xor1(float x) { return __builtin_bit_cast(float, __builtin_amdgcn_update_dpp(0, __builtin_bit_cast(int, x), 0xB1, 0xF, 0xF, true)); }
; __device__ __forceinline__ float dpp_xor2(float x) { return __builtin_bit_cast(float, __builtin_amdgcn_update_dpp(0, __builtin_bit_cast(int, x), 0x4E, 0xF, 0xF, true)); }
; __device__ __forceinline__ float dpp_hmir(float x) { return __builtin_bit_cast(float, __builtin_amdgcn_update_dpp(0, __builtin_bit_cast(int, x), 0x141, 0xF, 0xF, true)); }
; __device__ __forceinline__ float dpp_mir(float x)  { return __builtin_bit_cast(float, __builtin_amdgcn_update_dpp(0, __builtin_bit_cast(int, x), 0x140, 0xF, 0xF, true)); }
; __device__ __forceinline__ float red16(float x) { x += dpp_xor1(x); x += dpp_xor2(x); x += dpp_hmir(x); x += dpp_mir(x); return x; }
; __device__ __forceinline__ float wsum(float x) {
;     x = red16(x); const int xi = __builtin_bit_cast(int, x);
;     const float r0 = __builtin_bit_cast(float, __builtin_amdgcn_readlane(xi, 0)), r1 = __builtin_bit_cast(float, __builtin_amdgcn_readlane(xi, 16));
;     const float r2 = __builtin_bit_cast(float, __builtin_amdgcn_readlane(xi, 32)), r3 = __builtin_bit_cast(float, __builtin_amdgcn_readlane(xi, 48));
;     return (r0 + r1) + (r2 + r3);
; }
; __device__ __forceinline__ void rw_post(Frame& F) {
;     ...
;             for (int q = 0; q < 8; ++q) { const int row = rb0 + t0 + q;
;                 const float mean = wsum(y[q]) * (1.f / 64.f); const float dv = y[q] - mean; const float var = wsum(dv * dv) * (1.f / 64.f);
;                 const float yn = dv * (1.f / sqrtf(var + 64e-5f)) * g_ + b_;
;                 OB[(size_t)row * DH + col] = (bf16)f2bf((yn + rk[q] * vv[q]) * bf2f(gg[q])); }
	v_readfirstlane_b32 s48, v247
	v_writelane_b32 v168, s40, 1
	v_writelane_b32 v168, s44, 2
	v_writelane_b32 v168, s48, 3
	v_mul_f32_e32 v169, 0x4f800000, v168
	v_cmp_gt_f32_e64 s[52:53], s68, v168
	v_mov_b32_e32 v170, v168
	s_nop 1
	v_cndmask_b32_e64 v168, v170, v169, s[52:53]
	v_sqrt_f32_e32 v169, v168
	s_nop 0
	v_add_u32_e32 v170, -1, v169
	v_fma_f32 v171, -v170, v169, v168
	v_cmp_ge_f32_e64 s[60:61], 0, v171
	v_add_u32_e32 v171, 1, v169
	s_nop 1
	v_cndmask_b32_e64 v170, v169, v170, s[60:61]
	v_fma_f32 v169, -v171, v169, v168
	v_cmp_lt_f32_e64 s[60:61], 0, v169
	s_nop 1
	v_cndmask_b32_e64 v169, v170, v171, s[60:61]
	v_mul_f32_e32 v170, 0x37800000, v169
	v_cndmask_b32_e64 v169, v169, v170, s[52:53]
	v_cmp_class_f32_e64 s[60:61], v168, v8
	s_nop 1
	v_cndmask_b32_e64 v168, v169, v168, s[60:61]
	v_div_scale_f32 v169, s[60:61], v168, v168, 1.0
	v_rcp_f32_e32 v170, v169
	s_nop 0
	v_fma_f32 v171, -v169, v170, 1.0
	v_fmac_f32_e32 v170, v171, v170
	v_div_scale_f32 v171, vcc, 1.0, v168, 1.0
	v_mul_f32_e32 v172, v171, v170
	v_fma_f32 v173, -v169, v172, v171
	v_fmac_f32_e32 v172, v173, v170
	v_fma_f32 v169, -v169, v172, v171
	v_div_fmas_f32 v169, v169, v170, v172
	v_div_fixup_f32 v168, v169, v168, 1.0
	s_nop 0
	v_readlane_b32 s37, v168, 0
	v_readlane_b32 s41, v168, 1
	v_readlane_b32 s45, v168, 2
	v_readlane_b32 s49, v168, 3
	v_mul_f32_e32 v80, s37, v80
	v_mul_f32_e32 v85, s41, v85
	v_mul_f32_e32 v90, s45, v90
	v_mul_f32_e32 v95, s49, v95
	v_lshlrev_b32_e32 v83, 16, v83
	v_lshlrev_b32_e32 v88, 16, v88
	v_lshlrev_b32_e32 v93, 16, v93
	v_lshlrev_b32_e32 v98, 16, v98
	v_fma_f32 v80, v6, v80, v7
	v_fma_f32 v85, v6, v85, v7
	v_fma_f32 v90, v6, v90, v7
	v_fma_f32 v95, v6, v95, v7
	v_fmac_f32_e32 v80, s69, v81
	v_fmac_f32_e32 v85, s70, v86
	v_fmac_f32_e32 v90, s71, v91
	v_fmac_f32_e32 v95, s72, v96
	v_mul_f32_e32 v80, v80, v83
	v_mul_f32_e32 v85, v85, v88
	v_mul_f32_e32 v90, v90, v93
	v_mul_f32_e32 v95, v95, v98
	v_cvt_pk_bf16_f32 v169, v80, v80
	v_cvt_pk_bf16_f32 v175, v85, v85
	v_cvt_pk_bf16_f32 v242, v90, v90
	v_cvt_pk_bf16_f32 v248, v95, v95
	global_store_short v2, v169, s[28:29]
	s_add_u32 s28, s28, 0x1000
	s_addc_u32 s29, s29, 0
	global_store_short v2, v175, s[28:29]
	s_add_u32 s28, s28, 0x1000
	s_addc_u32 s29, s29, 0
	global_store_short v2, v242, s[28:29]
	s_add_u32 s28, s28, 0x1000
	s_addc_u32 s29, s29, 0
	global_store_short v2, v248, s[28:29]
	s_add_u32 s28, s28, 0x1000
	s_addc_u32 s29, s29, 0
	v_add_f32_e32 v100, v100, v40
	v_add_f32_e32 v105, v105, v41
	v_add_f32_e32 v110, v110, v42
	v_add_f32_e32 v115, v115, v43
	v_add_f32_dpp v168, v100, v100 quad_perm:[1,0,3,2] row_mask:0xf bank_mask:0xf bound_ctrl:1
	v_add_f32_dpp v174, v105, v105 quad_perm:[1,0,3,2] row_mask:0xf bank_mask:0xf bound_ctrl:1
	v_add_f32_dpp v241, v110, v110 quad_perm:[1,0,3,2] row_mask:0xf bank_mask:0xf bound_ctrl:1
	v_add_f32_dpp v247, v115, v115 quad_perm:[1,0,3,2] row_mask:0xf bank_mask:0xf bound_ctrl:1
	v_add_f32_dpp v168, v168, v168 quad_perm:[2,3,0,1] row_mask:0xf bank_mask:0xf bound_ctrl:1
	v_add_f32_dpp v174, v174, v174 quad_perm:[2,3,0,1] row_mask:0xf bank_mask:0xf bound_ctrl:1
	v_add_f32_dpp v241, v241, v241 quad_perm:[2,3,0,1] row_mask:0xf bank_mask:0xf bound_ctrl:1
	v_add_f32_dpp v247, v247, v247 quad_perm:[2,3,0,1] row_mask:0xf bank_mask:0xf bound_ctrl:1
	v_add_f32_dpp v168, v168, v168 row_half_mirror row_mask:0xf bank_mask:0xf bound_ctrl:1
	v_add_f32_dpp v174, v174, v174 row_half_mirror row_mask:0xf bank_mask:0xf bound_ctrl:1
	v_add_f32_dpp v241, v241, v241 row_half_mirror row_mask:0xf bank_mask:0xf bound_ctrl:1
	v_add_f32_dpp v247, v247, v247 row_half_mirror row_mask:0xf bank_mask:0xf bound_ctrl:1
	v_add_f32_dpp v168, v168, v168 row_mirror row_mask:0xf bank_mask:0xf bound_ctrl:1
	v_add_f32_dpp v174, v174, v174 row_mirror row_mask:0xf bank_mask:0xf bound_ctrl:1
	v_add_f32_dpp v241, v241, v241 row_mirror row_mask:0xf bank_mask:0xf bound_ctrl:1
	v_add_f32_dpp v247, v247, v247 row_mirror row_mask:0xf bank_mask:0xf bound_ctrl:1
	v_readlane_b32 s36, v168, 16
	v_readlane_b32 s40, v174, 16
	v_readlane_b32 s44, v241, 16
	v_readlane_b32 s48, v247, 16
	v_readlane_b32 s37, v168, 48
	v_readlane_b32 s41, v174, 48
	v_readlane_b32 s45, v241, 48
	v_readlane_b32 s49, v247, 48
	v_readlane_b32 s38, v168, 0
	v_readlane_b32 s42, v174, 0
	v_readlane_b32 s46, v241, 0
	v_readlane_b32 s50, v247, 0
	v_readlane_b32 s39, v168, 32
	v_readlane_b32 s43, v174, 32
	v_readlane_b32 s47, v241, 32
	v_readlane_b32 s51, v247, 32
	v_mov_b32_e32 v168, s36
	v_mov_b32_e32 v174, s40
	v_mov_b32_e32 v241, s44
	v_mov_b32_e32 v247, s48
	v_mov_b32_e32 v169, s37
	v_mov_b32_e32 v175, s41
	v_mov_b32_e32 v242, s45
	v_mov_b32_e32 v248, s49
	v_add_f32_e32 v168, s38, v168
	v_add_f32_e32 v174, s42, v174
	v_add_f32_e32 v241, s46, v241
	v_add_f32_e32 v247, s50, v247
	v_add_f32_e32 v169, s39, v169
	v_add_f32_e32 v175, s43, v175
	v_add_f32_e32 v242, s47, v242
	v_add_f32_e32 v248, s51, v248
	v_add_f32_e32 v168, v168, v169
	v_add_f32_e32 v174, v174, v175
	v_add_f32_e32 v241, v241, v242
	v_add_f32_e32 v247, v247, v248
	v_fmamk_f32 v100, v168, 0xbc800000, v100
	v_fmamk_f32 v105, v174, 0xbc800000, v105
	v_fmamk_f32 v110, v241, 0xbc800000, v110
	v_fmamk_f32 v115, v247, 0xbc800000, v115
	v_mul_f32_e32 v168, v100, v100
	v_mul_f32_e32 v174, v105, v105
	v_mul_f32_e32 v241, v110, v110
	v_mul_f32_e32 v247, v115, v115
	v_mov_b32_dpp v168, v168 quad_perm:[1,0,3,2] row_mask:0xf bank_mask:0xf bound_ctrl:1
	v_mov_b32_dpp v174, v174 quad_perm:[1,0,3,2] row_mask:0xf bank_mask:0xf bound_ctrl:1
	v_mov_b32_dpp v241, v241 quad_perm:[1,0,3,2] row_mask:0xf bank_mask:0xf bound_ctrl:1
	v_mov_b32_dpp v247, v247 quad_perm:[1,0,3,2] row_mask:0xf bank_mask:0xf bound_ctrl:1
; __device__ __forceinline__ float bf2f(bf16 x) { return __uint_as_float(((unsigned)x) << 16); }
; __device__ __forceinline__ unsigned f2bf(float f) { return cvt_pk_bf16(f, 0.f) & 0xffffu; }
; #define POST_LD(Y_, V_, G_, R_, C_, t) do { _Pragma("unroll") for (int q = 0; q < 8; ++q) { const size_t o_ = (size_t)((t) + q) * DH; Y_[q] = yp[o_]; V_[q] = vp[o_]; G_[q] = gp[o_]; R_[q] = rp[((t) + q) * 32]; C_[q] = cp[o_]; } } while (0)
; __device__ __forceinline__ void rw_post(Frame& F) {
;     ...
;         POST_LD(y, vv, gg, rk, cc, 0);
;         for (int t0 = 0; t0 < 64; t0 += 8) {
;             float ny[8], nv[8], nr[8], nc[8]; bf16 ng[8];
;             const int tn = t0 + 8 < 64 ? t0 + 8 : t0;
;             POST_LD(ny, nv, ng, nr, nc, tn);
;     ...
;             for (int q = 0; q < 8; ++q) { const int row = rb0 + t0 + q;
;                 const float mean = wsum(y[q]) * (1.f / 64.f); const float dv = y[q] - mean; const float var = wsum(dv * dv) * (1.f / 64.f);
;                 const float yn = dv * (1.f / sqrtf(var + 64e-5f)) * g_ + b_;
;                 OB[(size_t)row * DH + col] = (bf16)f2bf((yn + rk[q] * vv[q]) * bf2f(gg[q])); }
; #pragma unroll
;             for (int q = 0; q < 8; ++q) { y[q] = ny[q]; vv[q] = nv[q]; gg[q] = ng[q]; rk[q] = nr[q]; cc[q] = nc[q]; }
	v_fmac_f32_e32 v168, v100, v100
	v_fmac_f32_e32 v174, v105, v105
	v_fmac_f32_e32 v241, v110, v110
	v_fmac_f32_e32 v247, v115, v115
	v_add_f32_dpp v168, v168, v168 quad_perm:[2,3,0,1] row_mask:0xf bank_mask:0xf bound_ctrl:1
	v_add_f32_dpp v174, v174, v174 quad_perm:[2,3,0,1] row_mask:0xf bank_mask:0xf bound_ctrl:1
	v_add_f32_dpp v241, v241, v241 quad_perm:[2,3,0,1] row_mask:0xf bank_mask:0xf bound_ctrl:1
	v_add_f32_dpp v247, v247, v247 quad_perm:[2,3,0,1] row_mask:0xf bank_mask:0xf bound_ctrl:1
	v_add_f32_dpp v168, v168, v168 row_half_mirror row_mask:0xf bank_mask:0xf bound_ctrl:1
	v_add_f32_dpp v174, v174, v174 row_half_mirror row_mask:0xf bank_mask:0xf bound_ctrl:1
	v_add_f32_dpp v241, v241, v241 row_half_mirror row_mask:0xf bank_mask:0xf bound_ctrl:1
	v_add_f32_dpp v247, v247, v247 row_half_mirror row_mask:0xf bank_mask:0xf bound_ctrl:1
	v_add_f32_dpp v168, v168, v168 row_mirror row_mask:0xf bank_mask:0xf bound_ctrl:1
	v_add_f32_dpp v174, v174, v174 row_mirror row_mask:0xf bank_mask:0xf bound_ctrl:1
	v_add_f32_dpp v241, v241, v241 row_mirror row_mask:0xf bank_mask:0xf bound_ctrl:1
	v_add_f32_dpp v247, v247, v247 row_mirror row_mask:0xf bank_mask:0xf bound_ctrl:1
	v_readlane_b32 s36, v168, 16
	v_readlane_b32 s40, v174, 16
	v_readlane_b32 s44, v241, 16
	v_readlane_b32 s48, v247, 16
	v_readlane_b32 s37, v168, 48
	v_readlane_b32 s41, v174, 48
	v_readlane_b32 s45, v241, 48
	v_readlane_b32 s49, v247, 48
	v_readlane_b32 s38, v168, 0
	v_readlane_b32 s42, v174, 0
	v_readlane_b32 s46, v241, 0
	v_readlane_b32 s50, v247, 0
	v_readlane_b32 s39, v168, 32
	v_readlane_b32 s43, v174, 32
	v_readlane_b32 s47, v241, 32
	v_readlane_b32 s51, v247, 32
	v_mov_b32_e32 v168, s36
	v_mov_b32_e32 v174, s40
	v_mov_b32_e32 v241, s44
	v_mov_b32_e32 v247, s48
	v_mov_b32_e32 v169, s37
	v_mov_b32_e32 v175, s41
	v_mov_b32_e32 v242, s45
	v_mov_b32_e32 v248, s49
	v_add_f32_e32 v168, s38, v168
	v_add_f32_e32 v174, s42, v174
	v_add_f32_e32 v241, s46, v241
	v_add_f32_e32 v247, s50, v247
	v_add_f32_e32 v169, s39, v169
	v_add_f32_e32 v175, s43, v175
	v_add_f32_e32 v242, s47, v242
	v_add_f32_e32 v248, s51, v248
	v_add_f32_e32 v168, v168, v169
	v_add_f32_e32 v174, v174, v175
	v_add_f32_e32 v241, v241, v242
	v_add_f32_e32 v247, v247, v248
	v_fmamk_f32 v168, v168, 0x3c800000, v9
	v_fmamk_f32 v174, v174, 0x3c800000, v9
	v_fmamk_f32 v241, v241, 0x3c800000, v9
	v_fmamk_f32 v247, v247, 0x3c800000, v9
	v_readfirstlane_b32 s40, v174
	v_readfirstlane_b32 s44, v241
	v_readfirstlane_b32 s48, v247
	v_writelane_b32 v168, s40, 1
	v_writelane_b32 v168, s44, 2
	v_writelane_b32 v168, s48, 3
	v_mul_f32_e32 v169, 0x4f800000, v168
	v_cmp_gt_f32_e64 s[52:53], s68, v168
	v_mov_b32_e32 v170, v168
	s_nop 1
	v_cndmask_b32_e64 v168, v170, v169, s[52:53]
	v_sqrt_f32_e32 v169, v168
	s_nop 0
	v_add_u32_e32 v170, -1, v169
	v_fma_f32 v171, -v170, v169, v168
	v_cmp_ge_f32_e64 s[60:61], 0, v171
	v_add_u32_e32 v171, 1, v169
	s_nop 1
	v_cndmask_b32_e64 v170, v169, v170, s[60:61]
	v_fma_f32 v169, -v171, v169, v168
	v_cmp_lt_f32_e64 s[60:61], 0, v169
	s_nop 1
	v_cndmask_b32_e64 v169, v170, v171, s[60:61]
	v_mul_f32_e32 v170, 0x37800000, v169
	v_cndmask_b32_e64 v169, v169, v170, s[52:53]
	v_cmp_class_f32_e64 s[60:61], v168, v8
	s_nop 1
	v_cndmask_b32_e64 v168, v169, v168, s[60:61]
	v_div_scale_f32 v169, s[60:61], v168, v168, 1.0
	v_rcp_f32_e32 v170, v169
	s_nop 0
	v_fma_f32 v171, -v169, v170, 1.0
	v_fmac_f32_e32 v170, v171, v170
	v_div_scale_f32 v171, vcc, 1.0, v168, 1.0
	v_mul_f32_e32 v172, v171, v170
	v_fma_f32 v173, -v169, v172, v171
	v_fmac_f32_e32 v172, v173, v170
	v_fma_f32 v169, -v169, v172, v171
	v_div_fmas_f32 v169, v169, v170, v172
	v_div_fixup_f32 v168, v169, v168, 1.0
	s_nop 0
	v_readlane_b32 s37, v168, 0
	v_readlane_b32 s41, v168, 1
	v_readlane_b32 s45, v168, 2
	v_readlane_b32 s49, v168, 3
	v_mul_f32_e32 v100, s37, v100
	v_mul_f32_e32 v105, s41, v105
	v_mul_f32_e32 v110, s45, v110
	v_mul_f32_e32 v115, s49, v115
	v_lshlrev_b32_e32 v103, 16, v103
	v_lshlrev_b32_e32 v108, 16, v108
	v_lshlrev_b32_e32 v113, 16, v113
	v_lshlrev_b32_e32 v118, 16, v118
	v_fma_f32 v100, v6, v100, v7
	v_fma_f32 v105, v6, v105, v7
	v_fma_f32 v110, v6, v110, v7
	v_fma_f32 v115, v6, v115, v7
	v_fmac_f32_e32 v100, s73, v101
	v_fmac_f32_e32 v105, s26, v106
	v_fmac_f32_e32 v110, s27, v111
	v_fmac_f32_e32 v115, s32, v116
	v_mul_f32_e32 v100, v100, v103
	v_mul_f32_e32 v105, v105, v108
	v_mul_f32_e32 v110, v110, v113
	v_mul_f32_e32 v115, v115, v118
	v_cvt_pk_bf16_f32 v169, v100, v100
	v_cvt_pk_bf16_f32 v175, v105, v105
	v_cvt_pk_bf16_f32 v242, v110, v110
	v_cvt_pk_bf16_f32 v248, v115, v115
	global_store_short v2, v169, s[28:29]
	s_add_u32 s28, s28, 0x1000
	s_addc_u32 s29, s29, 0
	global_store_short v2, v175, s[28:29]
	s_add_u32 s28, s28, 0x1000
	s_addc_u32 s29, s29, 0
	global_store_short v2, v242, s[28:29]
	s_add_u32 s28, s28, 0x1000
	s_addc_u32 s29, s29, 0
	global_store_short v2, v248, s[28:29]
	s_add_u32 s28, s28, 0x1000
	s_addc_u32 s29, s29, 0
	s_waitcnt vmcnt(8)
	ds_write_b128 v13, v[120:123] offset:0
	ds_write_b128 v13, v[124:127] offset:1024
	ds_write_b128 v13, v[128:131] offset:16384
	ds_write_b128 v13, v[132:135] offset:17408
	ds_write_b128 v15, v[136:139]
	v_readlane_b32 s69, v159, 0
	v_readlane_b32 s70, v159, 1
	v_readlane_b32 s71, v159, 2
	v_readlane_b32 s72, v159, 3
	v_readlane_b32 s73, v159, 4
	v_readlane_b32 s26, v159, 5
	v_readlane_b32 s27, v159, 6
	v_readlane_b32 s32, v159, 7
	global_load_dwordx4 v[120:123], v11, s[6:7]
	global_load_dwordx4 v[124:127], v11, s[6:7] offset:1024
	global_load_dwordx4 v[128:131], v11, s[8:9]
	global_load_dwordx4 v[132:135], v11, s[8:9] offset:1024
	global_load_dwordx4 v[136:139], v11, s[10:11]
	global_load_dword v159, v158, s[12:13]
	s_add_u32 s6, s6, 0x10000
	s_addc_u32 s7, s7, 0
	s_add_u32 s8, s8, 0x10000
	s_addc_u32 s9, s9, 0
	s_add_u32 s10, s10, 0x8000
	s_addc_u32 s11, s11, 0
	s_add_u32 s12, s12, 0x400
	s_addc_u32 s13, s13, 0
	s_waitcnt lgkmcnt(0)
	s_barrier
; #define POST_LD(Y_, V_, G_, R_, C_, t) do { _Pragma("unroll") for (int q = 0; q < 8; ++q) { const size_t o_ = (size_t)((t) + q) * DH; Y_[q] = yp[o_]; V_[q] = vp[o_]; G_[q] = gp[o_]; R_[q] = rp[((t) + q) * 32]; C_[q] = cp[o_]; } } while (0)
; __device__ __forceinline__ void rw_post(Frame& F) {
;     ...
;         POST_LD(y, vv, gg, rk, cc, 0);
;     ...
;             for (int q = 0; q < 8; ++q) { const int row = rb0 + t0 + q;
;                 const float mean = wsum(y[q]) * (1.f / 64.f); const float dv = y[q] - mean; const float var = wsum(dv * dv) * (1.f / 64.f);
;                 const float yn = dv * (1.f / sqrtf(var + 64e-5f)) * g_ + b_;
	ds_read_b32 v80, v155 offset:0
	ds_read_b32 v81, v155 offset:16384
	ds_read_u16 v83, v157 offset:0
	ds_read_b32 v85, v155 offset:2048
	ds_read_b32 v86, v155 offset:18432
	ds_read_u16 v88, v157 offset:1024
	ds_read_b32 v90, v155 offset:4096
	ds_read_b32 v91, v155 offset:20480
	ds_read_u16 v93, v157 offset:2048
	ds_read_b32 v95, v155 offset:6144
	ds_read_b32 v96, v155 offset:22528
	ds_read_u16 v98, v157 offset:3072
	ds_read_b32 v100, v155 offset:8192
	ds_read_b32 v101, v155 offset:24576
	ds_read_u16 v103, v157 offset:4096
	ds_read_b32 v105, v155 offset:10240
	ds_read_b32 v106, v155 offset:26624
	ds_read_u16 v108, v157 offset:5120
	ds_read_b32 v110, v155 offset:12288
	ds_read_b32 v111, v155 offset:28672
	ds_read_u16 v113, v157 offset:6144
	ds_read_b32 v115, v155 offset:14336
	ds_read_b32 v116, v155 offset:30720
	ds_read_u16 v118, v157 offset:7168
	s_waitcnt lgkmcnt(0)
	v_add_f32_e32 v80, v80, v28
	v_add_f32_e32 v85, v85, v29
	v_add_f32_e32 v90, v90, v30
	v_add_f32_e32 v95, v95, v31
	v_add_f32_dpp v168, v80, v80 quad_perm:[1,0,3,2] row_mask:0xf bank_mask:0xf bound_ctrl:1
	v_add_f32_dpp v174, v85, v85 quad_perm:[1,0,3,2] row_mask:0xf bank_mask:0xf bound_ctrl:1
	v_add_f32_dpp v241, v90, v90 quad_perm:[1,0,3,2] row_mask:0xf bank_mask:0xf bound_ctrl:1
	v_add_f32_dpp v247, v95, v95 quad_perm:[1,0,3,2] row_mask:0xf bank_mask:0xf bound_ctrl:1
	v_add_f32_dpp v168, v168, v168 quad_perm:[2,3,0,1] row_mask:0xf bank_mask:0xf bound_ctrl:1
	v_add_f32_dpp v174, v174, v174 quad_perm:[2,3,0,1] row_mask:0xf bank_mask:0xf bound_ctrl:1
	v_add_f32_dpp v241, v241, v241 quad_perm:[2,3,0,1] row_mask:0xf bank_mask:0xf bound_ctrl:1
	v_add_f32_dpp v247, v247, v247 quad_perm:[2,3,0,1] row_mask:0xf bank_mask:0xf bound_ctrl:1
	v_add_f32_dpp v168, v168, v168 row_half_mirror row_mask:0xf bank_mask:0xf bound_ctrl:1
	v_add_f32_dpp v174, v174, v174 row_half_mirror row_mask:0xf bank_mask:0xf bound_ctrl:1
	v_add_f32_dpp v241, v241, v241 row_half_mirror row_mask:0xf bank_mask:0xf bound_ctrl:1
	v_add_f32_dpp v247, v247, v247 row_half_mirror row_mask:0xf bank_mask:0xf bound_ctrl:1
	v_add_f32_dpp v168, v168, v168 row_mirror row_mask:0xf bank_mask:0xf bound_ctrl:1
	v_add_f32_dpp v174, v174, v174 row_mirror row_mask:0xf bank_mask:0xf bound_ctrl:1
	v_add_f32_dpp v241, v241, v241 row_mirror row_mask:0xf bank_mask:0xf bound_ctrl:1
	v_add_f32_dpp v247, v247, v247 row_mirror row_mask:0xf bank_mask:0xf bound_ctrl:1
	v_readlane_b32 s36, v168, 16
	v_readlane_b32 s40, v174, 16
	v_readlane_b32 s44, v241, 16
	v_readlane_b32 s48, v247, 16
	v_readlane_b32 s37, v168, 48
	v_readlane_b32 s41, v174, 48
	v_readlane_b32 s45, v241, 48
	v_readlane_b32 s49, v247, 48
	v_readlane_b32 s38, v168, 0
	v_readlane_b32 s42, v174, 0
	v_readlane_b32 s46, v241, 0
	v_readlane_b32 s50, v247, 0
	v_readlane_b32 s39, v168, 32
	v_readlane_b32 s43, v174, 32
	v_readlane_b32 s47, v241, 32
	v_readlane_b32 s51, v247, 32
	v_mov_b32_e32 v168, s36
	v_mov_b32_e32 v174, s40
	v_mov_b32_e32 v241, s44
	v_mov_b32_e32 v247, s48
	v_mov_b32_e32 v169, s37
	v_mov_b32_e32 v175, s41
	v_mov_b32_e32 v242, s45
	v_mov_b32_e32 v248, s49
	v_add_f32_e32 v168, s38, v168
	v_add_f32_e32 v174, s42, v174
	v_add_f32_e32 v241, s46, v241
	v_add_f32_e32 v247, s50, v247
	v_add_f32_e32 v169, s39, v169
	v_add_f32_e32 v175, s43, v175
	v_add_f32_e32 v242, s47, v242
	v_add_f32_e32 v248, s51, v248
	v_add_f32_e32 v168, v168, v169
	v_add_f32_e32 v174, v174, v175
	v_add_f32_e32 v241, v241, v242
	v_add_f32_e32 v247, v247, v248
	v_fmamk_f32 v80, v168, 0xbc800000, v80
	v_fmamk_f32 v85, v174, 0xbc800000, v85
	v_fmamk_f32 v90, v241, 0xbc800000, v90
	v_fmamk_f32 v95, v247, 0xbc800000, v95
	v_mul_f32_e32 v168, v80, v80
	v_mul_f32_e32 v174, v85, v85
	v_mul_f32_e32 v241, v90, v90
	v_mul_f32_e32 v247, v95, v95
	v_mov_b32_dpp v168, v168 quad_perm:[1,0,3,2] row_mask:0xf bank_mask:0xf bound_ctrl:1
	v_mov_b32_dpp v174, v174 quad_perm:[1,0,3,2] row_mask:0xf bank_mask:0xf bound_ctrl:1
	v_mov_b32_dpp v241, v241 quad_perm:[1,0,3,2] row_mask:0xf bank_mask:0xf bound_ctrl:1
	v_mov_b32_dpp v247, v247 quad_perm:[1,0,3,2] row_mask:0xf bank_mask:0xf bound_ctrl:1
	v_fmac_f32_e32 v168, v80, v80
	v_fmac_f32_e32 v174, v85, v85
	v_fmac_f32_e32 v241, v90, v90
	v_fmac_f32_e32 v247, v95, v95
	v_add_f32_dpp v168, v168, v168 quad_perm:[2,3,0,1] row_mask:0xf bank_mask:0xf bound_ctrl:1
	v_add_f32_dpp v174, v174, v174 quad_perm:[2,3,0,1] row_mask:0xf bank_mask:0xf bound_ctrl:1
	v_add_f32_dpp v241, v241, v241 quad_perm:[2,3,0,1] row_mask:0xf bank_mask:0xf bound_ctrl:1
	v_add_f32_dpp v247, v247, v247 quad_perm:[2,3,0,1] row_mask:0xf bank_mask:0xf bound_ctrl:1
	v_add_f32_dpp v168, v168, v168 row_half_mirror row_mask:0xf bank_mask:0xf bound_ctrl:1
	v_add_f32_dpp v174, v174, v174 row_half_mirror row_mask:0xf bank_mask:0xf bound_ctrl:1
	v_add_f32_dpp v241, v241, v241 row_half_mirror row_mask:0xf bank_mask:0xf bound_ctrl:1
	v_add_f32_dpp v247, v247, v247 row_half_mirror row_mask:0xf bank_mask:0xf bound_ctrl:1
	v_add_f32_dpp v168, v168, v168 row_mirror row_mask:0xf bank_mask:0xf bound_ctrl:1
	v_add_f32_dpp v174, v174, v174 row_mirror row_mask:0xf bank_mask:0xf bound_ctrl:1
	v_add_f32_dpp v241, v241, v241 row_mirror row_mask:0xf bank_mask:0xf bound_ctrl:1
	v_add_f32_dpp v247, v247, v247 row_mirror row_mask:0xf bank_mask:0xf bound_ctrl:1
	v_readlane_b32 s36, v168, 16
	v_readlane_b32 s40, v174, 16
	v_readlane_b32 s44, v241, 16
	v_readlane_b32 s48, v247, 16
	v_readlane_b32 s37, v168, 48
	v_readlane_b32 s41, v174, 48
	v_readlane_b32 s45, v241, 48
	v_readlane_b32 s49, v247, 48
	v_readlane_b32 s38, v168, 0
	v_readlane_b32 s42, v174, 0
	v_readlane_b32 s46, v241, 0
	v_readlane_b32 s50, v247, 0
	v_readlane_b32 s39, v168, 32
; __device__ __forceinline__ float bf2f(bf16 x) { return __uint_as_float(((unsigned)x) << 16); }
; __device__ __forceinline__ unsigned f2bf(float f) { return cvt_pk_bf16(f, 0.f) & 0xffffu; }
; __device__ __forceinline__ float dpp_xor1(float x) { return __builtin_bit_cast(float, __builtin_amdgcn_update_dpp(0, __builtin_bit_cast(int, x), 0xB1, 0xF, 0xF, true)); }
; __device__ __forceinline__ float dpp_xor2(float x) { return __builtin_bit_cast(float, __builtin_amdgcn_update_dpp(0, __builtin_bit_cast(int, x), 0x4E, 0xF, 0xF, true)); }
; __device__ __forceinline__ float dpp_hmir(float x) { return __builtin_bit_cast(float, __builtin_amdgcn_update_dpp(0, __builtin_bit_cast(int, x), 0x141, 0xF, 0xF, true)); }
; __device__ __forceinline__ float dpp_mir(float x)  { return __builtin_bit_cast(float, __builtin_amdgcn_update_dpp(0, __builtin_bit_cast(int, x), 0x140, 0xF, 0xF, true)); }
; __device__ __forceinline__ float red16(float x) { x += dpp_xor1(x); x += dpp_xor2(x); x += dpp_hmir(x); x += dpp_mir(x); return x; }
; __device__ __forceinline__ float wsum(float x) {
;     x = red16(x); const int xi = __builtin_bit_cast(int, x);
;     const float r0 = __builtin_bit_cast(float, __builtin_amdgcn_readlane(xi, 0)), r1 = __builtin_bit_cast(float, __builtin_amdgcn_readlane(xi, 16));
;     const float r2 = __builtin_bit_cast(float, __builtin_amdgcn_readlane(xi, 32)), r3 = __builtin_bit_cast(float, __builtin_amdgcn_readlane(xi, 48));
;     return (r0 + r1) + (r2 + r3);
; }
; __device__ __forceinline__ void rw_post(Frame& F) {
;     ...
;             for (int q = 0; q < 8; ++q) { const int row = rb0 + t0 + q;
;                 const float mean = wsum(y[q]) * (1.f / 64.f); const float dv = y[q] - mean; const float var = wsum(dv * dv) * (1.f / 64.f);
;                 const float yn = dv * (1.f / sqrtf(var + 64e-5f)) * g_ + b_;
;                 OB[(size_t)row * DH + col] = (bf16)f2bf((yn + rk[q] * vv[q]) * bf2f(gg[q])); }
	v_readlane_b32 s43, v174, 32
	v_readlane_b32 s47, v241, 32
	v_readlane_b32 s51, v247, 32
	v_mov_b32_e32 v168, s36
	v_mov_b32_e32 v174, s40
	v_mov_b32_e32 v241, s44
	v_mov_b32_e32 v247, s48
	v_mov_b32_e32 v169, s37
	v_mov_b32_e32 v175, s41
	v_mov_b32_e32 v242, s45
	v_mov_b32_e32 v248, s49
	v_add_f32_e32 v168, s38, v168
	v_add_f32_e32 v174, s42, v174
	v_add_f32_e32 v241, s46, v241
	v_add_f32_e32 v247, s50, v247
	v_add_f32_e32 v169, s39, v169
	v_add_f32_e32 v175, s43, v175
	v_add_f32_e32 v242, s47, v242
	v_add_f32_e32 v248, s51, v248
	v_add_f32_e32 v168, v168, v169
	v_add_f32_e32 v174, v174, v175
	v_add_f32_e32 v241, v241, v242
	v_add_f32_e32 v247, v247, v248
	v_fmamk_f32 v168, v168, 0x3c800000, v9
	v_fmamk_f32 v174, v174, 0x3c800000, v9
	v_fmamk_f32 v241, v241, 0x3c800000, v9
	v_fmamk_f32 v247, v247, 0x3c800000, v9
	v_readfirstlane_b32 s40, v174
	v_readfirstlane_b32 s44, v241
	v_readfirstlane_b32 s48, v247
	v_writelane_b32 v168, s40, 1
	v_writelane_b32 v168, s44, 2
	v_writelane_b32 v168, s48, 3
	v_mul_f32_e32 v169, 0x4f800000, v168
	v_cmp_gt_f32_e64 s[52:53], s68, v168
	v_mov_b32_e32 v170, v168
	s_nop 1
	v_cndmask_b32_e64 v168, v170, v169, s[52:53]
	v_sqrt_f32_e32 v169, v168
	s_nop 0
	v_add_u32_e32 v170, -1, v169
	v_fma_f32 v171, -v170, v169, v168
	v_cmp_ge_f32_e64 s[60:61], 0, v171
	v_add_u32_e32 v171, 1, v169
	s_nop 1
	v_cndmask_b32_e64 v170, v169, v170, s[60:61]
	v_fma_f32 v169, -v171, v169, v168
	v_cmp_lt_f32_e64 s[60:61], 0, v169
	s_nop 1
	v_cndmask_b32_e64 v169, v170, v171, s[60:61]
	v_mul_f32_e32 v170, 0x37800000, v169
	v_cndmask_b32_e64 v169, v169, v170, s[52:53]
	v_cmp_class_f32_e64 s[60:61], v168, v8
	s_nop 1
	v_cndmask_b32_e64 v168, v169, v168, s[60:61]
	v_div_scale_f32 v169, s[60:61], v168, v168, 1.0
	v_rcp_f32_e32 v170, v169
	s_nop 0
	v_fma_f32 v171, -v169, v170, 1.0
	v_fmac_f32_e32 v170, v171, v170
	v_div_scale_f32 v171, vcc, 1.0, v168, 1.0
	v_mul_f32_e32 v172, v171, v170
	v_fma_f32 v173, -v169, v172, v171
	v_fmac_f32_e32 v172, v173, v170
	v_fma_f32 v169, -v169, v172, v171
	v_div_fmas_f32 v169, v169, v170, v172
	v_div_fixup_f32 v168, v169, v168, 1.0
	s_nop 0
	v_readlane_b32 s37, v168, 0
	v_readlane_b32 s41, v168, 1
	v_readlane_b32 s45, v168, 2
	v_readlane_b32 s49, v168, 3
	v_mul_f32_e32 v80, s37, v80
	v_mul_f32_e32 v85, s41, v85
	v_mul_f32_e32 v90, s45, v90
	v_mul_f32_e32 v95, s49, v95
	v_lshlrev_b32_e32 v83, 16, v83
	v_lshlrev_b32_e32 v88, 16, v88
	v_lshlrev_b32_e32 v93, 16, v93
	v_lshlrev_b32_e32 v98, 16, v98
	v_fma_f32 v80, v6, v80, v7
	v_fma_f32 v85, v6, v85, v7
	v_fma_f32 v90, v6, v90, v7
	v_fma_f32 v95, v6, v95, v7
	v_fmac_f32_e32 v80, s69, v81
	v_fmac_f32_e32 v85, s70, v86
	v_fmac_f32_e32 v90, s71, v91
	v_fmac_f32_e32 v95, s72, v96
	v_mul_f32_e32 v80, v80, v83
	v_mul_f32_e32 v85, v85, v88
	v_mul_f32_e32 v90, v90, v93
	v_mul_f32_e32 v95, v95, v98
	v_cvt_pk_bf16_f32 v169, v80, v80
	v_cvt_pk_bf16_f32 v175, v85, v85
	v_cvt_pk_bf16_f32 v242, v90, v90
	v_cvt_pk_bf16_f32 v248, v95, v95
	global_store_short v2, v169, s[28:29]
	s_add_u32 s28, s28, 0x1000
	s_addc_u32 s29, s29, 0
	global_store_short v2, v175, s[28:29]
	s_add_u32 s28, s28, 0x1000
	s_addc_u32 s29, s29, 0
	global_store_short v2, v242, s[28:29]
	s_add_u32 s28, s28, 0x1000
	s_addc_u32 s29, s29, 0
	global_store_short v2, v248, s[28:29]
	s_add_u32 s28, s28, 0x1000
	s_addc_u32 s29, s29, 0
	v_add_f32_e32 v100, v100, v44
	v_add_f32_e32 v105, v105, v45
	v_add_f32_e32 v110, v110, v46
	v_add_f32_e32 v115, v115, v47
	v_add_f32_dpp v168, v100, v100 quad_perm:[1,0,3,2] row_mask:0xf bank_mask:0xf bound_ctrl:1
	v_add_f32_dpp v174, v105, v105 quad_perm:[1,0,3,2] row_mask:0xf bank_mask:0xf bound_ctrl:1
	v_add_f32_dpp v241, v110, v110 quad_perm:[1,0,3,2] row_mask:0xf bank_mask:0xf bound_ctrl:1
	v_add_f32_dpp v247, v115, v115 quad_perm:[1,0,3,2] row_mask:0xf bank_mask:0xf bound_ctrl:1
	v_add_f32_dpp v168, v168, v168 quad_perm:[2,3,0,1] row_mask:0xf bank_mask:0xf bound_ctrl:1
	v_add_f32_dpp v174, v174, v174 quad_perm:[2,3,0,1] row_mask:0xf bank_mask:0xf bound_ctrl:1
	v_add_f32_dpp v241, v241, v241 quad_perm:[2,3,0,1] row_mask:0xf bank_mask:0xf bound_ctrl:1
	v_add_f32_dpp v247, v247, v247 quad_perm:[2,3,0,1] row_mask:0xf bank_mask:0xf bound_ctrl:1
	v_add_f32_dpp v168, v168, v168 row_half_mirror row_mask:0xf bank_mask:0xf bound_ctrl:1
	v_add_f32_dpp v174, v174, v174 row_half_mirror row_mask:0xf bank_mask:0xf bound_ctrl:1
	v_add_f32_dpp v241, v241, v241 row_half_mirror row_mask:0xf bank_mask:0xf bound_ctrl:1
	v_add_f32_dpp v247, v247, v247 row_half_mirror row_mask:0xf bank_mask:0xf bound_ctrl:1
	v_add_f32_dpp v168, v168, v168 row_mirror row_mask:0xf bank_mask:0xf bound_ctrl:1
	v_add_f32_dpp v174, v174, v174 row_mirror row_mask:0xf bank_mask:0xf bound_ctrl:1
	v_add_f32_dpp v241, v241, v241 row_mirror row_mask:0xf bank_mask:0xf bound_ctrl:1
	v_add_f32_dpp v247, v247, v247 row_mirror row_mask:0xf bank_mask:0xf bound_ctrl:1
	v_readlane_b32 s36, v168, 16
	v_readlane_b32 s40, v174, 16
	v_readlane_b32 s44, v241, 16
	v_readlane_b32 s48, v247, 16
	v_readlane_b32 s37, v168, 48
	v_readlane_b32 s41, v174, 48
	v_readlane_b32 s45, v241, 48
	v_readlane_b32 s49, v247, 48
	v_readlane_b32 s38, v168, 0
	v_readlane_b32 s42, v174, 0
	v_readlane_b32 s46, v241, 0
	v_readlane_b32 s50, v247, 0
	v_readlane_b32 s39, v168, 32
	v_readlane_b32 s43, v174, 32
	v_readlane_b32 s47, v241, 32
	v_readlane_b32 s51, v247, 32
	v_mov_b32_e32 v168, s36
	v_mov_b32_e32 v174, s40
	v_mov_b32_e32 v241, s44
	v_mov_b32_e32 v247, s48
	v_mov_b32_e32 v169, s37
	v_mov_b32_e32 v175, s41
	v_mov_b32_e32 v242, s45
	v_mov_b32_e32 v248, s49
	v_add_f32_e32 v168, s38, v168
	v_add_f32_e32 v174, s42, v174
	v_add_f32_e32 v241, s46, v241
; __device__ __forceinline__ float bf2f(bf16 x) { return __uint_as_float(((unsigned)x) << 16); }
; __device__ __forceinline__ unsigned f2bf(float f) { return cvt_pk_bf16(f, 0.f) & 0xffffu; }
; #define POST_LD(Y_, V_, G_, R_, C_, t) do { _Pragma("unroll") for (int q = 0; q < 8; ++q) { const size_t o_ = (size_t)((t) + q) * DH; Y_[q] = yp[o_]; V_[q] = vp[o_]; G_[q] = gp[o_]; R_[q] = rp[((t) + q) * 32]; C_[q] = cp[o_]; } } while (0)
; __device__ __forceinline__ void rw_post(Frame& F) {
;     ...
;         POST_LD(y, vv, gg, rk, cc, 0);
;         for (int t0 = 0; t0 < 64; t0 += 8) {
;             float ny[8], nv[8], nr[8], nc[8]; bf16 ng[8];
;             const int tn = t0 + 8 < 64 ? t0 + 8 : t0;
;             POST_LD(ny, nv, ng, nr, nc, tn);
;     ...
;             for (int q = 0; q < 8; ++q) { const int row = rb0 + t0 + q;
;                 const float mean = wsum(y[q]) * (1.f / 64.f); const float dv = y[q] - mean; const float var = wsum(dv * dv) * (1.f / 64.f);
;                 const float yn = dv * (1.f / sqrtf(var + 64e-5f)) * g_ + b_;
;                 OB[(size_t)row * DH + col] = (bf16)f2bf((yn + rk[q] * vv[q]) * bf2f(gg[q])); }
; #pragma unroll
;             for (int q = 0; q < 8; ++q) { y[q] = ny[q]; vv[q] = nv[q]; gg[q] = ng[q]; rk[q] = nr[q]; cc[q] = nc[q]; }
	v_add_f32_e32 v247, s50, v247
	v_add_f32_e32 v169, s39, v169
	v_add_f32_e32 v175, s43, v175
	v_add_f32_e32 v242, s47, v242
	v_add_f32_e32 v248, s51, v248
	v_add_f32_e32 v168, v168, v169
	v_add_f32_e32 v174, v174, v175
	v_add_f32_e32 v241, v241, v242
	v_add_f32_e32 v247, v247, v248
	v_fmamk_f32 v100, v168, 0xbc800000, v100
	v_fmamk_f32 v105, v174, 0xbc800000, v105
	v_fmamk_f32 v110, v241, 0xbc800000, v110
	v_fmamk_f32 v115, v247, 0xbc800000, v115
	v_mul_f32_e32 v168, v100, v100
	v_mul_f32_e32 v174, v105, v105
	v_mul_f32_e32 v241, v110, v110
	v_mul_f32_e32 v247, v115, v115
	v_mov_b32_dpp v168, v168 quad_perm:[1,0,3,2] row_mask:0xf bank_mask:0xf bound_ctrl:1
	v_mov_b32_dpp v174, v174 quad_perm:[1,0,3,2] row_mask:0xf bank_mask:0xf bound_ctrl:1
	v_mov_b32_dpp v241, v241 quad_perm:[1,0,3,2] row_mask:0xf bank_mask:0xf bound_ctrl:1
	v_mov_b32_dpp v247, v247 quad_perm:[1,0,3,2] row_mask:0xf bank_mask:0xf bound_ctrl:1
	v_fmac_f32_e32 v168, v100, v100
	v_fmac_f32_e32 v174, v105, v105
	v_fmac_f32_e32 v241, v110, v110
	v_fmac_f32_e32 v247, v115, v115
	v_add_f32_dpp v168, v168, v168 quad_perm:[2,3,0,1] row_mask:0xf bank_mask:0xf bound_ctrl:1
	v_add_f32_dpp v174, v174, v174 quad_perm:[2,3,0,1] row_mask:0xf bank_mask:0xf bound_ctrl:1
	v_add_f32_dpp v241, v241, v241 quad_perm:[2,3,0,1] row_mask:0xf bank_mask:0xf bound_ctrl:1
	v_add_f32_dpp v247, v247, v247 quad_perm:[2,3,0,1] row_mask:0xf bank_mask:0xf bound_ctrl:1
	v_add_f32_dpp v168, v168, v168 row_half_mirror row_mask:0xf bank_mask:0xf bound_ctrl:1
	v_add_f32_dpp v174, v174, v174 row_half_mirror row_mask:0xf bank_mask:0xf bound_ctrl:1
	v_add_f32_dpp v241, v241, v241 row_half_mirror row_mask:0xf bank_mask:0xf bound_ctrl:1
	v_add_f32_dpp v247, v247, v247 row_half_mirror row_mask:0xf bank_mask:0xf bound_ctrl:1
	v_add_f32_dpp v168, v168, v168 row_mirror row_mask:0xf bank_mask:0xf bound_ctrl:1
	v_add_f32_dpp v174, v174, v174 row_mirror row_mask:0xf bank_mask:0xf bound_ctrl:1
	v_add_f32_dpp v241, v241, v241 row_mirror row_mask:0xf bank_mask:0xf bound_ctrl:1
	v_add_f32_dpp v247, v247, v247 row_mirror row_mask:0xf bank_mask:0xf bound_ctrl:1
	v_readlane_b32 s36, v168, 16
	v_readlane_b32 s40, v174, 16
	v_readlane_b32 s44, v241, 16
	v_readlane_b32 s48, v247, 16
	v_readlane_b32 s37, v168, 48
	v_readlane_b32 s41, v174, 48
	v_readlane_b32 s45, v241, 48
	v_readlane_b32 s49, v247, 48
	v_readlane_b32 s38, v168, 0
	v_readlane_b32 s42, v174, 0
	v_readlane_b32 s46, v241, 0
	v_readlane_b32 s50, v247, 0
	v_readlane_b32 s39, v168, 32
	v_readlane_b32 s43, v174, 32
	v_readlane_b32 s47, v241, 32
	v_readlane_b32 s51, v247, 32
	v_mov_b32_e32 v168, s36
	v_mov_b32_e32 v174, s40
	v_mov_b32_e32 v241, s44
	v_mov_b32_e32 v247, s48
	v_mov_b32_e32 v169, s37
	v_mov_b32_e32 v175, s41
	v_mov_b32_e32 v242, s45
	v_mov_b32_e32 v248, s49
	v_add_f32_e32 v168, s38, v168
	v_add_f32_e32 v174, s42, v174
	v_add_f32_e32 v241, s46, v241
	v_add_f32_e32 v247, s50, v247
	v_add_f32_e32 v169, s39, v169
	v_add_f32_e32 v175, s43, v175
	v_add_f32_e32 v242, s47, v242
	v_add_f32_e32 v248, s51, v248
	v_add_f32_e32 v168, v168, v169
	v_add_f32_e32 v174, v174, v175
	v_add_f32_e32 v241, v241, v242
	v_add_f32_e32 v247, v247, v248
	v_fmamk_f32 v168, v168, 0x3c800000, v9
	v_fmamk_f32 v174, v174, 0x3c800000, v9
	v_fmamk_f32 v241, v241, 0x3c800000, v9
	v_fmamk_f32 v247, v247, 0x3c800000, v9
	v_readfirstlane_b32 s40, v174
	v_readfirstlane_b32 s44, v241
	v_readfirstlane_b32 s48, v247
	v_writelane_b32 v168, s40, 1
	v_writelane_b32 v168, s44, 2
	v_writelane_b32 v168, s48, 3
	v_mul_f32_e32 v169, 0x4f800000, v168
	v_cmp_gt_f32_e64 s[52:53], s68, v168
	v_mov_b32_e32 v170, v168
	s_nop 1
	v_cndmask_b32_e64 v168, v170, v169, s[52:53]
	v_sqrt_f32_e32 v169, v168
	s_nop 0
	v_add_u32_e32 v170, -1, v169
	v_fma_f32 v171, -v170, v169, v168
	v_cmp_ge_f32_e64 s[60:61], 0, v171
	v_add_u32_e32 v171, 1, v169
	s_nop 1
	v_cndmask_b32_e64 v170, v169, v170, s[60:61]
	v_fma_f32 v169, -v171, v169, v168
	v_cmp_lt_f32_e64 s[60:61], 0, v169
	s_nop 1
	v_cndmask_b32_e64 v169, v170, v171, s[60:61]
	v_mul_f32_e32 v170, 0x37800000, v169
	v_cndmask_b32_e64 v169, v169, v170, s[52:53]
	v_cmp_class_f32_e64 s[60:61], v168, v8
	s_nop 1
	v_cndmask_b32_e64 v168, v169, v168, s[60:61]
	v_div_scale_f32 v169, s[60:61], v168, v168, 1.0
	v_rcp_f32_e32 v170, v169
	s_nop 0
	v_fma_f32 v171, -v169, v170, 1.0
	v_fmac_f32_e32 v170, v171, v170
	v_div_scale_f32 v171, vcc, 1.0, v168, 1.0
	v_mul_f32_e32 v172, v171, v170
	v_fma_f32 v173, -v169, v172, v171
	v_fmac_f32_e32 v172, v173, v170
	v_fma_f32 v169, -v169, v172, v171
	v_div_fmas_f32 v169, v169, v170, v172
	v_div_fixup_f32 v168, v169, v168, 1.0
	s_nop 0
	v_readlane_b32 s37, v168, 0
	v_readlane_b32 s41, v168, 1
	v_readlane_b32 s45, v168, 2
	v_readlane_b32 s49, v168, 3
	v_mul_f32_e32 v100, s37, v100
	v_mul_f32_e32 v105, s41, v105
	v_mul_f32_e32 v110, s45, v110
	v_mul_f32_e32 v115, s49, v115
	v_lshlrev_b32_e32 v103, 16, v103
	v_lshlrev_b32_e32 v108, 16, v108
	v_lshlrev_b32_e32 v113, 16, v113
	v_lshlrev_b32_e32 v118, 16, v118
	v_fma_f32 v100, v6, v100, v7
	v_fma_f32 v105, v6, v105, v7
	v_fma_f32 v110, v6, v110, v7
	v_fma_f32 v115, v6, v115, v7
	v_fmac_f32_e32 v100, s73, v101
	v_fmac_f32_e32 v105, s26, v106
	v_fmac_f32_e32 v110, s27, v111
	v_fmac_f32_e32 v115, s32, v116
	v_mul_f32_e32 v100, v100, v103
	v_mul_f32_e32 v105, v105, v108
	v_mul_f32_e32 v110, v110, v113
	v_mul_f32_e32 v115, v115, v118
	v_cvt_pk_bf16_f32 v169, v100, v100
	v_cvt_pk_bf16_f32 v175, v105, v105
	v_cvt_pk_bf16_f32 v242, v110, v110
	v_cvt_pk_bf16_f32 v248, v115, v115
	global_store_short v2, v169, s[28:29]
	s_add_u32 s28, s28, 0x1000
	s_addc_u32 s29, s29, 0
	global_store_short v2, v175, s[28:29]
	s_add_u32 s28, s28, 0x1000
	s_addc_u32 s29, s29, 0
	global_store_short v2, v242, s[28:29]
	s_add_u32 s28, s28, 0x1000
	s_addc_u32 s29, s29, 0
	global_store_short v2, v248, s[28:29]
	s_add_u32 s28, s28, 0x1000
	s_addc_u32 s29, s29, 0
	s_waitcnt vmcnt(8)
	ds_write_b128 v12, v[120:123] offset:0
	ds_write_b128 v12, v[124:127] offset:1024
	ds_write_b128 v12, v[128:131] offset:16384
	ds_write_b128 v12, v[132:135] offset:17408
	ds_write_b128 v14, v[136:139]
	v_readlane_b32 s69, v159, 0
	v_readlane_b32 s70, v159, 1
	v_readlane_b32 s71, v159, 2
	v_readlane_b32 s72, v159, 3
	v_readlane_b32 s73, v159, 4
	v_readlane_b32 s26, v159, 5
	v_readlane_b32 s27, v159, 6
	v_readlane_b32 s32, v159, 7
	global_load_dwordx4 v[120:123], v11, s[6:7]
	global_load_dwordx4 v[124:127], v11, s[6:7] offset:1024
	global_load_dwordx4 v[128:131], v11, s[8:9]
	global_load_dwordx4 v[132:135], v11, s[8:9] offset:1024
	global_load_dwordx4 v[136:139], v11, s[10:11]
	global_load_dword v159, v158, s[12:13]
	s_add_u32 s6, s6, 0x10000
	s_addc_u32 s7, s7, 0
	s_add_u32 s8, s8, 0x10000
	s_addc_u32 s9, s9, 0
	s_add_u32 s10, s10, 0x8000
	s_addc_u32 s11, s11, 0
	s_add_u32 s12, s12, 0x400
	s_addc_u32 s13, s13, 0
	s_waitcnt lgkmcnt(0)
	s_barrier
; #define POST_LD(Y_, V_, G_, R_, C_, t) do { _Pragma("unroll") for (int q = 0; q < 8; ++q) { const size_t o_ = (size_t)((t) + q) * DH; Y_[q] = yp[o_]; V_[q] = vp[o_]; G_[q] = gp[o_]; R_[q] = rp[((t) + q) * 32]; C_[q] = cp[o_]; } } while (0)
; __device__ __forceinline__ void rw_post(Frame& F) {
;     ...
;         POST_LD(y, vv, gg, rk, cc, 0);
;     ...
;             for (int q = 0; q < 8; ++q) { const int row = rb0 + t0 + q;
;                 const float mean = wsum(y[q]) * (1.f / 64.f); const float dv = y[q] - mean; const float var = wsum(dv * dv) * (1.f / 64.f);
;                 const float yn = dv * (1.f / sqrtf(var + 64e-5f)) * g_ + b_;
	ds_read_b32 v80, v154 offset:0
	ds_read_b32 v81, v154 offset:16384
	ds_read_u16 v83, v156 offset:0
	ds_read_b32 v85, v154 offset:2048
	ds_read_b32 v86, v154 offset:18432
	ds_read_u16 v88, v156 offset:1024
	ds_read_b32 v90, v154 offset:4096
	ds_read_b32 v91, v154 offset:20480
	ds_read_u16 v93, v156 offset:2048
	ds_read_b32 v95, v154 offset:6144
	ds_read_b32 v96, v154 offset:22528
	ds_read_u16 v98, v156 offset:3072
	ds_read_b32 v100, v154 offset:8192
	ds_read_b32 v101, v154 offset:24576
	ds_read_u16 v103, v156 offset:4096
	ds_read_b32 v105, v154 offset:10240
	ds_read_b32 v106, v154 offset:26624
	ds_read_u16 v108, v156 offset:5120
	ds_read_b32 v110, v154 offset:12288
	ds_read_b32 v111, v154 offset:28672
	ds_read_u16 v113, v156 offset:6144
	ds_read_b32 v115, v154 offset:14336
	ds_read_b32 v116, v154 offset:30720
	ds_read_u16 v118, v156 offset:7168
	s_waitcnt lgkmcnt(0)
	v_add_f32_e32 v80, v80, v48
	v_add_f32_e32 v85, v85, v49
	v_add_f32_e32 v90, v90, v50
	v_add_f32_e32 v95, v95, v51
	v_add_f32_dpp v168, v80, v80 quad_perm:[1,0,3,2] row_mask:0xf bank_mask:0xf bound_ctrl:1
	v_add_f32_dpp v174, v85, v85 quad_perm:[1,0,3,2] row_mask:0xf bank_mask:0xf bound_ctrl:1
	v_add_f32_dpp v241, v90, v90 quad_perm:[1,0,3,2] row_mask:0xf bank_mask:0xf bound_ctrl:1
	v_add_f32_dpp v247, v95, v95 quad_perm:[1,0,3,2] row_mask:0xf bank_mask:0xf bound_ctrl:1
	v_add_f32_dpp v168, v168, v168 quad_perm:[2,3,0,1] row_mask:0xf bank_mask:0xf bound_ctrl:1
	v_add_f32_dpp v174, v174, v174 quad_perm:[2,3,0,1] row_mask:0xf bank_mask:0xf bound_ctrl:1
	v_add_f32_dpp v241, v241, v241 quad_perm:[2,3,0,1] row_mask:0xf bank_mask:0xf bound_ctrl:1
	v_add_f32_dpp v247, v247, v247 quad_perm:[2,3,0,1] row_mask:0xf bank_mask:0xf bound_ctrl:1
	v_add_f32_dpp v168, v168, v168 row_half_mirror row_mask:0xf bank_mask:0xf bound_ctrl:1
	v_add_f32_dpp v174, v174, v174 row_half_mirror row_mask:0xf bank_mask:0xf bound_ctrl:1
	v_add_f32_dpp v241, v241, v241 row_half_mirror row_mask:0xf bank_mask:0xf bound_ctrl:1
	v_add_f32_dpp v247, v247, v247 row_half_mirror row_mask:0xf bank_mask:0xf bound_ctrl:1
	v_add_f32_dpp v168, v168, v168 row_mirror row_mask:0xf bank_mask:0xf bound_ctrl:1
	v_add_f32_dpp v174, v174, v174 row_mirror row_mask:0xf bank_mask:0xf bound_ctrl:1
	v_add_f32_dpp v241, v241, v241 row_mirror row_mask:0xf bank_mask:0xf bound_ctrl:1
	v_add_f32_dpp v247, v247, v247 row_mirror row_mask:0xf bank_mask:0xf bound_ctrl:1
	v_readlane_b32 s36, v168, 16
	v_readlane_b32 s40, v174, 16
	v_readlane_b32 s44, v241, 16
	v_readlane_b32 s48, v247, 16
	v_readlane_b32 s37, v168, 48
	v_readlane_b32 s41, v174, 48
	v_readlane_b32 s45, v241, 48
	v_readlane_b32 s49, v247, 48
	v_readlane_b32 s38, v168, 0
	v_readlane_b32 s42, v174, 0
	v_readlane_b32 s46, v241, 0
	v_readlane_b32 s50, v247, 0
	v_readlane_b32 s39, v168, 32
	v_readlane_b32 s43, v174, 32
	v_readlane_b32 s47, v241, 32
	v_readlane_b32 s51, v247, 32
	v_mov_b32_e32 v168, s36
	v_mov_b32_e32 v174, s40
	v_mov_b32_e32 v241, s44
	v_mov_b32_e32 v247, s48
	v_mov_b32_e32 v169, s37
	v_mov_b32_e32 v175, s41
	v_mov_b32_e32 v242, s45
	v_mov_b32_e32 v248, s49
	v_add_f32_e32 v168, s38, v168
	v_add_f32_e32 v174, s42, v174
	v_add_f32_e32 v241, s46, v241
	v_add_f32_e32 v247, s50, v247
	v_add_f32_e32 v169, s39, v169
	v_add_f32_e32 v175, s43, v175
	v_add_f32_e32 v242, s47, v242
	v_add_f32_e32 v248, s51, v248
	v_add_f32_e32 v168, v168, v169
	v_add_f32_e32 v174, v174, v175
	v_add_f32_e32 v241, v241, v242
	v_add_f32_e32 v247, v247, v248
	v_fmamk_f32 v80, v168, 0xbc800000, v80
	v_fmamk_f32 v85, v174, 0xbc800000, v85
	v_fmamk_f32 v90, v241, 0xbc800000, v90
	v_fmamk_f32 v95, v247, 0xbc800000, v95
	v_mul_f32_e32 v168, v80, v80
	v_mul_f32_e32 v174, v85, v85
	v_mul_f32_e32 v241, v90, v90
	v_mul_f32_e32 v247, v95, v95
	v_mov_b32_dpp v168, v168 quad_perm:[1,0,3,2] row_mask:0xf bank_mask:0xf bound_ctrl:1
	v_mov_b32_dpp v174, v174 quad_perm:[1,0,3,2] row_mask:0xf bank_mask:0xf bound_ctrl:1
	v_mov_b32_dpp v241, v241 quad_perm:[1,0,3,2] row_mask:0xf bank_mask:0xf bound_ctrl:1
	v_mov_b32_dpp v247, v247 quad_perm:[1,0,3,2] row_mask:0xf bank_mask:0xf bound_ctrl:1
	v_fmac_f32_e32 v168, v80, v80
	v_fmac_f32_e32 v174, v85, v85
	v_fmac_f32_e32 v241, v90, v90
	v_fmac_f32_e32 v247, v95, v95
	v_add_f32_dpp v168, v168, v168 quad_perm:[2,3,0,1] row_mask:0xf bank_mask:0xf bound_ctrl:1
	v_add_f32_dpp v174, v174, v174 quad_perm:[2,3,0,1] row_mask:0xf bank_mask:0xf bound_ctrl:1
	v_add_f32_dpp v241, v241, v241 quad_perm:[2,3,0,1] row_mask:0xf bank_mask:0xf bound_ctrl:1
	v_add_f32_dpp v247, v247, v247 quad_perm:[2,3,0,1] row_mask:0xf bank_mask:0xf bound_ctrl:1
	v_add_f32_dpp v168, v168, v168 row_half_mirror row_mask:0xf bank_mask:0xf bound_ctrl:1
	v_add_f32_dpp v174, v174, v174 row_half_mirror row_mask:0xf bank_mask:0xf bound_ctrl:1
	v_add_f32_dpp v241, v241, v241 row_half_mirror row_mask:0xf bank_mask:0xf bound_ctrl:1
	v_add_f32_dpp v247, v247, v247 row_half_mirror row_mask:0xf bank_mask:0xf bound_ctrl:1
	v_add_f32_dpp v168, v168, v168 row_mirror row_mask:0xf bank_mask:0xf bound_ctrl:1
	v_add_f32_dpp v174, v174, v174 row_mirror row_mask:0xf bank_mask:0xf bound_ctrl:1
	v_add_f32_dpp v241, v241, v241 row_mirror row_mask:0xf bank_mask:0xf bound_ctrl:1
	v_add_f32_dpp v247, v247, v247 row_mirror row_mask:0xf bank_mask:0xf bound_ctrl:1
	v_readlane_b32 s36, v168, 16
	v_readlane_b32 s40, v174, 16
	v_readlane_b32 s44, v241, 16
	v_readlane_b32 s48, v247, 16
	v_readlane_b32 s37, v168, 48
	v_readlane_b32 s41, v174, 48
	v_readlane_b32 s45, v241, 48
	v_readlane_b32 s49, v247, 48
	v_readlane_b32 s38, v168, 0
	v_readlane_b32 s42, v174, 0
	v_readlane_b32 s46, v241, 0
	v_readlane_b32 s50, v247, 0
	v_readlane_b32 s39, v168, 32
; __device__ __forceinline__ float bf2f(bf16 x) { return __uint_as_float(((unsigned)x) << 16); }
; __device__ __forceinline__ unsigned f2bf(float f) { return cvt_pk_bf16(f, 0.f) & 0xffffu; }
; __device__ __forceinline__ float dpp_xor1(float x) { return __builtin_bit_cast(float, __builtin_amdgcn_update_dpp(0, __builtin_bit_cast(int, x), 0xB1, 0xF, 0xF, true)); }
; __device__ __forceinline__ float dpp_xor2(float x) { return __builtin_bit_cast(float, __builtin_amdgcn_update_dpp(0, __builtin_bit_cast(int, x), 0x4E, 0xF, 0xF, true)); }
; __device__ __forceinline__ float dpp_hmir(float x) { return __builtin_bit_cast(float, __builtin_amdgcn_update_dpp(0, __builtin_bit_cast(int, x), 0x141, 0xF, 0xF, true)); }
; __device__ __forceinline__ float dpp_mir(float x)  { return __builtin_bit_cast(float, __builtin_amdgcn_update_dpp(0, __builtin_bit_cast(int, x), 0x140, 0xF, 0xF, true)); }
; __device__ __forceinline__ float red16(float x) { x += dpp_xor1(x); x += dpp_xor2(x); x += dpp_hmir(x); x += dpp_mir(x); return x; }
; __device__ __forceinline__ float wsum(float x) {
;     x = red16(x); const int xi = __builtin_bit_cast(int, x);
;     const float r0 = __builtin_bit_cast(float, __builtin_amdgcn_readlane(xi, 0)), r1 = __builtin_bit_cast(float, __builtin_amdgcn_readlane(xi, 16));
;     const float r2 = __builtin_bit_cast(float, __builtin_amdgcn_readlane(xi, 32)), r3 = __builtin_bit_cast(float, __builtin_amdgcn_readlane(xi, 48));
;     return (r0 + r1) + (r2 + r3);
; }
; __device__ __forceinline__ void rw_post(Frame& F) {
;     ...
;             for (int q = 0; q < 8; ++q) { const int row = rb0 + t0 + q;
;                 const float mean = wsum(y[q]) * (1.f / 64.f); const float dv = y[q] - mean; const float var = wsum(dv * dv) * (1.f / 64.f);
;                 const float yn = dv * (1.f / sqrtf(var + 64e-5f)) * g_ + b_;
;                 OB[(size_t)row * DH + col] = (bf16)f2bf((yn + rk[q] * vv[q]) * bf2f(gg[q])); }
	v_readlane_b32 s43, v174, 32
	v_readlane_b32 s47, v241, 32
	v_readlane_b32 s51, v247, 32
	v_mov_b32_e32 v168, s36
	v_mov_b32_e32 v174, s40
	v_mov_b32_e32 v241, s44
	v_mov_b32_e32 v247, s48
	v_mov_b32_e32 v169, s37
	v_mov_b32_e32 v175, s41
	v_mov_b32_e32 v242, s45
	v_mov_b32_e32 v248, s49
	v_add_f32_e32 v168, s38, v168
	v_add_f32_e32 v174, s42, v174
	v_add_f32_e32 v241, s46, v241
	v_add_f32_e32 v247, s50, v247
	v_add_f32_e32 v169, s39, v169
	v_add_f32_e32 v175, s43, v175
	v_add_f32_e32 v242, s47, v242
	v_add_f32_e32 v248, s51, v248
	v_add_f32_e32 v168, v168, v169
	v_add_f32_e32 v174, v174, v175
	v_add_f32_e32 v241, v241, v242
	v_add_f32_e32 v247, v247, v248
	v_fmamk_f32 v168, v168, 0x3c800000, v9
	v_fmamk_f32 v174, v174, 0x3c800000, v9
	v_fmamk_f32 v241, v241, 0x3c800000, v9
	v_fmamk_f32 v247, v247, 0x3c800000, v9
	v_readfirstlane_b32 s40, v174
	v_readfirstlane_b32 s44, v241
	v_readfirstlane_b32 s48, v247
	v_writelane_b32 v168, s40, 1
	v_writelane_b32 v168, s44, 2
	v_writelane_b32 v168, s48, 3
	v_mul_f32_e32 v169, 0x4f800000, v168
	v_cmp_gt_f32_e64 s[52:53], s68, v168
	v_mov_b32_e32 v170, v168
	s_nop 1
	v_cndmask_b32_e64 v168, v170, v169, s[52:53]
	v_sqrt_f32_e32 v169, v168
	s_nop 0
	v_add_u32_e32 v170, -1, v169
	v_fma_f32 v171, -v170, v169, v168
	v_cmp_ge_f32_e64 s[60:61], 0, v171
	v_add_u32_e32 v171, 1, v169
	s_nop 1
	v_cndmask_b32_e64 v170, v169, v170, s[60:61]
	v_fma_f32 v169, -v171, v169, v168
	v_cmp_lt_f32_e64 s[60:61], 0, v169
	s_nop 1
	v_cndmask_b32_e64 v169, v170, v171, s[60:61]
	v_mul_f32_e32 v170, 0x37800000, v169
	v_cndmask_b32_e64 v169, v169, v170, s[52:53]
	v_cmp_class_f32_e64 s[60:61], v168, v8
	s_nop 1
	v_cndmask_b32_e64 v168, v169, v168, s[60:61]
	v_div_scale_f32 v169, s[60:61], v168, v168, 1.0
	v_rcp_f32_e32 v170, v169
	s_nop 0
	v_fma_f32 v171, -v169, v170, 1.0
	v_fmac_f32_e32 v170, v171, v170
	v_div_scale_f32 v171, vcc, 1.0, v168, 1.0
	v_mul_f32_e32 v172, v171, v170
	v_fma_f32 v173, -v169, v172, v171
	v_fmac_f32_e32 v172, v173, v170
	v_fma_f32 v169, -v169, v172, v171
	v_div_fmas_f32 v169, v169, v170, v172
	v_div_fixup_f32 v168, v169, v168, 1.0
	s_nop 0
	v_readlane_b32 s37, v168, 0
	v_readlane_b32 s41, v168, 1
	v_readlane_b32 s45, v168, 2
	v_readlane_b32 s49, v168, 3
	v_mul_f32_e32 v80, s37, v80
	v_mul_f32_e32 v85, s41, v85
	v_mul_f32_e32 v90, s45, v90
	v_mul_f32_e32 v95, s49, v95
	v_lshlrev_b32_e32 v83, 16, v83
	v_lshlrev_b32_e32 v88, 16, v88
	v_lshlrev_b32_e32 v93, 16, v93
	v_lshlrev_b32_e32 v98, 16, v98
	v_fma_f32 v80, v6, v80, v7
	v_fma_f32 v85, v6, v85, v7
	v_fma_f32 v90, v6, v90, v7
	v_fma_f32 v95, v6, v95, v7
	v_fmac_f32_e32 v80, s69, v81
	v_fmac_f32_e32 v85, s70, v86
	v_fmac_f32_e32 v90, s71, v91
	v_fmac_f32_e32 v95, s72, v96
	v_mul_f32_e32 v80, v80, v83
	v_mul_f32_e32 v85, v85, v88
	v_mul_f32_e32 v90, v90, v93
	v_mul_f32_e32 v95, v95, v98
	v_cvt_pk_bf16_f32 v169, v80, v80
	v_cvt_pk_bf16_f32 v175, v85, v85
	v_cvt_pk_bf16_f32 v242, v90, v90
	v_cvt_pk_bf16_f32 v248, v95, v95
	global_store_short v2, v169, s[28:29]
	s_add_u32 s28, s28, 0x1000
	s_addc_u32 s29, s29, 0
	global_store_short v2, v175, s[28:29]
	s_add_u32 s28, s28, 0x1000
	s_addc_u32 s29, s29, 0
	global_store_short v2, v242, s[28:29]
	s_add_u32 s28, s28, 0x1000
	s_addc_u32 s29, s29, 0
	global_store_short v2, v248, s[28:29]
	s_add_u32 s28, s28, 0x1000
	s_addc_u32 s29, s29, 0
	v_add_f32_e32 v100, v100, v64
	v_add_f32_e32 v105, v105, v65
	v_add_f32_e32 v110, v110, v66
	v_add_f32_e32 v115, v115, v67
	v_add_f32_dpp v168, v100, v100 quad_perm:[1,0,3,2] row_mask:0xf bank_mask:0xf bound_ctrl:1
	v_add_f32_dpp v174, v105, v105 quad_perm:[1,0,3,2] row_mask:0xf bank_mask:0xf bound_ctrl:1
	v_add_f32_dpp v241, v110, v110 quad_perm:[1,0,3,2] row_mask:0xf bank_mask:0xf bound_ctrl:1
	v_add_f32_dpp v247, v115, v115 quad_perm:[1,0,3,2] row_mask:0xf bank_mask:0xf bound_ctrl:1
	v_add_f32_dpp v168, v168, v168 quad_perm:[2,3,0,1] row_mask:0xf bank_mask:0xf bound_ctrl:1
	v_add_f32_dpp v174, v174, v174 quad_perm:[2,3,0,1] row_mask:0xf bank_mask:0xf bound_ctrl:1
	v_add_f32_dpp v241, v241, v241 quad_perm:[2,3,0,1] row_mask:0xf bank_mask:0xf bound_ctrl:1
	v_add_f32_dpp v247, v247, v247 quad_perm:[2,3,0,1] row_mask:0xf bank_mask:0xf bound_ctrl:1
	v_add_f32_dpp v168, v168, v168 row_half_mirror row_mask:0xf bank_mask:0xf bound_ctrl:1
	v_add_f32_dpp v174, v174, v174 row_half_mirror row_mask:0xf bank_mask:0xf bound_ctrl:1
	v_add_f32_dpp v241, v241, v241 row_half_mirror row_mask:0xf bank_mask:0xf bound_ctrl:1
	v_add_f32_dpp v247, v247, v247 row_half_mirror row_mask:0xf bank_mask:0xf bound_ctrl:1
	v_add_f32_dpp v168, v168, v168 row_mirror row_mask:0xf bank_mask:0xf bound_ctrl:1
	v_add_f32_dpp v174, v174, v174 row_mirror row_mask:0xf bank_mask:0xf bound_ctrl:1
	v_add_f32_dpp v241, v241, v241 row_mirror row_mask:0xf bank_mask:0xf bound_ctrl:1
	v_add_f32_dpp v247, v247, v247 row_mirror row_mask:0xf bank_mask:0xf bound_ctrl:1
	v_readlane_b32 s36, v168, 16
	v_readlane_b32 s40, v174, 16
	v_readlane_b32 s44, v241, 16
	v_readlane_b32 s48, v247, 16
	v_readlane_b32 s37, v168, 48
	v_readlane_b32 s41, v174, 48
	v_readlane_b32 s45, v241, 48
	v_readlane_b32 s49, v247, 48
	v_readlane_b32 s38, v168, 0
	v_readlane_b32 s42, v174, 0
	v_readlane_b32 s46, v241, 0
	v_readlane_b32 s50, v247, 0
	v_readlane_b32 s39, v168, 32
	v_readlane_b32 s43, v174, 32
	v_readlane_b32 s47, v241, 32
	v_readlane_b32 s51, v247, 32
	v_mov_b32_e32 v168, s36
	v_mov_b32_e32 v174, s40
	v_mov_b32_e32 v241, s44
	v_mov_b32_e32 v247, s48
	v_mov_b32_e32 v169, s37
	v_mov_b32_e32 v175, s41
	v_mov_b32_e32 v242, s45
	v_mov_b32_e32 v248, s49
	v_add_f32_e32 v168, s38, v168
	v_add_f32_e32 v174, s42, v174
	v_add_f32_e32 v241, s46, v241
; __device__ __forceinline__ float bf2f(bf16 x) { return __uint_as_float(((unsigned)x) << 16); }
; __device__ __forceinline__ unsigned f2bf(float f) { return cvt_pk_bf16(f, 0.f) & 0xffffu; }
; #define POST_LD(Y_, V_, G_, R_, C_, t) do { _Pragma("unroll") for (int q = 0; q < 8; ++q) { const size_t o_ = (size_t)((t) + q) * DH; Y_[q] = yp[o_]; V_[q] = vp[o_]; G_[q] = gp[o_]; R_[q] = rp[((t) + q) * 32]; C_[q] = cp[o_]; } } while (0)
; __device__ __forceinline__ void rw_post(Frame& F) {
;     ...
;         POST_LD(y, vv, gg, rk, cc, 0);
;         for (int t0 = 0; t0 < 64; t0 += 8) {
;             float ny[8], nv[8], nr[8], nc[8]; bf16 ng[8];
;             const int tn = t0 + 8 < 64 ? t0 + 8 : t0;
;             POST_LD(ny, nv, ng, nr, nc, tn);
;     ...
;             for (int q = 0; q < 8; ++q) { const int row = rb0 + t0 + q;
;                 const float mean = wsum(y[q]) * (1.f / 64.f); const float dv = y[q] - mean; const float var = wsum(dv * dv) * (1.f / 64.f);
;                 const float yn = dv * (1.f / sqrtf(var + 64e-5f)) * g_ + b_;
;                 OB[(size_t)row * DH + col] = (bf16)f2bf((yn + rk[q] * vv[q]) * bf2f(gg[q])); }
; #pragma unroll
;             for (int q = 0; q < 8; ++q) { y[q] = ny[q]; vv[q] = nv[q]; gg[q] = ng[q]; rk[q] = nr[q]; cc[q] = nc[q]; }
	v_add_f32_e32 v247, s50, v247
	v_add_f32_e32 v169, s39, v169
	v_add_f32_e32 v175, s43, v175
	v_add_f32_e32 v242, s47, v242
	v_add_f32_e32 v248, s51, v248
	v_add_f32_e32 v168, v168, v169
	v_add_f32_e32 v174, v174, v175
	v_add_f32_e32 v241, v241, v242
	v_add_f32_e32 v247, v247, v248
	v_fmamk_f32 v100, v168, 0xbc800000, v100
	v_fmamk_f32 v105, v174, 0xbc800000, v105
	v_fmamk_f32 v110, v241, 0xbc800000, v110
	v_fmamk_f32 v115, v247, 0xbc800000, v115
	v_mul_f32_e32 v168, v100, v100
	v_mul_f32_e32 v174, v105, v105
	v_mul_f32_e32 v241, v110, v110
	v_mul_f32_e32 v247, v115, v115
	v_mov_b32_dpp v168, v168 quad_perm:[1,0,3,2] row_mask:0xf bank_mask:0xf bound_ctrl:1
	v_mov_b32_dpp v174, v174 quad_perm:[1,0,3,2] row_mask:0xf bank_mask:0xf bound_ctrl:1
	v_mov_b32_dpp v241, v241 quad_perm:[1,0,3,2] row_mask:0xf bank_mask:0xf bound_ctrl:1
	v_mov_b32_dpp v247, v247 quad_perm:[1,0,3,2] row_mask:0xf bank_mask:0xf bound_ctrl:1
	v_fmac_f32_e32 v168, v100, v100
	v_fmac_f32_e32 v174, v105, v105
	v_fmac_f32_e32 v241, v110, v110
	v_fmac_f32_e32 v247, v115, v115
	v_add_f32_dpp v168, v168, v168 quad_perm:[2,3,0,1] row_mask:0xf bank_mask:0xf bound_ctrl:1
	v_add_f32_dpp v174, v174, v174 quad_perm:[2,3,0,1] row_mask:0xf bank_mask:0xf bound_ctrl:1
	v_add_f32_dpp v241, v241, v241 quad_perm:[2,3,0,1] row_mask:0xf bank_mask:0xf bound_ctrl:1
	v_add_f32_dpp v247, v247, v247 quad_perm:[2,3,0,1] row_mask:0xf bank_mask:0xf bound_ctrl:1
	v_add_f32_dpp v168, v168, v168 row_half_mirror row_mask:0xf bank_mask:0xf bound_ctrl:1
	v_add_f32_dpp v174, v174, v174 row_half_mirror row_mask:0xf bank_mask:0xf bound_ctrl:1
	v_add_f32_dpp v241, v241, v241 row_half_mirror row_mask:0xf bank_mask:0xf bound_ctrl:1
	v_add_f32_dpp v247, v247, v247 row_half_mirror row_mask:0xf bank_mask:0xf bound_ctrl:1
	v_add_f32_dpp v168, v168, v168 row_mirror row_mask:0xf bank_mask:0xf bound_ctrl:1
	v_add_f32_dpp v174, v174, v174 row_mirror row_mask:0xf bank_mask:0xf bound_ctrl:1
	v_add_f32_dpp v241, v241, v241 row_mirror row_mask:0xf bank_mask:0xf bound_ctrl:1
	v_add_f32_dpp v247, v247, v247 row_mirror row_mask:0xf bank_mask:0xf bound_ctrl:1
	v_readlane_b32 s36, v168, 16
	v_readlane_b32 s40, v174, 16
	v_readlane_b32 s44, v241, 16
	v_readlane_b32 s48, v247, 16
	v_readlane_b32 s37, v168, 48
	v_readlane_b32 s41, v174, 48
	v_readlane_b32 s45, v241, 48
	v_readlane_b32 s49, v247, 48
	v_readlane_b32 s38, v168, 0
	v_readlane_b32 s42, v174, 0
	v_readlane_b32 s46, v241, 0
	v_readlane_b32 s50, v247, 0
	v_readlane_b32 s39, v168, 32
	v_readlane_b32 s43, v174, 32
	v_readlane_b32 s47, v241, 32
	v_readlane_b32 s51, v247, 32
	v_mov_b32_e32 v168, s36
	v_mov_b32_e32 v174, s40
	v_mov_b32_e32 v241, s44
	v_mov_b32_e32 v247, s48
	v_mov_b32_e32 v169, s37
	v_mov_b32_e32 v175, s41
	v_mov_b32_e32 v242, s45
	v_mov_b32_e32 v248, s49
	v_add_f32_e32 v168, s38, v168
	v_add_f32_e32 v174, s42, v174
	v_add_f32_e32 v241, s46, v241
	v_add_f32_e32 v247, s50, v247
	v_add_f32_e32 v169, s39, v169
	v_add_f32_e32 v175, s43, v175
	v_add_f32_e32 v242, s47, v242
	v_add_f32_e32 v248, s51, v248
	v_add_f32_e32 v168, v168, v169
	v_add_f32_e32 v174, v174, v175
	v_add_f32_e32 v241, v241, v242
	v_add_f32_e32 v247, v247, v248
	v_fmamk_f32 v168, v168, 0x3c800000, v9
	v_fmamk_f32 v174, v174, 0x3c800000, v9
	v_fmamk_f32 v241, v241, 0x3c800000, v9
	v_fmamk_f32 v247, v247, 0x3c800000, v9
	v_readfirstlane_b32 s40, v174
	v_readfirstlane_b32 s44, v241
	v_readfirstlane_b32 s48, v247
	v_writelane_b32 v168, s40, 1
	v_writelane_b32 v168, s44, 2
	v_writelane_b32 v168, s48, 3
	v_mul_f32_e32 v169, 0x4f800000, v168
	v_cmp_gt_f32_e64 s[52:53], s68, v168
	v_mov_b32_e32 v170, v168
	s_nop 1
	v_cndmask_b32_e64 v168, v170, v169, s[52:53]
	v_sqrt_f32_e32 v169, v168
	s_nop 0
	v_add_u32_e32 v170, -1, v169
	v_fma_f32 v171, -v170, v169, v168
	v_cmp_ge_f32_e64 s[60:61], 0, v171
	v_add_u32_e32 v171, 1, v169
	s_nop 1
	v_cndmask_b32_e64 v170, v169, v170, s[60:61]
	v_fma_f32 v169, -v171, v169, v168
	v_cmp_lt_f32_e64 s[60:61], 0, v169
	s_nop 1
	v_cndmask_b32_e64 v169, v170, v171, s[60:61]
	v_mul_f32_e32 v170, 0x37800000, v169
	v_cndmask_b32_e64 v169, v169, v170, s[52:53]
	v_cmp_class_f32_e64 s[60:61], v168, v8
	s_nop 1
	v_cndmask_b32_e64 v168, v169, v168, s[60:61]
	v_div_scale_f32 v169, s[60:61], v168, v168, 1.0
	v_rcp_f32_e32 v170, v169
	s_nop 0
	v_fma_f32 v171, -v169, v170, 1.0
	v_fmac_f32_e32 v170, v171, v170
	v_div_scale_f32 v171, vcc, 1.0, v168, 1.0
	v_mul_f32_e32 v172, v171, v170
	v_fma_f32 v173, -v169, v172, v171
	v_fmac_f32_e32 v172, v173, v170
	v_fma_f32 v169, -v169, v172, v171
	v_div_fmas_f32 v169, v169, v170, v172
	v_div_fixup_f32 v168, v169, v168, 1.0
	s_nop 0
	v_readlane_b32 s37, v168, 0
	v_readlane_b32 s41, v168, 1
	v_readlane_b32 s45, v168, 2
	v_readlane_b32 s49, v168, 3
	v_mul_f32_e32 v100, s37, v100
	v_mul_f32_e32 v105, s41, v105
	v_mul_f32_e32 v110, s45, v110
	v_mul_f32_e32 v115, s49, v115
	v_lshlrev_b32_e32 v103, 16, v103
	v_lshlrev_b32_e32 v108, 16, v108
	v_lshlrev_b32_e32 v113, 16, v113
	v_lshlrev_b32_e32 v118, 16, v118
	v_fma_f32 v100, v6, v100, v7
	v_fma_f32 v105, v6, v105, v7
	v_fma_f32 v110, v6, v110, v7
	v_fma_f32 v115, v6, v115, v7
	v_fmac_f32_e32 v100, s73, v101
	v_fmac_f32_e32 v105, s26, v106
	v_fmac_f32_e32 v110, s27, v111
	v_fmac_f32_e32 v115, s32, v116
	v_mul_f32_e32 v100, v100, v103
	v_mul_f32_e32 v105, v105, v108
	v_mul_f32_e32 v110, v110, v113
	v_mul_f32_e32 v115, v115, v118
	v_cvt_pk_bf16_f32 v169, v100, v100
	v_cvt_pk_bf16_f32 v175, v105, v105
	v_cvt_pk_bf16_f32 v242, v110, v110
	v_cvt_pk_bf16_f32 v248, v115, v115
	global_store_short v2, v169, s[28:29]
	s_add_u32 s28, s28, 0x1000
	s_addc_u32 s29, s29, 0
	global_store_short v2, v175, s[28:29]
	s_add_u32 s28, s28, 0x1000
	s_addc_u32 s29, s29, 0
	global_store_short v2, v242, s[28:29]
	s_add_u32 s28, s28, 0x1000
	s_addc_u32 s29, s29, 0
	global_store_short v2, v248, s[28:29]
	s_add_u32 s28, s28, 0x1000
	s_addc_u32 s29, s29, 0
	s_waitcnt vmcnt(8)
	ds_write_b128 v13, v[120:123] offset:0
	ds_write_b128 v13, v[124:127] offset:1024
	ds_write_b128 v13, v[128:131] offset:16384
	ds_write_b128 v13, v[132:135] offset:17408
	ds_write_b128 v15, v[136:139]
	v_readlane_b32 s69, v159, 0
	v_readlane_b32 s70, v159, 1
	v_readlane_b32 s71, v159, 2
	v_readlane_b32 s72, v159, 3
	v_readlane_b32 s73, v159, 4
	v_readlane_b32 s26, v159, 5
	v_readlane_b32 s27, v159, 6
	v_readlane_b32 s32, v159, 7
	global_load_dwordx4 v[120:123], v11, s[6:7]
	global_load_dwordx4 v[124:127], v11, s[6:7] offset:1024
	global_load_dwordx4 v[128:131], v11, s[8:9]
	global_load_dwordx4 v[132:135], v11, s[8:9] offset:1024
	global_load_dwordx4 v[136:139], v11, s[10:11]
	global_load_dword v159, v158, s[12:13]
	s_add_u32 s6, s6, 0x10000
	s_addc_u32 s7, s7, 0
	s_add_u32 s8, s8, 0x10000
	s_addc_u32 s9, s9, 0
	s_add_u32 s10, s10, 0x8000
	s_addc_u32 s11, s11, 0
	s_add_u32 s12, s12, 0x400
	s_addc_u32 s13, s13, 0
	s_waitcnt lgkmcnt(0)
	s_barrier
; #define POST_LD(Y_, V_, G_, R_, C_, t) do { _Pragma("unroll") for (int q = 0; q < 8; ++q) { const size_t o_ = (size_t)((t) + q) * DH; Y_[q] = yp[o_]; V_[q] = vp[o_]; G_[q] = gp[o_]; R_[q] = rp[((t) + q) * 32]; C_[q] = cp[o_]; } } while (0)
; __device__ __forceinline__ void rw_post(Frame& F) {
;     ...
;         POST_LD(y, vv, gg, rk, cc, 0);
;     ...
;             for (int q = 0; q < 8; ++q) { const int row = rb0 + t0 + q;
;                 const float mean = wsum(y[q]) * (1.f / 64.f); const float dv = y[q] - mean; const float var = wsum(dv * dv) * (1.f / 64.f);
;                 const float yn = dv * (1.f / sqrtf(var + 64e-5f)) * g_ + b_;
	ds_read_b32 v80, v155 offset:0
	ds_read_b32 v81, v155 offset:16384
	ds_read_u16 v83, v157 offset:0
	ds_read_b32 v85, v155 offset:2048
	ds_read_b32 v86, v155 offset:18432
	ds_read_u16 v88, v157 offset:1024
	ds_read_b32 v90, v155 offset:4096
	ds_read_b32 v91, v155 offset:20480
	ds_read_u16 v93, v157 offset:2048
	ds_read_b32 v95, v155 offset:6144
	ds_read_b32 v96, v155 offset:22528
	ds_read_u16 v98, v157 offset:3072
	ds_read_b32 v100, v155 offset:8192
	ds_read_b32 v101, v155 offset:24576
	ds_read_u16 v103, v157 offset:4096
	ds_read_b32 v105, v155 offset:10240
	ds_read_b32 v106, v155 offset:26624
	ds_read_u16 v108, v157 offset:5120
	ds_read_b32 v110, v155 offset:12288
	ds_read_b32 v111, v155 offset:28672
	ds_read_u16 v113, v157 offset:6144
	ds_read_b32 v115, v155 offset:14336
	ds_read_b32 v116, v155 offset:30720
	ds_read_u16 v118, v157 offset:7168
	s_waitcnt lgkmcnt(0)
	v_add_f32_e32 v80, v80, v52
	v_add_f32_e32 v85, v85, v53
	v_add_f32_e32 v90, v90, v54
	v_add_f32_e32 v95, v95, v55
	v_add_f32_dpp v168, v80, v80 quad_perm:[1,0,3,2] row_mask:0xf bank_mask:0xf bound_ctrl:1
	v_add_f32_dpp v174, v85, v85 quad_perm:[1,0,3,2] row_mask:0xf bank_mask:0xf bound_ctrl:1
	v_add_f32_dpp v241, v90, v90 quad_perm:[1,0,3,2] row_mask:0xf bank_mask:0xf bound_ctrl:1
	v_add_f32_dpp v247, v95, v95 quad_perm:[1,0,3,2] row_mask:0xf bank_mask:0xf bound_ctrl:1
	v_add_f32_dpp v168, v168, v168 quad_perm:[2,3,0,1] row_mask:0xf bank_mask:0xf bound_ctrl:1
	v_add_f32_dpp v174, v174, v174 quad_perm:[2,3,0,1] row_mask:0xf bank_mask:0xf bound_ctrl:1
	v_add_f32_dpp v241, v241, v241 quad_perm:[2,3,0,1] row_mask:0xf bank_mask:0xf bound_ctrl:1
	v_add_f32_dpp v247, v247, v247 quad_perm:[2,3,0,1] row_mask:0xf bank_mask:0xf bound_ctrl:1
	v_add_f32_dpp v168, v168, v168 row_half_mirror row_mask:0xf bank_mask:0xf bound_ctrl:1
	v_add_f32_dpp v174, v174, v174 row_half_mirror row_mask:0xf bank_mask:0xf bound_ctrl:1
	v_add_f32_dpp v241, v241, v241 row_half_mirror row_mask:0xf bank_mask:0xf bound_ctrl:1
	v_add_f32_dpp v247, v247, v247 row_half_mirror row_mask:0xf bank_mask:0xf bound_ctrl:1
	v_add_f32_dpp v168, v168, v168 row_mirror row_mask:0xf bank_mask:0xf bound_ctrl:1
	v_add_f32_dpp v174, v174, v174 row_mirror row_mask:0xf bank_mask:0xf bound_ctrl:1
	v_add_f32_dpp v241, v241, v241 row_mirror row_mask:0xf bank_mask:0xf bound_ctrl:1
	v_add_f32_dpp v247, v247, v247 row_mirror row_mask:0xf bank_mask:0xf bound_ctrl:1
	v_readlane_b32 s36, v168, 16
	v_readlane_b32 s40, v174, 16
	v_readlane_b32 s44, v241, 16
	v_readlane_b32 s48, v247, 16
	v_readlane_b32 s37, v168, 48
	v_readlane_b32 s41, v174, 48
	v_readlane_b32 s45, v241, 48
	v_readlane_b32 s49, v247, 48
	v_readlane_b32 s38, v168, 0
	v_readlane_b32 s42, v174, 0
	v_readlane_b32 s46, v241, 0
	v_readlane_b32 s50, v247, 0
	v_readlane_b32 s39, v168, 32
	v_readlane_b32 s43, v174, 32
	v_readlane_b32 s47, v241, 32
	v_readlane_b32 s51, v247, 32
	v_mov_b32_e32 v168, s36
	v_mov_b32_e32 v174, s40
	v_mov_b32_e32 v241, s44
	v_mov_b32_e32 v247, s48
	v_mov_b32_e32 v169, s37
	v_mov_b32_e32 v175, s41
	v_mov_b32_e32 v242, s45
	v_mov_b32_e32 v248, s49
	v_add_f32_e32 v168, s38, v168
	v_add_f32_e32 v174, s42, v174
	v_add_f32_e32 v241, s46, v241
	v_add_f32_e32 v247, s50, v247
	v_add_f32_e32 v169, s39, v169
	v_add_f32_e32 v175, s43, v175
	v_add_f32_e32 v242, s47, v242
	v_add_f32_e32 v248, s51, v248
	v_add_f32_e32 v168, v168, v169
	v_add_f32_e32 v174, v174, v175
	v_add_f32_e32 v241, v241, v242
	v_add_f32_e32 v247, v247, v248
	v_fmamk_f32 v80, v168, 0xbc800000, v80
	v_fmamk_f32 v85, v174, 0xbc800000, v85
	v_fmamk_f32 v90, v241, 0xbc800000, v90
	v_fmamk_f32 v95, v247, 0xbc800000, v95
	v_mul_f32_e32 v168, v80, v80
	v_mul_f32_e32 v174, v85, v85
	v_mul_f32_e32 v241, v90, v90
	v_mul_f32_e32 v247, v95, v95
	v_mov_b32_dpp v168, v168 quad_perm:[1,0,3,2] row_mask:0xf bank_mask:0xf bound_ctrl:1
	v_mov_b32_dpp v174, v174 quad_perm:[1,0,3,2] row_mask:0xf bank_mask:0xf bound_ctrl:1
	v_mov_b32_dpp v241, v241 quad_perm:[1,0,3,2] row_mask:0xf bank_mask:0xf bound_ctrl:1
	v_mov_b32_dpp v247, v247 quad_perm:[1,0,3,2] row_mask:0xf bank_mask:0xf bound_ctrl:1
	v_fmac_f32_e32 v168, v80, v80
	v_fmac_f32_e32 v174, v85, v85
	v_fmac_f32_e32 v241, v90, v90
	v_fmac_f32_e32 v247, v95, v95
	v_add_f32_dpp v168, v168, v168 quad_perm:[2,3,0,1] row_mask:0xf bank_mask:0xf bound_ctrl:1
	v_add_f32_dpp v174, v174, v174 quad_perm:[2,3,0,1] row_mask:0xf bank_mask:0xf bound_ctrl:1
	v_add_f32_dpp v241, v241, v241 quad_perm:[2,3,0,1] row_mask:0xf bank_mask:0xf bound_ctrl:1
	v_add_f32_dpp v247, v247, v247 quad_perm:[2,3,0,1] row_mask:0xf bank_mask:0xf bound_ctrl:1
	v_add_f32_dpp v168, v168, v168 row_half_mirror row_mask:0xf bank_mask:0xf bound_ctrl:1
	v_add_f32_dpp v174, v174, v174 row_half_mirror row_mask:0xf bank_mask:0xf bound_ctrl:1
	v_add_f32_dpp v241, v241, v241 row_half_mirror row_mask:0xf bank_mask:0xf bound_ctrl:1
	v_add_f32_dpp v247, v247, v247 row_half_mirror row_mask:0xf bank_mask:0xf bound_ctrl:1
	v_add_f32_dpp v168, v168, v168 row_mirror row_mask:0xf bank_mask:0xf bound_ctrl:1
	v_add_f32_dpp v174, v174, v174 row_mirror row_mask:0xf bank_mask:0xf bound_ctrl:1
	v_add_f32_dpp v241, v241, v241 row_mirror row_mask:0xf bank_mask:0xf bound_ctrl:1
	v_add_f32_dpp v247, v247, v247 row_mirror row_mask:0xf bank_mask:0xf bound_ctrl:1
	v_readlane_b32 s36, v168, 16
	v_readlane_b32 s40, v174, 16
	v_readlane_b32 s44, v241, 16
	v_readlane_b32 s48, v247, 16
	v_readlane_b32 s37, v168, 48
	v_readlane_b32 s41, v174, 48
	v_readlane_b32 s45, v241, 48
	v_readlane_b32 s49, v247, 48
	v_readlane_b32 s38, v168, 0
	v_readlane_b32 s42, v174, 0
	v_readlane_b32 s46, v241, 0
	v_readlane_b32 s50, v247, 0
	v_readlane_b32 s39, v168, 32
; __device__ __forceinline__ float bf2f(bf16 x) { return __uint_as_float(((unsigned)x) << 16); }
; __device__ __forceinline__ unsigned f2bf(float f) { return cvt_pk_bf16(f, 0.f) & 0xffffu; }
; __device__ __forceinline__ float dpp_xor1(float x) { return __builtin_bit_cast(float, __builtin_amdgcn_update_dpp(0, __builtin_bit_cast(int, x), 0xB1, 0xF, 0xF, true)); }
; __device__ __forceinline__ float dpp_xor2(float x) { return __builtin_bit_cast(float, __builtin_amdgcn_update_dpp(0, __builtin_bit_cast(int, x), 0x4E, 0xF, 0xF, true)); }
; __device__ __forceinline__ float dpp_hmir(float x) { return __builtin_bit_cast(float, __builtin_amdgcn_update_dpp(0, __builtin_bit_cast(int, x), 0x141, 0xF, 0xF, true)); }
; __device__ __forceinline__ float dpp_mir(float x)  { return __builtin_bit_cast(float, __builtin_amdgcn_update_dpp(0, __builtin_bit_cast(int, x), 0x140, 0xF, 0xF, true)); }
; __device__ __forceinline__ float red16(float x) { x += dpp_xor1(x); x += dpp_xor2(x); x += dpp_hmir(x); x += dpp_mir(x); return x; }
; __device__ __forceinline__ float wsum(float x) {
;     x = red16(x); const int xi = __builtin_bit_cast(int, x);
;     const float r0 = __builtin_bit_cast(float, __builtin_amdgcn_readlane(xi, 0)), r1 = __builtin_bit_cast(float, __builtin_amdgcn_readlane(xi, 16));
;     const float r2 = __builtin_bit_cast(float, __builtin_amdgcn_readlane(xi, 32)), r3 = __builtin_bit_cast(float, __builtin_amdgcn_readlane(xi, 48));
;     return (r0 + r1) + (r2 + r3);
; }
; __device__ __forceinline__ void rw_post(Frame& F) {
;     ...
;             for (int q = 0; q < 8; ++q) { const int row = rb0 + t0 + q;
;                 const float mean = wsum(y[q]) * (1.f / 64.f); const float dv = y[q] - mean; const float var = wsum(dv * dv) * (1.f / 64.f);
;                 const float yn = dv * (1.f / sqrtf(var + 64e-5f)) * g_ + b_;
;                 OB[(size_t)row * DH + col] = (bf16)f2bf((yn + rk[q] * vv[q]) * bf2f(gg[q])); }
	v_readlane_b32 s43, v174, 32
	v_readlane_b32 s47, v241, 32
	v_readlane_b32 s51, v247, 32
	v_mov_b32_e32 v168, s36
	v_mov_b32_e32 v174, s40
	v_mov_b32_e32 v241, s44
	v_mov_b32_e32 v247, s48
	v_mov_b32_e32 v169, s37
	v_mov_b32_e32 v175, s41
	v_mov_b32_e32 v242, s45
	v_mov_b32_e32 v248, s49
	v_add_f32_e32 v168, s38, v168
	v_add_f32_e32 v174, s42, v174
	v_add_f32_e32 v241, s46, v241
	v_add_f32_e32 v247, s50, v247
	v_add_f32_e32 v169, s39, v169
	v_add_f32_e32 v175, s43, v175
	v_add_f32_e32 v242, s47, v242
	v_add_f32_e32 v248, s51, v248
	v_add_f32_e32 v168, v168, v169
	v_add_f32_e32 v174, v174, v175
	v_add_f32_e32 v241, v241, v242
	v_add_f32_e32 v247, v247, v248
	v_fmamk_f32 v168, v168, 0x3c800000, v9
	v_fmamk_f32 v174, v174, 0x3c800000, v9
	v_fmamk_f32 v241, v241, 0x3c800000, v9
	v_fmamk_f32 v247, v247, 0x3c800000, v9
	v_readfirstlane_b32 s40, v174
	v_readfirstlane_b32 s44, v241
	v_readfirstlane_b32 s48, v247
	v_writelane_b32 v168, s40, 1
	v_writelane_b32 v168, s44, 2
	v_writelane_b32 v168, s48, 3
	v_mul_f32_e32 v169, 0x4f800000, v168
	v_cmp_gt_f32_e64 s[52:53], s68, v168
	v_mov_b32_e32 v170, v168
	s_nop 1
	v_cndmask_b32_e64 v168, v170, v169, s[52:53]
	v_sqrt_f32_e32 v169, v168
	s_nop 0
	v_add_u32_e32 v170, -1, v169
	v_fma_f32 v171, -v170, v169, v168
	v_cmp_ge_f32_e64 s[60:61], 0, v171
	v_add_u32_e32 v171, 1, v169
	s_nop 1
	v_cndmask_b32_e64 v170, v169, v170, s[60:61]
	v_fma_f32 v169, -v171, v169, v168
	v_cmp_lt_f32_e64 s[60:61], 0, v169
	s_nop 1
	v_cndmask_b32_e64 v169, v170, v171, s[60:61]
	v_mul_f32_e32 v170, 0x37800000, v169
	v_cndmask_b32_e64 v169, v169, v170, s[52:53]
	v_cmp_class_f32_e64 s[60:61], v168, v8
	s_nop 1
	v_cndmask_b32_e64 v168, v169, v168, s[60:61]
	v_div_scale_f32 v169, s[60:61], v168, v168, 1.0
	v_rcp_f32_e32 v170, v169
	s_nop 0
	v_fma_f32 v171, -v169, v170, 1.0
	v_fmac_f32_e32 v170, v171, v170
	v_div_scale_f32 v171, vcc, 1.0, v168, 1.0
	v_mul_f32_e32 v172, v171, v170
	v_fma_f32 v173, -v169, v172, v171
	v_fmac_f32_e32 v172, v173, v170
	v_fma_f32 v169, -v169, v172, v171
	v_div_fmas_f32 v169, v169, v170, v172
	v_div_fixup_f32 v168, v169, v168, 1.0
	s_nop 0
	v_readlane_b32 s37, v168, 0
	v_readlane_b32 s41, v168, 1
	v_readlane_b32 s45, v168, 2
	v_readlane_b32 s49, v168, 3
	v_mul_f32_e32 v80, s37, v80
	v_mul_f32_e32 v85, s41, v85
	v_mul_f32_e32 v90, s45, v90
	v_mul_f32_e32 v95, s49, v95
	v_lshlrev_b32_e32 v83, 16, v83
	v_lshlrev_b32_e32 v88, 16, v88
	v_lshlrev_b32_e32 v93, 16, v93
	v_lshlrev_b32_e32 v98, 16, v98
	v_fma_f32 v80, v6, v80, v7
	v_fma_f32 v85, v6, v85, v7
	v_fma_f32 v90, v6, v90, v7
	v_fma_f32 v95, v6, v95, v7
	v_fmac_f32_e32 v80, s69, v81
	v_fmac_f32_e32 v85, s70, v86
	v_fmac_f32_e32 v90, s71, v91
	v_fmac_f32_e32 v95, s72, v96
	v_mul_f32_e32 v80, v80, v83
	v_mul_f32_e32 v85, v85, v88
	v_mul_f32_e32 v90, v90, v93
	v_mul_f32_e32 v95, v95, v98
	v_cvt_pk_bf16_f32 v169, v80, v80
	v_cvt_pk_bf16_f32 v175, v85, v85
	v_cvt_pk_bf16_f32 v242, v90, v90
	v_cvt_pk_bf16_f32 v248, v95, v95
	global_store_short v2, v169, s[28:29]
	s_add_u32 s28, s28, 0x1000
	s_addc_u32 s29, s29, 0
	global_store_short v2, v175, s[28:29]
	s_add_u32 s28, s28, 0x1000
	s_addc_u32 s29, s29, 0
	global_store_short v2, v242, s[28:29]
	s_add_u32 s28, s28, 0x1000
	s_addc_u32 s29, s29, 0
	global_store_short v2, v248, s[28:29]
	s_add_u32 s28, s28, 0x1000
	s_addc_u32 s29, s29, 0
	v_add_f32_e32 v100, v100, v68
	v_add_f32_e32 v105, v105, v69
	v_add_f32_e32 v110, v110, v70
	v_add_f32_e32 v115, v115, v71
	v_add_f32_dpp v168, v100, v100 quad_perm:[1,0,3,2] row_mask:0xf bank_mask:0xf bound_ctrl:1
	v_add_f32_dpp v174, v105, v105 quad_perm:[1,0,3,2] row_mask:0xf bank_mask:0xf bound_ctrl:1
	v_add_f32_dpp v241, v110, v110 quad_perm:[1,0,3,2] row_mask:0xf bank_mask:0xf bound_ctrl:1
	v_add_f32_dpp v247, v115, v115 quad_perm:[1,0,3,2] row_mask:0xf bank_mask:0xf bound_ctrl:1
	v_add_f32_dpp v168, v168, v168 quad_perm:[2,3,0,1] row_mask:0xf bank_mask:0xf bound_ctrl:1
	v_add_f32_dpp v174, v174, v174 quad_perm:[2,3,0,1] row_mask:0xf bank_mask:0xf bound_ctrl:1
	v_add_f32_dpp v241, v241, v241 quad_perm:[2,3,0,1] row_mask:0xf bank_mask:0xf bound_ctrl:1
	v_add_f32_dpp v247, v247, v247 quad_perm:[2,3,0,1] row_mask:0xf bank_mask:0xf bound_ctrl:1
	v_add_f32_dpp v168, v168, v168 row_half_mirror row_mask:0xf bank_mask:0xf bound_ctrl:1
	v_add_f32_dpp v174, v174, v174 row_half_mirror row_mask:0xf bank_mask:0xf bound_ctrl:1
	v_add_f32_dpp v241, v241, v241 row_half_mirror row_mask:0xf bank_mask:0xf bound_ctrl:1
	v_add_f32_dpp v247, v247, v247 row_half_mirror row_mask:0xf bank_mask:0xf bound_ctrl:1
	v_add_f32_dpp v168, v168, v168 row_mirror row_mask:0xf bank_mask:0xf bound_ctrl:1
	v_add_f32_dpp v174, v174, v174 row_mirror row_mask:0xf bank_mask:0xf bound_ctrl:1
	v_add_f32_dpp v241, v241, v241 row_mirror row_mask:0xf bank_mask:0xf bound_ctrl:1
	v_add_f32_dpp v247, v247, v247 row_mirror row_mask:0xf bank_mask:0xf bound_ctrl:1
	v_readlane_b32 s36, v168, 16
	v_readlane_b32 s40, v174, 16
	v_readlane_b32 s44, v241, 16
	v_readlane_b32 s48, v247, 16
	v_readlane_b32 s37, v168, 48
	v_readlane_b32 s41, v174, 48
	v_readlane_b32 s45, v241, 48
	v_readlane_b32 s49, v247, 48
	v_readlane_b32 s38, v168, 0
	v_readlane_b32 s42, v174, 0
	v_readlane_b32 s46, v241, 0
	v_readlane_b32 s50, v247, 0
	v_readlane_b32 s39, v168, 32
	v_readlane_b32 s43, v174, 32
	v_readlane_b32 s47, v241, 32
	v_readlane_b32 s51, v247, 32
	v_mov_b32_e32 v168, s36
	v_mov_b32_e32 v174, s40
	v_mov_b32_e32 v241, s44
	v_mov_b32_e32 v247, s48
	v_mov_b32_e32 v169, s37
	v_mov_b32_e32 v175, s41
	v_mov_b32_e32 v242, s45
	v_mov_b32_e32 v248, s49
	v_add_f32_e32 v168, s38, v168
	v_add_f32_e32 v174, s42, v174
	v_add_f32_e32 v241, s46, v241
; __device__ __forceinline__ float bf2f(bf16 x) { return __uint_as_float(((unsigned)x) << 16); }
; __device__ __forceinline__ unsigned f2bf(float f) { return cvt_pk_bf16(f, 0.f) & 0xffffu; }
; #define POST_LD(Y_, V_, G_, R_, C_, t) do { _Pragma("unroll") for (int q = 0; q < 8; ++q) { const size_t o_ = (size_t)((t) + q) * DH; Y_[q] = yp[o_]; V_[q] = vp[o_]; G_[q] = gp[o_]; R_[q] = rp[((t) + q) * 32]; C_[q] = cp[o_]; } } while (0)
; __device__ __forceinline__ void rw_post(Frame& F) {
;     ...
;         POST_LD(y, vv, gg, rk, cc, 0);
;         for (int t0 = 0; t0 < 64; t0 += 8) {
;             float ny[8], nv[8], nr[8], nc[8]; bf16 ng[8];
;             const int tn = t0 + 8 < 64 ? t0 + 8 : t0;
;             POST_LD(ny, nv, ng, nr, nc, tn);
;     ...
;             for (int q = 0; q < 8; ++q) { const int row = rb0 + t0 + q;
;                 const float mean = wsum(y[q]) * (1.f / 64.f); const float dv = y[q] - mean; const float var = wsum(dv * dv) * (1.f / 64.f);
;                 const float yn = dv * (1.f / sqrtf(var + 64e-5f)) * g_ + b_;
;                 OB[(size_t)row * DH + col] = (bf16)f2bf((yn + rk[q] * vv[q]) * bf2f(gg[q])); }
; #pragma unroll
;             for (int q = 0; q < 8; ++q) { y[q] = ny[q]; vv[q] = nv[q]; gg[q] = ng[q]; rk[q] = nr[q]; cc[q] = nc[q]; }
	v_add_f32_e32 v247, s50, v247
	v_add_f32_e32 v169, s39, v169
	v_add_f32_e32 v175, s43, v175
	v_add_f32_e32 v242, s47, v242
	v_add_f32_e32 v248, s51, v248
	v_add_f32_e32 v168, v168, v169
	v_add_f32_e32 v174, v174, v175
	v_add_f32_e32 v241, v241, v242
	v_add_f32_e32 v247, v247, v248
	v_fmamk_f32 v100, v168, 0xbc800000, v100
	v_fmamk_f32 v105, v174, 0xbc800000, v105
	v_fmamk_f32 v110, v241, 0xbc800000, v110
	v_fmamk_f32 v115, v247, 0xbc800000, v115
	v_mul_f32_e32 v168, v100, v100
	v_mul_f32_e32 v174, v105, v105
	v_mul_f32_e32 v241, v110, v110
	v_mul_f32_e32 v247, v115, v115
	v_mov_b32_dpp v168, v168 quad_perm:[1,0,3,2] row_mask:0xf bank_mask:0xf bound_ctrl:1
	v_mov_b32_dpp v174, v174 quad_perm:[1,0,3,2] row_mask:0xf bank_mask:0xf bound_ctrl:1
	v_mov_b32_dpp v241, v241 quad_perm:[1,0,3,2] row_mask:0xf bank_mask:0xf bound_ctrl:1
	v_mov_b32_dpp v247, v247 quad_perm:[1,0,3,2] row_mask:0xf bank_mask:0xf bound_ctrl:1
	v_fmac_f32_e32 v168, v100, v100
	v_fmac_f32_e32 v174, v105, v105
	v_fmac_f32_e32 v241, v110, v110
	v_fmac_f32_e32 v247, v115, v115
	v_add_f32_dpp v168, v168, v168 quad_perm:[2,3,0,1] row_mask:0xf bank_mask:0xf bound_ctrl:1
	v_add_f32_dpp v174, v174, v174 quad_perm:[2,3,0,1] row_mask:0xf bank_mask:0xf bound_ctrl:1
	v_add_f32_dpp v241, v241, v241 quad_perm:[2,3,0,1] row_mask:0xf bank_mask:0xf bound_ctrl:1
	v_add_f32_dpp v247, v247, v247 quad_perm:[2,3,0,1] row_mask:0xf bank_mask:0xf bound_ctrl:1
	v_add_f32_dpp v168, v168, v168 row_half_mirror row_mask:0xf bank_mask:0xf bound_ctrl:1
	v_add_f32_dpp v174, v174, v174 row_half_mirror row_mask:0xf bank_mask:0xf bound_ctrl:1
	v_add_f32_dpp v241, v241, v241 row_half_mirror row_mask:0xf bank_mask:0xf bound_ctrl:1
	v_add_f32_dpp v247, v247, v247 row_half_mirror row_mask:0xf bank_mask:0xf bound_ctrl:1
	v_add_f32_dpp v168, v168, v168 row_mirror row_mask:0xf bank_mask:0xf bound_ctrl:1
	v_add_f32_dpp v174, v174, v174 row_mirror row_mask:0xf bank_mask:0xf bound_ctrl:1
	v_add_f32_dpp v241, v241, v241 row_mirror row_mask:0xf bank_mask:0xf bound_ctrl:1
	v_add_f32_dpp v247, v247, v247 row_mirror row_mask:0xf bank_mask:0xf bound_ctrl:1
	v_readlane_b32 s36, v168, 16
	v_readlane_b32 s40, v174, 16
	v_readlane_b32 s44, v241, 16
	v_readlane_b32 s48, v247, 16
	v_readlane_b32 s37, v168, 48
	v_readlane_b32 s41, v174, 48
	v_readlane_b32 s45, v241, 48
	v_readlane_b32 s49, v247, 48
	v_readlane_b32 s38, v168, 0
	v_readlane_b32 s42, v174, 0
	v_readlane_b32 s46, v241, 0
	v_readlane_b32 s50, v247, 0
	v_readlane_b32 s39, v168, 32
	v_readlane_b32 s43, v174, 32
	v_readlane_b32 s47, v241, 32
	v_readlane_b32 s51, v247, 32
	v_mov_b32_e32 v168, s36
	v_mov_b32_e32 v174, s40
	v_mov_b32_e32 v241, s44
	v_mov_b32_e32 v247, s48
	v_mov_b32_e32 v169, s37
	v_mov_b32_e32 v175, s41
	v_mov_b32_e32 v242, s45
	v_mov_b32_e32 v248, s49
	v_add_f32_e32 v168, s38, v168
	v_add_f32_e32 v174, s42, v174
	v_add_f32_e32 v241, s46, v241
	v_add_f32_e32 v247, s50, v247
	v_add_f32_e32 v169, s39, v169
	v_add_f32_e32 v175, s43, v175
	v_add_f32_e32 v242, s47, v242
	v_add_f32_e32 v248, s51, v248
	v_add_f32_e32 v168, v168, v169
	v_add_f32_e32 v174, v174, v175
	v_add_f32_e32 v241, v241, v242
	v_add_f32_e32 v247, v247, v248
	v_fmamk_f32 v168, v168, 0x3c800000, v9
	v_fmamk_f32 v174, v174, 0x3c800000, v9
	v_fmamk_f32 v241, v241, 0x3c800000, v9
	v_fmamk_f32 v247, v247, 0x3c800000, v9
	v_readfirstlane_b32 s40, v174
	v_readfirstlane_b32 s44, v241
	v_readfirstlane_b32 s48, v247
	v_writelane_b32 v168, s40, 1
	v_writelane_b32 v168, s44, 2
	v_writelane_b32 v168, s48, 3
	v_mul_f32_e32 v169, 0x4f800000, v168
	v_cmp_gt_f32_e64 s[52:53], s68, v168
	v_mov_b32_e32 v170, v168
	s_nop 1
	v_cndmask_b32_e64 v168, v170, v169, s[52:53]
	v_sqrt_f32_e32 v169, v168
	s_nop 0
	v_add_u32_e32 v170, -1, v169
	v_fma_f32 v171, -v170, v169, v168
	v_cmp_ge_f32_e64 s[60:61], 0, v171
	v_add_u32_e32 v171, 1, v169
	s_nop 1
	v_cndmask_b32_e64 v170, v169, v170, s[60:61]
	v_fma_f32 v169, -v171, v169, v168
	v_cmp_lt_f32_e64 s[60:61], 0, v169
	s_nop 1
	v_cndmask_b32_e64 v169, v170, v171, s[60:61]
	v_mul_f32_e32 v170, 0x37800000, v169
	v_cndmask_b32_e64 v169, v169, v170, s[52:53]
	v_cmp_class_f32_e64 s[60:61], v168, v8
	s_nop 1
	v_cndmask_b32_e64 v168, v169, v168, s[60:61]
	v_div_scale_f32 v169, s[60:61], v168, v168, 1.0
	v_rcp_f32_e32 v170, v169
	s_nop 0
	v_fma_f32 v171, -v169, v170, 1.0
	v_fmac_f32_e32 v170, v171, v170
	v_div_scale_f32 v171, vcc, 1.0, v168, 1.0
	v_mul_f32_e32 v172, v171, v170
	v_fma_f32 v173, -v169, v172, v171
	v_fmac_f32_e32 v172, v173, v170
	v_fma_f32 v169, -v169, v172, v171
	v_div_fmas_f32 v169, v169, v170, v172
	v_div_fixup_f32 v168, v169, v168, 1.0
	s_nop 0
	v_readlane_b32 s37, v168, 0
	v_readlane_b32 s41, v168, 1
	v_readlane_b32 s45, v168, 2
	v_readlane_b32 s49, v168, 3
	v_mul_f32_e32 v100, s37, v100
	v_mul_f32_e32 v105, s41, v105
	v_mul_f32_e32 v110, s45, v110
	v_mul_f32_e32 v115, s49, v115
	v_lshlrev_b32_e32 v103, 16, v103
	v_lshlrev_b32_e32 v108, 16, v108
	v_lshlrev_b32_e32 v113, 16, v113
	v_lshlrev_b32_e32 v118, 16, v118
	v_fma_f32 v100, v6, v100, v7
	v_fma_f32 v105, v6, v105, v7
	v_fma_f32 v110, v6, v110, v7
	v_fma_f32 v115, v6, v115, v7
	v_fmac_f32_e32 v100, s73, v101
	v_fmac_f32_e32 v105, s26, v106
	v_fmac_f32_e32 v110, s27, v111
	v_fmac_f32_e32 v115, s32, v116
	v_mul_f32_e32 v100, v100, v103
	v_mul_f32_e32 v105, v105, v108
	v_mul_f32_e32 v110, v110, v113
	v_mul_f32_e32 v115, v115, v118
	v_cvt_pk_bf16_f32 v169, v100, v100
	v_cvt_pk_bf16_f32 v175, v105, v105
	v_cvt_pk_bf16_f32 v242, v110, v110
	v_cvt_pk_bf16_f32 v248, v115, v115
	global_store_short v2, v169, s[28:29]
	s_add_u32 s28, s28, 0x1000
	s_addc_u32 s29, s29, 0
	global_store_short v2, v175, s[28:29]
	s_add_u32 s28, s28, 0x1000
	s_addc_u32 s29, s29, 0
	global_store_short v2, v242, s[28:29]
	s_add_u32 s28, s28, 0x1000
	s_addc_u32 s29, s29, 0
	global_store_short v2, v248, s[28:29]
	s_add_u32 s28, s28, 0x1000
	s_addc_u32 s29, s29, 0
	s_waitcnt vmcnt(8)
	ds_write_b128 v12, v[120:123] offset:0
	ds_write_b128 v12, v[124:127] offset:1024
	ds_write_b128 v12, v[128:131] offset:16384
	ds_write_b128 v12, v[132:135] offset:17408
	ds_write_b128 v14, v[136:139]
	v_readlane_b32 s69, v159, 0
	v_readlane_b32 s70, v159, 1
	v_readlane_b32 s71, v159, 2
	v_readlane_b32 s72, v159, 3
	v_readlane_b32 s73, v159, 4
	v_readlane_b32 s26, v159, 5
	v_readlane_b32 s27, v159, 6
	v_readlane_b32 s32, v159, 7
	global_load_dwordx4 v[120:123], v11, s[6:7]
	global_load_dwordx4 v[124:127], v11, s[6:7] offset:1024
	global_load_dwordx4 v[128:131], v11, s[8:9]
	global_load_dwordx4 v[132:135], v11, s[8:9] offset:1024
	global_load_dwordx4 v[136:139], v11, s[10:11]
	global_load_dword v159, v158, s[12:13]
	s_add_u32 s6, s6, 0x10000
	s_addc_u32 s7, s7, 0
	s_add_u32 s8, s8, 0x10000
	s_addc_u32 s9, s9, 0
	s_add_u32 s10, s10, 0x8000
	s_addc_u32 s11, s11, 0
	s_add_u32 s12, s12, 0x400
	s_addc_u32 s13, s13, 0
	s_waitcnt lgkmcnt(0)
	s_barrier
; #define POST_LD(Y_, V_, G_, R_, C_, t) do { _Pragma("unroll") for (int q = 0; q < 8; ++q) { const size_t o_ = (size_t)((t) + q) * DH; Y_[q] = yp[o_]; V_[q] = vp[o_]; G_[q] = gp[o_]; R_[q] = rp[((t) + q) * 32]; C_[q] = cp[o_]; } } while (0)
; __device__ __forceinline__ void rw_post(Frame& F) {
;     ...
;         POST_LD(y, vv, gg, rk, cc, 0);
;     ...
;             for (int q = 0; q < 8; ++q) { const int row = rb0 + t0 + q;
;                 const float mean = wsum(y[q]) * (1.f / 64.f); const float dv = y[q] - mean; const float var = wsum(dv * dv) * (1.f / 64.f);
;                 const float yn = dv * (1.f / sqrtf(var + 64e-5f)) * g_ + b_;
	ds_read_b32 v80, v154 offset:0
	ds_read_b32 v81, v154 offset:16384
	ds_read_u16 v83, v156 offset:0
	ds_read_b32 v85, v154 offset:2048
	ds_read_b32 v86, v154 offset:18432
	ds_read_u16 v88, v156 offset:1024
	ds_read_b32 v90, v154 offset:4096
	ds_read_b32 v91, v154 offset:20480
	ds_read_u16 v93, v156 offset:2048
	ds_read_b32 v95, v154 offset:6144
	ds_read_b32 v96, v154 offset:22528
	ds_read_u16 v98, v156 offset:3072
	ds_read_b32 v100, v154 offset:8192
	ds_read_b32 v101, v154 offset:24576
	ds_read_u16 v103, v156 offset:4096
	ds_read_b32 v105, v154 offset:10240
	ds_read_b32 v106, v154 offset:26624
	ds_read_u16 v108, v156 offset:5120
	ds_read_b32 v110, v154 offset:12288
	ds_read_b32 v111, v154 offset:28672
	ds_read_u16 v113, v156 offset:6144
	ds_read_b32 v115, v154 offset:14336
	ds_read_b32 v116, v154 offset:30720
	ds_read_u16 v118, v156 offset:7168
	s_waitcnt lgkmcnt(0)
	v_add_f32_e32 v80, v80, v56
	v_add_f32_e32 v85, v85, v57
	v_add_f32_e32 v90, v90, v58
	v_add_f32_e32 v95, v95, v59
	v_add_f32_dpp v168, v80, v80 quad_perm:[1,0,3,2] row_mask:0xf bank_mask:0xf bound_ctrl:1
	v_add_f32_dpp v174, v85, v85 quad_perm:[1,0,3,2] row_mask:0xf bank_mask:0xf bound_ctrl:1
	v_add_f32_dpp v241, v90, v90 quad_perm:[1,0,3,2] row_mask:0xf bank_mask:0xf bound_ctrl:1
	v_add_f32_dpp v247, v95, v95 quad_perm:[1,0,3,2] row_mask:0xf bank_mask:0xf bound_ctrl:1
	v_add_f32_dpp v168, v168, v168 quad_perm:[2,3,0,1] row_mask:0xf bank_mask:0xf bound_ctrl:1
	v_add_f32_dpp v174, v174, v174 quad_perm:[2,3,0,1] row_mask:0xf bank_mask:0xf bound_ctrl:1
	v_add_f32_dpp v241, v241, v241 quad_perm:[2,3,0,1] row_mask:0xf bank_mask:0xf bound_ctrl:1
	v_add_f32_dpp v247, v247, v247 quad_perm:[2,3,0,1] row_mask:0xf bank_mask:0xf bound_ctrl:1
	v_add_f32_dpp v168, v168, v168 row_half_mirror row_mask:0xf bank_mask:0xf bound_ctrl:1
	v_add_f32_dpp v174, v174, v174 row_half_mirror row_mask:0xf bank_mask:0xf bound_ctrl:1
	v_add_f32_dpp v241, v241, v241 row_half_mirror row_mask:0xf bank_mask:0xf bound_ctrl:1
	v_add_f32_dpp v247, v247, v247 row_half_mirror row_mask:0xf bank_mask:0xf bound_ctrl:1
	v_add_f32_dpp v168, v168, v168 row_mirror row_mask:0xf bank_mask:0xf bound_ctrl:1
	v_add_f32_dpp v174, v174, v174 row_mirror row_mask:0xf bank_mask:0xf bound_ctrl:1
	v_add_f32_dpp v241, v241, v241 row_mirror row_mask:0xf bank_mask:0xf bound_ctrl:1
	v_add_f32_dpp v247, v247, v247 row_mirror row_mask:0xf bank_mask:0xf bound_ctrl:1
	v_readlane_b32 s36, v168, 16
	v_readlane_b32 s40, v174, 16
	v_readlane_b32 s44, v241, 16
	v_readlane_b32 s48, v247, 16
	v_readlane_b32 s37, v168, 48
	v_readlane_b32 s41, v174, 48
	v_readlane_b32 s45, v241, 48
	v_readlane_b32 s49, v247, 48
	v_readlane_b32 s38, v168, 0
	v_readlane_b32 s42, v174, 0
	v_readlane_b32 s46, v241, 0
	v_readlane_b32 s50, v247, 0
	v_readlane_b32 s39, v168, 32
	v_readlane_b32 s43, v174, 32
	v_readlane_b32 s47, v241, 32
	v_readlane_b32 s51, v247, 32
	v_mov_b32_e32 v168, s36
	v_mov_b32_e32 v174, s40
	v_mov_b32_e32 v241, s44
	v_mov_b32_e32 v247, s48
	v_mov_b32_e32 v169, s37
	v_mov_b32_e32 v175, s41
	v_mov_b32_e32 v242, s45
	v_mov_b32_e32 v248, s49
	v_add_f32_e32 v168, s38, v168
	v_add_f32_e32 v174, s42, v174
	v_add_f32_e32 v241, s46, v241
	v_add_f32_e32 v247, s50, v247
	v_add_f32_e32 v169, s39, v169
	v_add_f32_e32 v175, s43, v175
	v_add_f32_e32 v242, s47, v242
	v_add_f32_e32 v248, s51, v248
	v_add_f32_e32 v168, v168, v169
	v_add_f32_e32 v174, v174, v175
	v_add_f32_e32 v241, v241, v242
	v_add_f32_e32 v247, v247, v248
	v_fmamk_f32 v80, v168, 0xbc800000, v80
	v_fmamk_f32 v85, v174, 0xbc800000, v85
	v_fmamk_f32 v90, v241, 0xbc800000, v90
	v_fmamk_f32 v95, v247, 0xbc800000, v95
	v_mul_f32_e32 v168, v80, v80
	v_mul_f32_e32 v174, v85, v85
	v_mul_f32_e32 v241, v90, v90
	v_mul_f32_e32 v247, v95, v95
	v_mov_b32_dpp v168, v168 quad_perm:[1,0,3,2] row_mask:0xf bank_mask:0xf bound_ctrl:1
	v_mov_b32_dpp v174, v174 quad_perm:[1,0,3,2] row_mask:0xf bank_mask:0xf bound_ctrl:1
	v_mov_b32_dpp v241, v241 quad_perm:[1,0,3,2] row_mask:0xf bank_mask:0xf bound_ctrl:1
	v_mov_b32_dpp v247, v247 quad_perm:[1,0,3,2] row_mask:0xf bank_mask:0xf bound_ctrl:1
	v_fmac_f32_e32 v168, v80, v80
	v_fmac_f32_e32 v174, v85, v85
	v_fmac_f32_e32 v241, v90, v90
	v_fmac_f32_e32 v247, v95, v95
	v_add_f32_dpp v168, v168, v168 quad_perm:[2,3,0,1] row_mask:0xf bank_mask:0xf bound_ctrl:1
	v_add_f32_dpp v174, v174, v174 quad_perm:[2,3,0,1] row_mask:0xf bank_mask:0xf bound_ctrl:1
	v_add_f32_dpp v241, v241, v241 quad_perm:[2,3,0,1] row_mask:0xf bank_mask:0xf bound_ctrl:1
	v_add_f32_dpp v247, v247, v247 quad_perm:[2,3,0,1] row_mask:0xf bank_mask:0xf bound_ctrl:1
	v_add_f32_dpp v168, v168, v168 row_half_mirror row_mask:0xf bank_mask:0xf bound_ctrl:1
	v_add_f32_dpp v174, v174, v174 row_half_mirror row_mask:0xf bank_mask:0xf bound_ctrl:1
	v_add_f32_dpp v241, v241, v241 row_half_mirror row_mask:0xf bank_mask:0xf bound_ctrl:1
	v_add_f32_dpp v247, v247, v247 row_half_mirror row_mask:0xf bank_mask:0xf bound_ctrl:1
	v_add_f32_dpp v168, v168, v168 row_mirror row_mask:0xf bank_mask:0xf bound_ctrl:1
	v_add_f32_dpp v174, v174, v174 row_mirror row_mask:0xf bank_mask:0xf bound_ctrl:1
	v_add_f32_dpp v241, v241, v241 row_mirror row_mask:0xf bank_mask:0xf bound_ctrl:1
	v_add_f32_dpp v247, v247, v247 row_mirror row_mask:0xf bank_mask:0xf bound_ctrl:1
	v_readlane_b32 s36, v168, 16
	v_readlane_b32 s40, v174, 16
	v_readlane_b32 s44, v241, 16
	v_readlane_b32 s48, v247, 16
	v_readlane_b32 s37, v168, 48
	v_readlane_b32 s41, v174, 48
	v_readlane_b32 s45, v241, 48
	v_readlane_b32 s49, v247, 48
	v_readlane_b32 s38, v168, 0
	v_readlane_b32 s42, v174, 0
	v_readlane_b32 s46, v241, 0
	v_readlane_b32 s50, v247, 0
	v_readlane_b32 s39, v168, 32
; __device__ __forceinline__ float bf2f(bf16 x) { return __uint_as_float(((unsigned)x) << 16); }
; __device__ __forceinline__ unsigned f2bf(float f) { return cvt_pk_bf16(f, 0.f) & 0xffffu; }
; __device__ __forceinline__ float dpp_xor1(float x) { return __builtin_bit_cast(float, __builtin_amdgcn_update_dpp(0, __builtin_bit_cast(int, x), 0xB1, 0xF, 0xF, true)); }
; __device__ __forceinline__ float dpp_xor2(float x) { return __builtin_bit_cast(float, __builtin_amdgcn_update_dpp(0, __builtin_bit_cast(int, x), 0x4E, 0xF, 0xF, true)); }
; __device__ __forceinline__ float dpp_hmir(float x) { return __builtin_bit_cast(float, __builtin_amdgcn_update_dpp(0, __builtin_bit_cast(int, x), 0x141, 0xF, 0xF, true)); }
; __device__ __forceinline__ float dpp_mir(float x)  { return __builtin_bit_cast(float, __builtin_amdgcn_update_dpp(0, __builtin_bit_cast(int, x), 0x140, 0xF, 0xF, true)); }
; __device__ __forceinline__ float red16(float x) { x += dpp_xor1(x); x += dpp_xor2(x); x += dpp_hmir(x); x += dpp_mir(x); return x; }
; __device__ __forceinline__ float wsum(float x) {
;     x = red16(x); const int xi = __builtin_bit_cast(int, x);
;     const float r0 = __builtin_bit_cast(float, __builtin_amdgcn_readlane(xi, 0)), r1 = __builtin_bit_cast(float, __builtin_amdgcn_readlane(xi, 16));
;     const float r2 = __builtin_bit_cast(float, __builtin_amdgcn_readlane(xi, 32)), r3 = __builtin_bit_cast(float, __builtin_amdgcn_readlane(xi, 48));
;     return (r0 + r1) + (r2 + r3);
; }
; __device__ __forceinline__ void rw_post(Frame& F) {
;     ...
;             for (int q = 0; q < 8; ++q) { const int row = rb0 + t0 + q;
;                 const float mean = wsum(y[q]) * (1.f / 64.f); const float dv = y[q] - mean; const float var = wsum(dv * dv) * (1.f / 64.f);
;                 const float yn = dv * (1.f / sqrtf(var + 64e-5f)) * g_ + b_;
;                 OB[(size_t)row * DH + col] = (bf16)f2bf((yn + rk[q] * vv[q]) * bf2f(gg[q])); }
	v_readlane_b32 s43, v174, 32
	v_readlane_b32 s47, v241, 32
	v_readlane_b32 s51, v247, 32
	v_mov_b32_e32 v168, s36
	v_mov_b32_e32 v174, s40
	v_mov_b32_e32 v241, s44
	v_mov_b32_e32 v247, s48
	v_mov_b32_e32 v169, s37
	v_mov_b32_e32 v175, s41
	v_mov_b32_e32 v242, s45
	v_mov_b32_e32 v248, s49
	v_add_f32_e32 v168, s38, v168
	v_add_f32_e32 v174, s42, v174
	v_add_f32_e32 v241, s46, v241
	v_add_f32_e32 v247, s50, v247
	v_add_f32_e32 v169, s39, v169
	v_add_f32_e32 v175, s43, v175
	v_add_f32_e32 v242, s47, v242
	v_add_f32_e32 v248, s51, v248
	v_add_f32_e32 v168, v168, v169
	v_add_f32_e32 v174, v174, v175
	v_add_f32_e32 v241, v241, v242
	v_add_f32_e32 v247, v247, v248
	v_fmamk_f32 v168, v168, 0x3c800000, v9
	v_fmamk_f32 v174, v174, 0x3c800000, v9
	v_fmamk_f32 v241, v241, 0x3c800000, v9
	v_fmamk_f32 v247, v247, 0x3c800000, v9
	v_readfirstlane_b32 s40, v174
	v_readfirstlane_b32 s44, v241
	v_readfirstlane_b32 s48, v247
	v_writelane_b32 v168, s40, 1
	v_writelane_b32 v168, s44, 2
	v_writelane_b32 v168, s48, 3
	v_mul_f32_e32 v169, 0x4f800000, v168
	v_cmp_gt_f32_e64 s[52:53], s68, v168
	v_mov_b32_e32 v170, v168
	s_nop 1
	v_cndmask_b32_e64 v168, v170, v169, s[52:53]
	v_sqrt_f32_e32 v169, v168
	s_nop 0
	v_add_u32_e32 v170, -1, v169
	v_fma_f32 v171, -v170, v169, v168
	v_cmp_ge_f32_e64 s[60:61], 0, v171
	v_add_u32_e32 v171, 1, v169
	s_nop 1
	v_cndmask_b32_e64 v170, v169, v170, s[60:61]
	v_fma_f32 v169, -v171, v169, v168
	v_cmp_lt_f32_e64 s[60:61], 0, v169
	s_nop 1
	v_cndmask_b32_e64 v169, v170, v171, s[60:61]
	v_mul_f32_e32 v170, 0x37800000, v169
	v_cndmask_b32_e64 v169, v169, v170, s[52:53]
	v_cmp_class_f32_e64 s[60:61], v168, v8
	s_nop 1
	v_cndmask_b32_e64 v168, v169, v168, s[60:61]
	v_div_scale_f32 v169, s[60:61], v168, v168, 1.0
	v_rcp_f32_e32 v170, v169
	s_nop 0
	v_fma_f32 v171, -v169, v170, 1.0
	v_fmac_f32_e32 v170, v171, v170
	v_div_scale_f32 v171, vcc, 1.0, v168, 1.0
	v_mul_f32_e32 v172, v171, v170
	v_fma_f32 v173, -v169, v172, v171
	v_fmac_f32_e32 v172, v173, v170
	v_fma_f32 v169, -v169, v172, v171
	v_div_fmas_f32 v169, v169, v170, v172
	v_div_fixup_f32 v168, v169, v168, 1.0
	s_nop 0
	v_readlane_b32 s37, v168, 0
	v_readlane_b32 s41, v168, 1
	v_readlane_b32 s45, v168, 2
	v_readlane_b32 s49, v168, 3
	v_mul_f32_e32 v80, s37, v80
	v_mul_f32_e32 v85, s41, v85
	v_mul_f32_e32 v90, s45, v90
	v_mul_f32_e32 v95, s49, v95
	v_lshlrev_b32_e32 v83, 16, v83
	v_lshlrev_b32_e32 v88, 16, v88
	v_lshlrev_b32_e32 v93, 16, v93
	v_lshlrev_b32_e32 v98, 16, v98
	v_fma_f32 v80, v6, v80, v7
	v_fma_f32 v85, v6, v85, v7
	v_fma_f32 v90, v6, v90, v7
	v_fma_f32 v95, v6, v95, v7
	v_fmac_f32_e32 v80, s69, v81
	v_fmac_f32_e32 v85, s70, v86
	v_fmac_f32_e32 v90, s71, v91
	v_fmac_f32_e32 v95, s72, v96
	v_mul_f32_e32 v80, v80, v83
	v_mul_f32_e32 v85, v85, v88
	v_mul_f32_e32 v90, v90, v93
	v_mul_f32_e32 v95, v95, v98
	v_cvt_pk_bf16_f32 v169, v80, v80
	v_cvt_pk_bf16_f32 v175, v85, v85
	v_cvt_pk_bf16_f32 v242, v90, v90
	v_cvt_pk_bf16_f32 v248, v95, v95
	global_store_short v2, v169, s[28:29]
	s_add_u32 s28, s28, 0x1000
	s_addc_u32 s29, s29, 0
	global_store_short v2, v175, s[28:29]
	s_add_u32 s28, s28, 0x1000
	s_addc_u32 s29, s29, 0
	global_store_short v2, v242, s[28:29]
	s_add_u32 s28, s28, 0x1000
	s_addc_u32 s29, s29, 0
	global_store_short v2, v248, s[28:29]
	s_add_u32 s28, s28, 0x1000
	s_addc_u32 s29, s29, 0
	v_add_f32_e32 v100, v100, v72
	v_add_f32_e32 v105, v105, v73
	v_add_f32_e32 v110, v110, v74
	v_add_f32_e32 v115, v115, v75
	v_add_f32_dpp v168, v100, v100 quad_perm:[1,0,3,2] row_mask:0xf bank_mask:0xf bound_ctrl:1
	v_add_f32_dpp v174, v105, v105 quad_perm:[1,0,3,2] row_mask:0xf bank_mask:0xf bound_ctrl:1
	v_add_f32_dpp v241, v110, v110 quad_perm:[1,0,3,2] row_mask:0xf bank_mask:0xf bound_ctrl:1
	v_add_f32_dpp v247, v115, v115 quad_perm:[1,0,3,2] row_mask:0xf bank_mask:0xf bound_ctrl:1
	v_add_f32_dpp v168, v168, v168 quad_perm:[2,3,0,1] row_mask:0xf bank_mask:0xf bound_ctrl:1
	v_add_f32_dpp v174, v174, v174 quad_perm:[2,3,0,1] row_mask:0xf bank_mask:0xf bound_ctrl:1
	v_add_f32_dpp v241, v241, v241 quad_perm:[2,3,0,1] row_mask:0xf bank_mask:0xf bound_ctrl:1
	v_add_f32_dpp v247, v247, v247 quad_perm:[2,3,0,1] row_mask:0xf bank_mask:0xf bound_ctrl:1
	v_add_f32_dpp v168, v168, v168 row_half_mirror row_mask:0xf bank_mask:0xf bound_ctrl:1
	v_add_f32_dpp v174, v174, v174 row_half_mirror row_mask:0xf bank_mask:0xf bound_ctrl:1
	v_add_f32_dpp v241, v241, v241 row_half_mirror row_mask:0xf bank_mask:0xf bound_ctrl:1
	v_add_f32_dpp v247, v247, v247 row_half_mirror row_mask:0xf bank_mask:0xf bound_ctrl:1
	v_add_f32_dpp v168, v168, v168 row_mirror row_mask:0xf bank_mask:0xf bound_ctrl:1
	v_add_f32_dpp v174, v174, v174 row_mirror row_mask:0xf bank_mask:0xf bound_ctrl:1
	v_add_f32_dpp v241, v241, v241 row_mirror row_mask:0xf bank_mask:0xf bound_ctrl:1
	v_add_f32_dpp v247, v247, v247 row_mirror row_mask:0xf bank_mask:0xf bound_ctrl:1
	v_readlane_b32 s36, v168, 16
	v_readlane_b32 s40, v174, 16
	v_readlane_b32 s44, v241, 16
	v_readlane_b32 s48, v247, 16
	v_readlane_b32 s37, v168, 48
	v_readlane_b32 s41, v174, 48
	v_readlane_b32 s45, v241, 48
	v_readlane_b32 s49, v247, 48
	v_readlane_b32 s38, v168, 0
	v_readlane_b32 s42, v174, 0
	v_readlane_b32 s46, v241, 0
	v_readlane_b32 s50, v247, 0
	v_readlane_b32 s39, v168, 32
	v_readlane_b32 s43, v174, 32
	v_readlane_b32 s47, v241, 32
	v_readlane_b32 s51, v247, 32
	v_mov_b32_e32 v168, s36
	v_mov_b32_e32 v174, s40
	v_mov_b32_e32 v241, s44
	v_mov_b32_e32 v247, s48
	v_mov_b32_e32 v169, s37
	v_mov_b32_e32 v175, s41
	v_mov_b32_e32 v242, s45
	v_mov_b32_e32 v248, s49
	v_add_f32_e32 v168, s38, v168
	v_add_f32_e32 v174, s42, v174
	v_add_f32_e32 v241, s46, v241
; __device__ __forceinline__ float bf2f(bf16 x) { return __uint_as_float(((unsigned)x) << 16); }
; __device__ __forceinline__ unsigned f2bf(float f) { return cvt_pk_bf16(f, 0.f) & 0xffffu; }
; #define POST_LD(Y_, V_, G_, R_, C_, t) do { _Pragma("unroll") for (int q = 0; q < 8; ++q) { const size_t o_ = (size_t)((t) + q) * DH; Y_[q] = yp[o_]; V_[q] = vp[o_]; G_[q] = gp[o_]; R_[q] = rp[((t) + q) * 32]; C_[q] = cp[o_]; } } while (0)
; __device__ __forceinline__ void rw_post(Frame& F) {
;     ...
;         POST_LD(y, vv, gg, rk, cc, 0);
;         for (int t0 = 0; t0 < 64; t0 += 8) {
;             float ny[8], nv[8], nr[8], nc[8]; bf16 ng[8];
;             const int tn = t0 + 8 < 64 ? t0 + 8 : t0;
;             POST_LD(ny, nv, ng, nr, nc, tn);
;     ...
;             for (int q = 0; q < 8; ++q) { const int row = rb0 + t0 + q;
;                 const float mean = wsum(y[q]) * (1.f / 64.f); const float dv = y[q] - mean; const float var = wsum(dv * dv) * (1.f / 64.f);
;                 const float yn = dv * (1.f / sqrtf(var + 64e-5f)) * g_ + b_;
;                 OB[(size_t)row * DH + col] = (bf16)f2bf((yn + rk[q] * vv[q]) * bf2f(gg[q])); }
; #pragma unroll
;             for (int q = 0; q < 8; ++q) { y[q] = ny[q]; vv[q] = nv[q]; gg[q] = ng[q]; rk[q] = nr[q]; cc[q] = nc[q]; }
	v_add_f32_e32 v247, s50, v247
	v_add_f32_e32 v169, s39, v169
	v_add_f32_e32 v175, s43, v175
	v_add_f32_e32 v242, s47, v242
	v_add_f32_e32 v248, s51, v248
	v_add_f32_e32 v168, v168, v169
	v_add_f32_e32 v174, v174, v175
	v_add_f32_e32 v241, v241, v242
	v_add_f32_e32 v247, v247, v248
	v_fmamk_f32 v100, v168, 0xbc800000, v100
	v_fmamk_f32 v105, v174, 0xbc800000, v105
	v_fmamk_f32 v110, v241, 0xbc800000, v110
	v_fmamk_f32 v115, v247, 0xbc800000, v115
	v_mul_f32_e32 v168, v100, v100
	v_mul_f32_e32 v174, v105, v105
	v_mul_f32_e32 v241, v110, v110
	v_mul_f32_e32 v247, v115, v115
	v_mov_b32_dpp v168, v168 quad_perm:[1,0,3,2] row_mask:0xf bank_mask:0xf bound_ctrl:1
	v_mov_b32_dpp v174, v174 quad_perm:[1,0,3,2] row_mask:0xf bank_mask:0xf bound_ctrl:1
	v_mov_b32_dpp v241, v241 quad_perm:[1,0,3,2] row_mask:0xf bank_mask:0xf bound_ctrl:1
	v_mov_b32_dpp v247, v247 quad_perm:[1,0,3,2] row_mask:0xf bank_mask:0xf bound_ctrl:1
	v_fmac_f32_e32 v168, v100, v100
	v_fmac_f32_e32 v174, v105, v105
	v_fmac_f32_e32 v241, v110, v110
	v_fmac_f32_e32 v247, v115, v115
	v_add_f32_dpp v168, v168, v168 quad_perm:[2,3,0,1] row_mask:0xf bank_mask:0xf bound_ctrl:1
	v_add_f32_dpp v174, v174, v174 quad_perm:[2,3,0,1] row_mask:0xf bank_mask:0xf bound_ctrl:1
	v_add_f32_dpp v241, v241, v241 quad_perm:[2,3,0,1] row_mask:0xf bank_mask:0xf bound_ctrl:1
	v_add_f32_dpp v247, v247, v247 quad_perm:[2,3,0,1] row_mask:0xf bank_mask:0xf bound_ctrl:1
	v_add_f32_dpp v168, v168, v168 row_half_mirror row_mask:0xf bank_mask:0xf bound_ctrl:1
	v_add_f32_dpp v174, v174, v174 row_half_mirror row_mask:0xf bank_mask:0xf bound_ctrl:1
	v_add_f32_dpp v241, v241, v241 row_half_mirror row_mask:0xf bank_mask:0xf bound_ctrl:1
	v_add_f32_dpp v247, v247, v247 row_half_mirror row_mask:0xf bank_mask:0xf bound_ctrl:1
	v_add_f32_dpp v168, v168, v168 row_mirror row_mask:0xf bank_mask:0xf bound_ctrl:1
	v_add_f32_dpp v174, v174, v174 row_mirror row_mask:0xf bank_mask:0xf bound_ctrl:1
	v_add_f32_dpp v241, v241, v241 row_mirror row_mask:0xf bank_mask:0xf bound_ctrl:1
	v_add_f32_dpp v247, v247, v247 row_mirror row_mask:0xf bank_mask:0xf bound_ctrl:1
	v_readlane_b32 s36, v168, 16
	v_readlane_b32 s40, v174, 16
	v_readlane_b32 s44, v241, 16
	v_readlane_b32 s48, v247, 16
	v_readlane_b32 s37, v168, 48
	v_readlane_b32 s41, v174, 48
	v_readlane_b32 s45, v241, 48
	v_readlane_b32 s49, v247, 48
	v_readlane_b32 s38, v168, 0
	v_readlane_b32 s42, v174, 0
	v_readlane_b32 s46, v241, 0
	v_readlane_b32 s50, v247, 0
	v_readlane_b32 s39, v168, 32
	v_readlane_b32 s43, v174, 32
	v_readlane_b32 s47, v241, 32
	v_readlane_b32 s51, v247, 32
	v_mov_b32_e32 v168, s36
	v_mov_b32_e32 v174, s40
	v_mov_b32_e32 v241, s44
	v_mov_b32_e32 v247, s48
	v_mov_b32_e32 v169, s37
	v_mov_b32_e32 v175, s41
	v_mov_b32_e32 v242, s45
	v_mov_b32_e32 v248, s49
	v_add_f32_e32 v168, s38, v168
	v_add_f32_e32 v174, s42, v174
	v_add_f32_e32 v241, s46, v241
	v_add_f32_e32 v247, s50, v247
	v_add_f32_e32 v169, s39, v169
	v_add_f32_e32 v175, s43, v175
	v_add_f32_e32 v242, s47, v242
	v_add_f32_e32 v248, s51, v248
	v_add_f32_e32 v168, v168, v169
	v_add_f32_e32 v174, v174, v175
	v_add_f32_e32 v241, v241, v242
	v_add_f32_e32 v247, v247, v248
	v_fmamk_f32 v168, v168, 0x3c800000, v9
	v_fmamk_f32 v174, v174, 0x3c800000, v9
	v_fmamk_f32 v241, v241, 0x3c800000, v9
	v_fmamk_f32 v247, v247, 0x3c800000, v9
	v_readfirstlane_b32 s40, v174
	v_readfirstlane_b32 s44, v241
	v_readfirstlane_b32 s48, v247
	v_writelane_b32 v168, s40, 1
	v_writelane_b32 v168, s44, 2
	v_writelane_b32 v168, s48, 3
	v_mul_f32_e32 v169, 0x4f800000, v168
	v_cmp_gt_f32_e64 s[52:53], s68, v168
	v_mov_b32_e32 v170, v168
	s_nop 1
	v_cndmask_b32_e64 v168, v170, v169, s[52:53]
	v_sqrt_f32_e32 v169, v168
	s_nop 0
	v_add_u32_e32 v170, -1, v169
	v_fma_f32 v171, -v170, v169, v168
	v_cmp_ge_f32_e64 s[60:61], 0, v171
	v_add_u32_e32 v171, 1, v169
	s_nop 1
	v_cndmask_b32_e64 v170, v169, v170, s[60:61]
	v_fma_f32 v169, -v171, v169, v168
	v_cmp_lt_f32_e64 s[60:61], 0, v169
	s_nop 1
	v_cndmask_b32_e64 v169, v170, v171, s[60:61]
	v_mul_f32_e32 v170, 0x37800000, v169
	v_cndmask_b32_e64 v169, v169, v170, s[52:53]
	v_cmp_class_f32_e64 s[60:61], v168, v8
	s_nop 1
	v_cndmask_b32_e64 v168, v169, v168, s[60:61]
	v_div_scale_f32 v169, s[60:61], v168, v168, 1.0
	v_rcp_f32_e32 v170, v169
	s_nop 0
	v_fma_f32 v171, -v169, v170, 1.0
	v_fmac_f32_e32 v170, v171, v170
	v_div_scale_f32 v171, vcc, 1.0, v168, 1.0
	v_mul_f32_e32 v172, v171, v170
	v_fma_f32 v173, -v169, v172, v171
	v_fmac_f32_e32 v172, v173, v170
	v_fma_f32 v169, -v169, v172, v171
	v_div_fmas_f32 v169, v169, v170, v172
	v_div_fixup_f32 v168, v169, v168, 1.0
	s_nop 0
	v_readlane_b32 s37, v168, 0
	v_readlane_b32 s41, v168, 1
	v_readlane_b32 s45, v168, 2
	v_readlane_b32 s49, v168, 3
	v_mul_f32_e32 v100, s37, v100
	v_mul_f32_e32 v105, s41, v105
	v_mul_f32_e32 v110, s45, v110
	v_mul_f32_e32 v115, s49, v115
	v_lshlrev_b32_e32 v103, 16, v103
	v_lshlrev_b32_e32 v108, 16, v108
	v_lshlrev_b32_e32 v113, 16, v113
	v_lshlrev_b32_e32 v118, 16, v118
	v_fma_f32 v100, v6, v100, v7
	v_fma_f32 v105, v6, v105, v7
	v_fma_f32 v110, v6, v110, v7
	v_fma_f32 v115, v6, v115, v7
	v_fmac_f32_e32 v100, s73, v101
	v_fmac_f32_e32 v105, s26, v106
	v_fmac_f32_e32 v110, s27, v111
	v_fmac_f32_e32 v115, s32, v116
	v_mul_f32_e32 v100, v100, v103
	v_mul_f32_e32 v105, v105, v108
	v_mul_f32_e32 v110, v110, v113
	v_mul_f32_e32 v115, v115, v118
	v_cvt_pk_bf16_f32 v169, v100, v100
	v_cvt_pk_bf16_f32 v175, v105, v105
	v_cvt_pk_bf16_f32 v242, v110, v110
	v_cvt_pk_bf16_f32 v248, v115, v115
	global_store_short v2, v169, s[28:29]
	s_add_u32 s28, s28, 0x1000
	s_addc_u32 s29, s29, 0
	global_store_short v2, v175, s[28:29]
	s_add_u32 s28, s28, 0x1000
	s_addc_u32 s29, s29, 0
	global_store_short v2, v242, s[28:29]
	s_add_u32 s28, s28, 0x1000
	s_addc_u32 s29, s29, 0
	global_store_short v2, v248, s[28:29]
	s_add_u32 s28, s28, 0x1000
	s_addc_u32 s29, s29, 0
	s_waitcnt vmcnt(8)
	ds_write_b128 v13, v[120:123] offset:0
	ds_write_b128 v13, v[124:127] offset:1024
	ds_write_b128 v13, v[128:131] offset:16384
	ds_write_b128 v13, v[132:135] offset:17408
	ds_write_b128 v15, v[136:139]
	v_readlane_b32 s69, v159, 0
	v_readlane_b32 s70, v159, 1
	v_readlane_b32 s71, v159, 2
	v_readlane_b32 s72, v159, 3
	v_readlane_b32 s73, v159, 4
	v_readlane_b32 s26, v159, 5
	v_readlane_b32 s27, v159, 6
	v_readlane_b32 s32, v159, 7
	s_waitcnt lgkmcnt(0)
	s_barrier
; #define POST_LD(Y_, V_, G_, R_, C_, t) do { _Pragma("unroll") for (int q = 0; q < 8; ++q) { const size_t o_ = (size_t)((t) + q) * DH; Y_[q] = yp[o_]; V_[q] = vp[o_]; G_[q] = gp[o_]; R_[q] = rp[((t) + q) * 32]; C_[q] = cp[o_]; } } while (0)
; __device__ __forceinline__ void rw_post(Frame& F) {
;     ...
;         POST_LD(y, vv, gg, rk, cc, 0);
;     ...
;             for (int q = 0; q < 8; ++q) { const int row = rb0 + t0 + q;
;                 const float mean = wsum(y[q]) * (1.f / 64.f); const float dv = y[q] - mean; const float var = wsum(dv * dv) * (1.f / 64.f);
;                 const float yn = dv * (1.f / sqrtf(var + 64e-5f)) * g_ + b_;
	ds_read_b32 v80, v155 offset:0
	ds_read_b32 v81, v155 offset:16384
	ds_read_u16 v83, v157 offset:0
	ds_read_b32 v85, v155 offset:2048
	ds_read_b32 v86, v155 offset:18432
	ds_read_u16 v88, v157 offset:1024
	ds_read_b32 v90, v155 offset:4096
	ds_read_b32 v91, v155 offset:20480
	ds_read_u16 v93, v157 offset:2048
	ds_read_b32 v95, v155 offset:6144
	ds_read_b32 v96, v155 offset:22528
	ds_read_u16 v98, v157 offset:3072
	ds_read_b32 v100, v155 offset:8192
	ds_read_b32 v101, v155 offset:24576
	ds_read_u16 v103, v157 offset:4096
	ds_read_b32 v105, v155 offset:10240
	ds_read_b32 v106, v155 offset:26624
	ds_read_u16 v108, v157 offset:5120
	ds_read_b32 v110, v155 offset:12288
	ds_read_b32 v111, v155 offset:28672
	ds_read_u16 v113, v157 offset:6144
	ds_read_b32 v115, v155 offset:14336
	ds_read_b32 v116, v155 offset:30720
	ds_read_u16 v118, v157 offset:7168
	s_waitcnt lgkmcnt(0)
	v_add_f32_e32 v80, v80, v60
	v_add_f32_e32 v85, v85, v61
	v_add_f32_e32 v90, v90, v62
	v_add_f32_e32 v95, v95, v63
	v_add_f32_dpp v168, v80, v80 quad_perm:[1,0,3,2] row_mask:0xf bank_mask:0xf bound_ctrl:1
	v_add_f32_dpp v174, v85, v85 quad_perm:[1,0,3,2] row_mask:0xf bank_mask:0xf bound_ctrl:1
	v_add_f32_dpp v241, v90, v90 quad_perm:[1,0,3,2] row_mask:0xf bank_mask:0xf bound_ctrl:1
	v_add_f32_dpp v247, v95, v95 quad_perm:[1,0,3,2] row_mask:0xf bank_mask:0xf bound_ctrl:1
	v_add_f32_dpp v168, v168, v168 quad_perm:[2,3,0,1] row_mask:0xf bank_mask:0xf bound_ctrl:1
	v_add_f32_dpp v174, v174, v174 quad_perm:[2,3,0,1] row_mask:0xf bank_mask:0xf bound_ctrl:1
	v_add_f32_dpp v241, v241, v241 quad_perm:[2,3,0,1] row_mask:0xf bank_mask:0xf bound_ctrl:1
	v_add_f32_dpp v247, v247, v247 quad_perm:[2,3,0,1] row_mask:0xf bank_mask:0xf bound_ctrl:1
	v_add_f32_dpp v168, v168, v168 row_half_mirror row_mask:0xf bank_mask:0xf bound_ctrl:1
	v_add_f32_dpp v174, v174, v174 row_half_mirror row_mask:0xf bank_mask:0xf bound_ctrl:1
	v_add_f32_dpp v241, v241, v241 row_half_mirror row_mask:0xf bank_mask:0xf bound_ctrl:1
	v_add_f32_dpp v247, v247, v247 row_half_mirror row_mask:0xf bank_mask:0xf bound_ctrl:1
	v_add_f32_dpp v168, v168, v168 row_mirror row_mask:0xf bank_mask:0xf bound_ctrl:1
	v_add_f32_dpp v174, v174, v174 row_mirror row_mask:0xf bank_mask:0xf bound_ctrl:1
	v_add_f32_dpp v241, v241, v241 row_mirror row_mask:0xf bank_mask:0xf bound_ctrl:1
	v_add_f32_dpp v247, v247, v247 row_mirror row_mask:0xf bank_mask:0xf bound_ctrl:1
	v_readlane_b32 s36, v168, 16
	v_readlane_b32 s40, v174, 16
	v_readlane_b32 s44, v241, 16
	v_readlane_b32 s48, v247, 16
	v_readlane_b32 s37, v168, 48
	v_readlane_b32 s41, v174, 48
	v_readlane_b32 s45, v241, 48
	v_readlane_b32 s49, v247, 48
	v_readlane_b32 s38, v168, 0
	v_readlane_b32 s42, v174, 0
	v_readlane_b32 s46, v241, 0
	v_readlane_b32 s50, v247, 0
	v_readlane_b32 s39, v168, 32
	v_readlane_b32 s43, v174, 32
	v_readlane_b32 s47, v241, 32
	v_readlane_b32 s51, v247, 32
	v_mov_b32_e32 v168, s36
	v_mov_b32_e32 v174, s40
	v_mov_b32_e32 v241, s44
	v_mov_b32_e32 v247, s48
	v_mov_b32_e32 v169, s37
	v_mov_b32_e32 v175, s41
	v_mov_b32_e32 v242, s45
	v_mov_b32_e32 v248, s49
	v_add_f32_e32 v168, s38, v168
	v_add_f32_e32 v174, s42, v174
	v_add_f32_e32 v241, s46, v241
	v_add_f32_e32 v247, s50, v247
	v_add_f32_e32 v169, s39, v169
	v_add_f32_e32 v175, s43, v175
	v_add_f32_e32 v242, s47, v242
	v_add_f32_e32 v248, s51, v248
	v_add_f32_e32 v168, v168, v169
	v_add_f32_e32 v174, v174, v175
	v_add_f32_e32 v241, v241, v242
	v_add_f32_e32 v247, v247, v248
	v_fmamk_f32 v80, v168, 0xbc800000, v80
	v_fmamk_f32 v85, v174, 0xbc800000, v85
	v_fmamk_f32 v90, v241, 0xbc800000, v90
	v_fmamk_f32 v95, v247, 0xbc800000, v95
	v_mul_f32_e32 v168, v80, v80
	v_mul_f32_e32 v174, v85, v85
	v_mul_f32_e32 v241, v90, v90
	v_mul_f32_e32 v247, v95, v95
	v_mov_b32_dpp v168, v168 quad_perm:[1,0,3,2] row_mask:0xf bank_mask:0xf bound_ctrl:1
	v_mov_b32_dpp v174, v174 quad_perm:[1,0,3,2] row_mask:0xf bank_mask:0xf bound_ctrl:1
	v_mov_b32_dpp v241, v241 quad_perm:[1,0,3,2] row_mask:0xf bank_mask:0xf bound_ctrl:1
	v_mov_b32_dpp v247, v247 quad_perm:[1,0,3,2] row_mask:0xf bank_mask:0xf bound_ctrl:1
	v_fmac_f32_e32 v168, v80, v80
	v_fmac_f32_e32 v174, v85, v85
	v_fmac_f32_e32 v241, v90, v90
	v_fmac_f32_e32 v247, v95, v95
	v_add_f32_dpp v168, v168, v168 quad_perm:[2,3,0,1] row_mask:0xf bank_mask:0xf bound_ctrl:1
	v_add_f32_dpp v174, v174, v174 quad_perm:[2,3,0,1] row_mask:0xf bank_mask:0xf bound_ctrl:1
	v_add_f32_dpp v241, v241, v241 quad_perm:[2,3,0,1] row_mask:0xf bank_mask:0xf bound_ctrl:1
	v_add_f32_dpp v247, v247, v247 quad_perm:[2,3,0,1] row_mask:0xf bank_mask:0xf bound_ctrl:1
	v_add_f32_dpp v168, v168, v168 row_half_mirror row_mask:0xf bank_mask:0xf bound_ctrl:1
	v_add_f32_dpp v174, v174, v174 row_half_mirror row_mask:0xf bank_mask:0xf bound_ctrl:1
	v_add_f32_dpp v241, v241, v241 row_half_mirror row_mask:0xf bank_mask:0xf bound_ctrl:1
	v_add_f32_dpp v247, v247, v247 row_half_mirror row_mask:0xf bank_mask:0xf bound_ctrl:1
	v_add_f32_dpp v168, v168, v168 row_mirror row_mask:0xf bank_mask:0xf bound_ctrl:1
	v_add_f32_dpp v174, v174, v174 row_mirror row_mask:0xf bank_mask:0xf bound_ctrl:1
	v_add_f32_dpp v241, v241, v241 row_mirror row_mask:0xf bank_mask:0xf bound_ctrl:1
	v_add_f32_dpp v247, v247, v247 row_mirror row_mask:0xf bank_mask:0xf bound_ctrl:1
	v_readlane_b32 s36, v168, 16
	v_readlane_b32 s40, v174, 16
	v_readlane_b32 s44, v241, 16
	v_readlane_b32 s48, v247, 16
	v_readlane_b32 s37, v168, 48
	v_readlane_b32 s41, v174, 48
	v_readlane_b32 s45, v241, 48
	v_readlane_b32 s49, v247, 48
	v_readlane_b32 s38, v168, 0
	v_readlane_b32 s42, v174, 0
	v_readlane_b32 s46, v241, 0
	v_readlane_b32 s50, v247, 0
	v_readlane_b32 s39, v168, 32
; __device__ __forceinline__ float bf2f(bf16 x) { return __uint_as_float(((unsigned)x) << 16); }
; __device__ __forceinline__ unsigned f2bf(float f) { return cvt_pk_bf16(f, 0.f) & 0xffffu; }
; __device__ __forceinline__ float dpp_xor1(float x) { return __builtin_bit_cast(float, __builtin_amdgcn_update_dpp(0, __builtin_bit_cast(int, x), 0xB1, 0xF, 0xF, true)); }
; __device__ __forceinline__ float dpp_xor2(float x) { return __builtin_bit_cast(float, __builtin_amdgcn_update_dpp(0, __builtin_bit_cast(int, x), 0x4E, 0xF, 0xF, true)); }
; __device__ __forceinline__ float dpp_hmir(float x) { return __builtin_bit_cast(float, __builtin_amdgcn_update_dpp(0, __builtin_bit_cast(int, x), 0x141, 0xF, 0xF, true)); }
; __device__ __forceinline__ float dpp_mir(float x)  { return __builtin_bit_cast(float, __builtin_amdgcn_update_dpp(0, __builtin_bit_cast(int, x), 0x140, 0xF, 0xF, true)); }
; __device__ __forceinline__ float red16(float x) { x += dpp_xor1(x); x += dpp_xor2(x); x += dpp_hmir(x); x += dpp_mir(x); return x; }
; __device__ __forceinline__ float wsum(float x) {
;     x = red16(x); const int xi = __builtin_bit_cast(int, x);
;     const float r0 = __builtin_bit_cast(float, __builtin_amdgcn_readlane(xi, 0)), r1 = __builtin_bit_cast(float, __builtin_amdgcn_readlane(xi, 16));
;     const float r2 = __builtin_bit_cast(float, __builtin_amdgcn_readlane(xi, 32)), r3 = __builtin_bit_cast(float, __builtin_amdgcn_readlane(xi, 48));
;     return (r0 + r1) + (r2 + r3);
; }
; __device__ __forceinline__ void rw_post(Frame& F) {
;     ...
;             for (int q = 0; q < 8; ++q) { const int row = rb0 + t0 + q;
;                 const float mean = wsum(y[q]) * (1.f / 64.f); const float dv = y[q] - mean; const float var = wsum(dv * dv) * (1.f / 64.f);
;                 const float yn = dv * (1.f / sqrtf(var + 64e-5f)) * g_ + b_;
;                 OB[(size_t)row * DH + col] = (bf16)f2bf((yn + rk[q] * vv[q]) * bf2f(gg[q])); }
	v_readlane_b32 s43, v174, 32
	v_readlane_b32 s47, v241, 32
	v_readlane_b32 s51, v247, 32
	v_mov_b32_e32 v168, s36
	v_mov_b32_e32 v174, s40
	v_mov_b32_e32 v241, s44
	v_mov_b32_e32 v247, s48
	v_mov_b32_e32 v169, s37
	v_mov_b32_e32 v175, s41
	v_mov_b32_e32 v242, s45
	v_mov_b32_e32 v248, s49
	v_add_f32_e32 v168, s38, v168
	v_add_f32_e32 v174, s42, v174
	v_add_f32_e32 v241, s46, v241
	v_add_f32_e32 v247, s50, v247
	v_add_f32_e32 v169, s39, v169
	v_add_f32_e32 v175, s43, v175
	v_add_f32_e32 v242, s47, v242
	v_add_f32_e32 v248, s51, v248
	v_add_f32_e32 v168, v168, v169
	v_add_f32_e32 v174, v174, v175
	v_add_f32_e32 v241, v241, v242
	v_add_f32_e32 v247, v247, v248
	v_fmamk_f32 v168, v168, 0x3c800000, v9
	v_fmamk_f32 v174, v174, 0x3c800000, v9
	v_fmamk_f32 v241, v241, 0x3c800000, v9
	v_fmamk_f32 v247, v247, 0x3c800000, v9
	v_readfirstlane_b32 s40, v174
	v_readfirstlane_b32 s44, v241
	v_readfirstlane_b32 s48, v247
	v_writelane_b32 v168, s40, 1
	v_writelane_b32 v168, s44, 2
	v_writelane_b32 v168, s48, 3
	v_mul_f32_e32 v169, 0x4f800000, v168
	v_cmp_gt_f32_e64 s[52:53], s68, v168
	v_mov_b32_e32 v170, v168
	s_nop 1
	v_cndmask_b32_e64 v168, v170, v169, s[52:53]
	v_sqrt_f32_e32 v169, v168
	s_nop 0
	v_add_u32_e32 v170, -1, v169
	v_fma_f32 v171, -v170, v169, v168
	v_cmp_ge_f32_e64 s[60:61], 0, v171
	v_add_u32_e32 v171, 1, v169
	s_nop 1
	v_cndmask_b32_e64 v170, v169, v170, s[60:61]
	v_fma_f32 v169, -v171, v169, v168
	v_cmp_lt_f32_e64 s[60:61], 0, v169
	s_nop 1
	v_cndmask_b32_e64 v169, v170, v171, s[60:61]
	v_mul_f32_e32 v170, 0x37800000, v169
	v_cndmask_b32_e64 v169, v169, v170, s[52:53]
	v_cmp_class_f32_e64 s[60:61], v168, v8
	s_nop 1
	v_cndmask_b32_e64 v168, v169, v168, s[60:61]
	v_div_scale_f32 v169, s[60:61], v168, v168, 1.0
	v_rcp_f32_e32 v170, v169
	s_nop 0
	v_fma_f32 v171, -v169, v170, 1.0
	v_fmac_f32_e32 v170, v171, v170
	v_div_scale_f32 v171, vcc, 1.0, v168, 1.0
	v_mul_f32_e32 v172, v171, v170
	v_fma_f32 v173, -v169, v172, v171
	v_fmac_f32_e32 v172, v173, v170
	v_fma_f32 v169, -v169, v172, v171
	v_div_fmas_f32 v169, v169, v170, v172
	v_div_fixup_f32 v168, v169, v168, 1.0
	s_nop 0
	v_readlane_b32 s37, v168, 0
	v_readlane_b32 s41, v168, 1
	v_readlane_b32 s45, v168, 2
	v_readlane_b32 s49, v168, 3
	v_mul_f32_e32 v80, s37, v80
	v_mul_f32_e32 v85, s41, v85
	v_mul_f32_e32 v90, s45, v90
	v_mul_f32_e32 v95, s49, v95
	v_lshlrev_b32_e32 v83, 16, v83
	v_lshlrev_b32_e32 v88, 16, v88
	v_lshlrev_b32_e32 v93, 16, v93
	v_lshlrev_b32_e32 v98, 16, v98
	v_fma_f32 v80, v6, v80, v7
	v_fma_f32 v85, v6, v85, v7
	v_fma_f32 v90, v6, v90, v7
	v_fma_f32 v95, v6, v95, v7
	v_fmac_f32_e32 v80, s69, v81
	v_fmac_f32_e32 v85, s70, v86
	v_fmac_f32_e32 v90, s71, v91
	v_fmac_f32_e32 v95, s72, v96
	v_mul_f32_e32 v80, v80, v83
	v_mul_f32_e32 v85, v85, v88
	v_mul_f32_e32 v90, v90, v93
	v_mul_f32_e32 v95, v95, v98
	v_cvt_pk_bf16_f32 v169, v80, v80
	v_cvt_pk_bf16_f32 v175, v85, v85
	v_cvt_pk_bf16_f32 v242, v90, v90
	v_cvt_pk_bf16_f32 v248, v95, v95
	global_store_short v2, v169, s[28:29]
	s_add_u32 s28, s28, 0x1000
	s_addc_u32 s29, s29, 0
	global_store_short v2, v175, s[28:29]
	s_add_u32 s28, s28, 0x1000
	s_addc_u32 s29, s29, 0
	global_store_short v2, v242, s[28:29]
	s_add_u32 s28, s28, 0x1000
	s_addc_u32 s29, s29, 0
	global_store_short v2, v248, s[28:29]
	s_add_u32 s28, s28, 0x1000
	s_addc_u32 s29, s29, 0
	v_add_f32_e32 v100, v100, v76
	v_add_f32_e32 v105, v105, v77
	v_add_f32_e32 v110, v110, v78
	v_add_f32_e32 v115, v115, v79
	v_add_f32_dpp v168, v100, v100 quad_perm:[1,0,3,2] row_mask:0xf bank_mask:0xf bound_ctrl:1
	v_add_f32_dpp v174, v105, v105 quad_perm:[1,0,3,2] row_mask:0xf bank_mask:0xf bound_ctrl:1
	v_add_f32_dpp v241, v110, v110 quad_perm:[1,0,3,2] row_mask:0xf bank_mask:0xf bound_ctrl:1
	v_add_f32_dpp v247, v115, v115 quad_perm:[1,0,3,2] row_mask:0xf bank_mask:0xf bound_ctrl:1
	v_add_f32_dpp v168, v168, v168 quad_perm:[2,3,0,1] row_mask:0xf bank_mask:0xf bound_ctrl:1
	v_add_f32_dpp v174, v174, v174 quad_perm:[2,3,0,1] row_mask:0xf bank_mask:0xf bound_ctrl:1
	v_add_f32_dpp v241, v241, v241 quad_perm:[2,3,0,1] row_mask:0xf bank_mask:0xf bound_ctrl:1
	v_add_f32_dpp v247, v247, v247 quad_perm:[2,3,0,1] row_mask:0xf bank_mask:0xf bound_ctrl:1
	v_add_f32_dpp v168, v168, v168 row_half_mirror row_mask:0xf bank_mask:0xf bound_ctrl:1
	v_add_f32_dpp v174, v174, v174 row_half_mirror row_mask:0xf bank_mask:0xf bound_ctrl:1
	v_add_f32_dpp v241, v241, v241 row_half_mirror row_mask:0xf bank_mask:0xf bound_ctrl:1
	v_add_f32_dpp v247, v247, v247 row_half_mirror row_mask:0xf bank_mask:0xf bound_ctrl:1
	v_add_f32_dpp v168, v168, v168 row_mirror row_mask:0xf bank_mask:0xf bound_ctrl:1
	v_add_f32_dpp v174, v174, v174 row_mirror row_mask:0xf bank_mask:0xf bound_ctrl:1
	v_add_f32_dpp v241, v241, v241 row_mirror row_mask:0xf bank_mask:0xf bound_ctrl:1
	v_add_f32_dpp v247, v247, v247 row_mirror row_mask:0xf bank_mask:0xf bound_ctrl:1
	v_readlane_b32 s36, v168, 16
	v_readlane_b32 s40, v174, 16
	v_readlane_b32 s44, v241, 16
	v_readlane_b32 s48, v247, 16
	v_readlane_b32 s37, v168, 48
	v_readlane_b32 s41, v174, 48
	v_readlane_b32 s45, v241, 48
	v_readlane_b32 s49, v247, 48
	v_readlane_b32 s38, v168, 0
	v_readlane_b32 s42, v174, 0
	v_readlane_b32 s46, v241, 0
	v_readlane_b32 s50, v247, 0
	v_readlane_b32 s39, v168, 32
	v_readlane_b32 s43, v174, 32
	v_readlane_b32 s47, v241, 32
	v_readlane_b32 s51, v247, 32
	v_mov_b32_e32 v168, s36
	v_mov_b32_e32 v174, s40
	v_mov_b32_e32 v241, s44
	v_mov_b32_e32 v247, s48
	v_mov_b32_e32 v169, s37
	v_mov_b32_e32 v175, s41
	v_mov_b32_e32 v242, s45
	v_mov_b32_e32 v248, s49
	v_add_f32_e32 v168, s38, v168
	v_add_f32_e32 v174, s42, v174
	v_add_f32_e32 v241, s46, v241
; __device__ __forceinline__ float bf2f(bf16 x) { return __uint_as_float(((unsigned)x) << 16); }
; __device__ __forceinline__ unsigned f2bf(float f) { return cvt_pk_bf16(f, 0.f) & 0xffffu; }
; __device__ __forceinline__ void rw_post(Frame& F) {
;     ...
;     for (int u = F.gw; u < 32 * (MR / 64); u += F.NGW) { const int h = u & 31, rb0 = (u >> 5) * 64, col = h * 64 + lane;
;     ...
;             for (int q = 0; q < 8; ++q) { const int row = rb0 + t0 + q;
;                 const float mean = wsum(y[q]) * (1.f / 64.f); const float dv = y[q] - mean; const float var = wsum(dv * dv) * (1.f / 64.f);
;                 const float yn = dv * (1.f / sqrtf(var + 64e-5f)) * g_ + b_;
;                 OB[(size_t)row * DH + col] = (bf16)f2bf((yn + rk[q] * vv[q]) * bf2f(gg[q])); }
	v_add_f32_e32 v247, s50, v247
	v_add_f32_e32 v169, s39, v169
	v_add_f32_e32 v175, s43, v175
	v_add_f32_e32 v242, s47, v242
	v_add_f32_e32 v248, s51, v248
	v_add_f32_e32 v168, v168, v169
	v_add_f32_e32 v174, v174, v175
	v_add_f32_e32 v241, v241, v242
	v_add_f32_e32 v247, v247, v248
	v_fmamk_f32 v100, v168, 0xbc800000, v100
	v_fmamk_f32 v105, v174, 0xbc800000, v105
	v_fmamk_f32 v110, v241, 0xbc800000, v110
	v_fmamk_f32 v115, v247, 0xbc800000, v115
	v_mul_f32_e32 v168, v100, v100
	v_mul_f32_e32 v174, v105, v105
	v_mul_f32_e32 v241, v110, v110
	v_mul_f32_e32 v247, v115, v115
	v_mov_b32_dpp v168, v168 quad_perm:[1,0,3,2] row_mask:0xf bank_mask:0xf bound_ctrl:1
	v_mov_b32_dpp v174, v174 quad_perm:[1,0,3,2] row_mask:0xf bank_mask:0xf bound_ctrl:1
	v_mov_b32_dpp v241, v241 quad_perm:[1,0,3,2] row_mask:0xf bank_mask:0xf bound_ctrl:1
	v_mov_b32_dpp v247, v247 quad_perm:[1,0,3,2] row_mask:0xf bank_mask:0xf bound_ctrl:1
	v_fmac_f32_e32 v168, v100, v100
	v_fmac_f32_e32 v174, v105, v105
	v_fmac_f32_e32 v241, v110, v110
	v_fmac_f32_e32 v247, v115, v115
	v_add_f32_dpp v168, v168, v168 quad_perm:[2,3,0,1] row_mask:0xf bank_mask:0xf bound_ctrl:1
	v_add_f32_dpp v174, v174, v174 quad_perm:[2,3,0,1] row_mask:0xf bank_mask:0xf bound_ctrl:1
	v_add_f32_dpp v241, v241, v241 quad_perm:[2,3,0,1] row_mask:0xf bank_mask:0xf bound_ctrl:1
	v_add_f32_dpp v247, v247, v247 quad_perm:[2,3,0,1] row_mask:0xf bank_mask:0xf bound_ctrl:1
	v_add_f32_dpp v168, v168, v168 row_half_mirror row_mask:0xf bank_mask:0xf bound_ctrl:1
	v_add_f32_dpp v174, v174, v174 row_half_mirror row_mask:0xf bank_mask:0xf bound_ctrl:1
	v_add_f32_dpp v241, v241, v241 row_half_mirror row_mask:0xf bank_mask:0xf bound_ctrl:1
	v_add_f32_dpp v247, v247, v247 row_half_mirror row_mask:0xf bank_mask:0xf bound_ctrl:1
	v_add_f32_dpp v168, v168, v168 row_mirror row_mask:0xf bank_mask:0xf bound_ctrl:1
	v_add_f32_dpp v174, v174, v174 row_mirror row_mask:0xf bank_mask:0xf bound_ctrl:1
	v_add_f32_dpp v241, v241, v241 row_mirror row_mask:0xf bank_mask:0xf bound_ctrl:1
	v_add_f32_dpp v247, v247, v247 row_mirror row_mask:0xf bank_mask:0xf bound_ctrl:1
	v_readlane_b32 s36, v168, 16
	v_readlane_b32 s40, v174, 16
	v_readlane_b32 s44, v241, 16
	v_readlane_b32 s48, v247, 16
	v_readlane_b32 s37, v168, 48
	v_readlane_b32 s41, v174, 48
	v_readlane_b32 s45, v241, 48
	v_readlane_b32 s49, v247, 48
	v_readlane_b32 s38, v168, 0
	v_readlane_b32 s42, v174, 0
	v_readlane_b32 s46, v241, 0
	v_readlane_b32 s50, v247, 0
	v_readlane_b32 s39, v168, 32
	v_readlane_b32 s43, v174, 32
	v_readlane_b32 s47, v241, 32
	v_readlane_b32 s51, v247, 32
	v_mov_b32_e32 v168, s36
	v_mov_b32_e32 v174, s40
	v_mov_b32_e32 v241, s44
	v_mov_b32_e32 v247, s48
	v_mov_b32_e32 v169, s37
	v_mov_b32_e32 v175, s41
	v_mov_b32_e32 v242, s45
	v_mov_b32_e32 v248, s49
	v_add_f32_e32 v168, s38, v168
	v_add_f32_e32 v174, s42, v174
	v_add_f32_e32 v241, s46, v241
	v_add_f32_e32 v247, s50, v247
	v_add_f32_e32 v169, s39, v169
	v_add_f32_e32 v175, s43, v175
	v_add_f32_e32 v242, s47, v242
	v_add_f32_e32 v248, s51, v248
	v_add_f32_e32 v168, v168, v169
	v_add_f32_e32 v174, v174, v175
	v_add_f32_e32 v241, v241, v242
	v_add_f32_e32 v247, v247, v248
	v_fmamk_f32 v168, v168, 0x3c800000, v9
	v_fmamk_f32 v174, v174, 0x3c800000, v9
	v_fmamk_f32 v241, v241, 0x3c800000, v9
	v_fmamk_f32 v247, v247, 0x3c800000, v9
	v_readfirstlane_b32 s40, v174
	v_readfirstlane_b32 s44, v241
	v_readfirstlane_b32 s48, v247
	v_writelane_b32 v168, s40, 1
	v_writelane_b32 v168, s44, 2
	v_writelane_b32 v168, s48, 3
	v_mul_f32_e32 v169, 0x4f800000, v168
	v_cmp_gt_f32_e64 s[52:53], s68, v168
	v_mov_b32_e32 v170, v168
	s_nop 1
	v_cndmask_b32_e64 v168, v170, v169, s[52:53]
	v_sqrt_f32_e32 v169, v168
	s_nop 0
	v_add_u32_e32 v170, -1, v169
	v_fma_f32 v171, -v170, v169, v168
	v_cmp_ge_f32_e64 s[60:61], 0, v171
	v_add_u32_e32 v171, 1, v169
	s_nop 1
	v_cndmask_b32_e64 v170, v169, v170, s[60:61]
	v_fma_f32 v169, -v171, v169, v168
	v_cmp_lt_f32_e64 s[60:61], 0, v169
	s_nop 1
	v_cndmask_b32_e64 v169, v170, v171, s[60:61]
	v_mul_f32_e32 v170, 0x37800000, v169
	v_cndmask_b32_e64 v169, v169, v170, s[52:53]
	v_cmp_class_f32_e64 s[60:61], v168, v8
	s_nop 1
	v_cndmask_b32_e64 v168, v169, v168, s[60:61]
	v_div_scale_f32 v169, s[60:61], v168, v168, 1.0
	v_rcp_f32_e32 v170, v169
	s_nop 0
	v_fma_f32 v171, -v169, v170, 1.0
	v_fmac_f32_e32 v170, v171, v170
	v_div_scale_f32 v171, vcc, 1.0, v168, 1.0
	v_mul_f32_e32 v172, v171, v170
	v_fma_f32 v173, -v169, v172, v171
	v_fmac_f32_e32 v172, v173, v170
	v_fma_f32 v169, -v169, v172, v171
	v_div_fmas_f32 v169, v169, v170, v172
	v_div_fixup_f32 v168, v169, v168, 1.0
	s_nop 0
	v_readlane_b32 s37, v168, 0
	v_readlane_b32 s41, v168, 1
	v_readlane_b32 s45, v168, 2
	v_readlane_b32 s49, v168, 3
	v_mul_f32_e32 v100, s37, v100
	v_mul_f32_e32 v105, s41, v105
	v_mul_f32_e32 v110, s45, v110
	v_mul_f32_e32 v115, s49, v115
	v_lshlrev_b32_e32 v103, 16, v103
	v_lshlrev_b32_e32 v108, 16, v108
	v_lshlrev_b32_e32 v113, 16, v113
	v_lshlrev_b32_e32 v118, 16, v118
	v_fma_f32 v100, v6, v100, v7
	v_fma_f32 v105, v6, v105, v7
	v_fma_f32 v110, v6, v110, v7
	v_fma_f32 v115, v6, v115, v7
	v_fmac_f32_e32 v100, s73, v101
	v_fmac_f32_e32 v105, s26, v106
	v_fmac_f32_e32 v110, s27, v111
	v_fmac_f32_e32 v115, s32, v116
	v_mul_f32_e32 v100, v100, v103
	v_mul_f32_e32 v105, v105, v108
	v_mul_f32_e32 v110, v110, v113
	v_mul_f32_e32 v115, v115, v118
	v_cvt_pk_bf16_f32 v169, v100, v100
	v_cvt_pk_bf16_f32 v175, v105, v105
	v_cvt_pk_bf16_f32 v242, v110, v110
	v_cvt_pk_bf16_f32 v248, v115, v115
	global_store_short v2, v169, s[28:29]
	s_add_u32 s28, s28, 0x1000
	s_addc_u32 s29, s29, 0
	global_store_short v2, v175, s[28:29]
	s_add_u32 s28, s28, 0x1000
	s_addc_u32 s29, s29, 0
	global_store_short v2, v242, s[28:29]
	s_add_u32 s28, s28, 0x1000
	s_addc_u32 s29, s29, 0
	global_store_short v2, v248, s[28:29]
	s_add_u32 s28, s28, 0x1000
	s_addc_u32 s29, s29, 0
	s_add_i32 s20, s20, s92
	s_cmpk_lt_i32 s20, 0x2000
	s_cbranch_scc1 .Lpo_unit
; #define POST_LD(Y_, V_, G_, R_, C_, t) do { _Pragma("unroll") for (int q = 0; q < 8; ++q) { const size_t o_ = (size_t)((t) + q) * DH; Y_[q] = yp[o_]; V_[q] = vp[o_]; G_[q] = gp[o_]; R_[q] = rp[((t) + q) * 32]; C_[q] = cp[o_]; } } while (0)
; __device__ __forceinline__ void rw_post(Frame& F) {
;     ...
;     for (int u = F.gw; u < 32 * (MR / 64); u += F.NGW) { const int h = u & 31, rb0 = (u >> 5) * 64, col = h * 64 + lane;
;         const float g_ = lng[col], b_ = lnb[col];
;         const int k = rb0 < MPR ? (rb0 / SEGLEN) : 0;
;         f32x4 Sr[16];
;         if (k > 0) {
; #pragma unroll
;             for (int q = 0; q < 16; ++q) Sr[q] = *(const f32x4*)(SST + ((size_t)(h * NSEG + k) * 64 + lane) * 64 + 4 * q); }
;         const float* yp = Y + (size_t)rb0 * DH + col; const float* vp = VS + (size_t)rb0 * DH + col; const bf16* gp = G + (size_t)rb0 * DH + col; const float* rp = RK + (size_t)rb0 * 32 + h;
;         const float* cp = k > 0 ? C + (size_t)(rb0 - SEGLEN) * DH + col : yp;
;         float y[8], vv[8], rk[8], cc[8]; bf16 gg[8];
;     ...
;         POST_LD(y, vv, gg, rk, cc, 0);
	s_cmp_lt_u32 s2, 64
	s_cbranch_scc0 .Lpo_done
	s_lshr_b32 s20, s2, 2
	s_and_b32 s20, s20, 1
	s_add_i32 s20, s20, 0x100
	s_lshl_b32 s20, s20, 5
	s_and_b32 s21, s2, 3
	s_lshl_b32 s21, s21, 3
	s_add_i32 s20, s20, s21
	s_add_i32 s20, s20, s33
	s_and_b32 s21, s20, 31
	s_lshr_b32 s22, s20, 5
	s_lshl_b32 s22, s22, 6
	s_lshr_b32 s23, s22, 10
	s_cmpk_lt_i32 s22, 0x4000
	s_cselect_b32 s23, s23, 0
	s_add_i32 s34, s22, s33
	s_and_b32 s35, s21, 24
	s_lshl_b32 s30, s34, 13
	s_lshl_b32 s31, s35, 8
	s_add_u32 s30, s30, s31
	s_add_u32 s6, s90, s30
	s_addc_u32 s7, s91, 0
	s_add_u32 s8, s6, 0x28700000
	s_addc_u32 s9, s7, 0
	s_add_u32 s6, s6, 0x39900000
	s_addc_u32 s7, s7, 0
	s_lshl_b32 s30, s34, 12
	s_lshl_b32 s31, s35, 7
	s_add_u32 s30, s30, s31
	s_add_u32 s10, s90, s30
	s_addc_u32 s11, s91, 0
	s_add_u32 s10, s10, 0x30800000
	s_addc_u32 s11, s11, 0
	s_lshl_b32 s30, s22, 12
	s_lshl_b32 s31, s21, 7
	s_add_u32 s30, s30, s31
	s_add_u32 s28, s90, s30
	s_addc_u32 s29, s91, 0
	s_add_u32 s28, s28, 0x18500000
	s_addc_u32 s29, s29, 0
	s_lshl_b32 s30, s22, 7
	s_lshl_b32 s31, s21, 2
	s_add_u32 s30, s30, s31
	s_add_u32 s12, s90, s30
	s_addc_u32 s13, s91, 0
	s_add_u32 s12, s12, 0x6e200000
	s_addc_u32 s13, s13, 0
	s_lshl_b32 s31, s21, 8
	s_add_u32 s30, s16, s31
	s_addc_u32 s31, s17, 0
	global_load_dword v6, v1, s[30:31]
	s_lshl_b32 s31, s21, 8
	s_add_u32 s30, s18, s31
	s_addc_u32 s31, s19, 0
	global_load_dword v7, v1, s[30:31]
	s_lshr_b32 s30, s2, 3
	s_and_b32 s30, s30, 7
	s_lshl_b32 s30, s30, 3
	s_lshl_b32 s31, s30, 13
	s_add_u32 s6, s6, s31
	s_addc_u32 s7, s7, 0
	s_add_u32 s8, s8, s31
	s_addc_u32 s9, s9, 0
	s_lshl_b32 s31, s30, 12
	s_add_u32 s10, s10, s31
	s_addc_u32 s11, s11, 0
	s_add_u32 s28, s28, s31
	s_addc_u32 s29, s29, 0
	s_lshl_b32 s31, s30, 7
	s_add_u32 s12, s12, s31
	s_addc_u32 s13, s13, 0
	s_barrier
	v_mov_b32_e32 v16, 0
	v_mov_b32_e32 v17, 0
	v_mov_b32_e32 v18, 0
	v_mov_b32_e32 v19, 0
	v_mov_b32_e32 v20, 0
	v_mov_b32_e32 v21, 0
	v_mov_b32_e32 v22, 0
	v_mov_b32_e32 v23, 0
	v_mov_b32_e32 v24, 0
	v_mov_b32_e32 v25, 0
	v_mov_b32_e32 v26, 0
	v_mov_b32_e32 v27, 0
	v_mov_b32_e32 v28, 0
	v_mov_b32_e32 v29, 0
	v_mov_b32_e32 v30, 0
	v_mov_b32_e32 v31, 0
	v_mov_b32_e32 v32, 0
	v_mov_b32_e32 v33, 0
	v_mov_b32_e32 v34, 0
	v_mov_b32_e32 v35, 0
	v_mov_b32_e32 v36, 0
	v_mov_b32_e32 v37, 0
	v_mov_b32_e32 v38, 0
	v_mov_b32_e32 v39, 0
	v_mov_b32_e32 v40, 0
	v_mov_b32_e32 v41, 0
	v_mov_b32_e32 v42, 0
	v_mov_b32_e32 v43, 0
	v_mov_b32_e32 v44, 0
	v_mov_b32_e32 v45, 0
	v_mov_b32_e32 v46, 0
	v_mov_b32_e32 v47, 0
	v_mov_b32_e32 v48, 0
	v_mov_b32_e32 v49, 0
	v_mov_b32_e32 v50, 0
	v_mov_b32_e32 v51, 0
	v_mov_b32_e32 v52, 0
	v_mov_b32_e32 v53, 0
	v_mov_b32_e32 v54, 0
	v_mov_b32_e32 v55, 0
	v_mov_b32_e32 v56, 0
	v_mov_b32_e32 v57, 0
	v_mov_b32_e32 v58, 0
	v_mov_b32_e32 v59, 0
	v_mov_b32_e32 v60, 0
	v_mov_b32_e32 v61, 0
	v_mov_b32_e32 v62, 0
	v_mov_b32_e32 v63, 0
	v_mov_b32_e32 v64, 0
	v_mov_b32_e32 v65, 0
	v_mov_b32_e32 v66, 0
	v_mov_b32_e32 v67, 0
	v_mov_b32_e32 v68, 0
	v_mov_b32_e32 v69, 0
	v_mov_b32_e32 v70, 0
	v_mov_b32_e32 v71, 0
	v_mov_b32_e32 v72, 0
	v_mov_b32_e32 v73, 0
	v_mov_b32_e32 v74, 0
	v_mov_b32_e32 v75, 0
	v_mov_b32_e32 v76, 0
	v_mov_b32_e32 v77, 0
	v_mov_b32_e32 v78, 0
	v_mov_b32_e32 v79, 0
	global_load_dwordx4 v[120:123], v11, s[6:7]
	global_load_dwordx4 v[124:127], v11, s[6:7] offset:1024
	global_load_dwordx4 v[128:131], v11, s[8:9]
	global_load_dwordx4 v[132:135], v11, s[8:9] offset:1024
	global_load_dwordx4 v[136:139], v11, s[10:11]
	global_load_dword v159, v158, s[12:13]
	s_add_u32 s6, s6, 0x10000
	s_addc_u32 s7, s7, 0
	s_add_u32 s8, s8, 0x10000
	s_addc_u32 s9, s9, 0
	s_add_u32 s10, s10, 0x8000
	s_addc_u32 s11, s11, 0
	s_add_u32 s12, s12, 0x400
	s_addc_u32 s13, s13, 0
	s_waitcnt vmcnt(0)
	s_waitcnt vmcnt(8)
	ds_write_b128 v12, v[120:123] offset:0
	ds_write_b128 v12, v[124:127] offset:1024
	ds_write_b128 v12, v[128:131] offset:16384
	ds_write_b128 v12, v[132:135] offset:17408
	ds_write_b128 v14, v[136:139]
	v_readlane_b32 s69, v159, 0
	v_readlane_b32 s70, v159, 1
	v_readlane_b32 s71, v159, 2
	v_readlane_b32 s72, v159, 3
	v_readlane_b32 s73, v159, 4
	v_readlane_b32 s26, v159, 5
	v_readlane_b32 s27, v159, 6
	v_readlane_b32 s32, v159, 7
	s_waitcnt lgkmcnt(0)
	s_barrier
	ds_read_b32 v80, v154 offset:0
	ds_read_b32 v81, v154 offset:16384
	ds_read_u16 v83, v156 offset:0
	ds_read_b32 v85, v154 offset:2048
	ds_read_b32 v86, v154 offset:18432
	ds_read_u16 v88, v156 offset:1024
	ds_read_b32 v90, v154 offset:4096
	ds_read_b32 v91, v154 offset:20480
	ds_read_u16 v93, v156 offset:2048
	ds_read_b32 v95, v154 offset:6144
	ds_read_b32 v96, v154 offset:22528
	ds_read_u16 v98, v156 offset:3072
	ds_read_b32 v100, v154 offset:8192
	ds_read_b32 v101, v154 offset:24576
	ds_read_u16 v103, v156 offset:4096
	ds_read_b32 v105, v154 offset:10240
	ds_read_b32 v106, v154 offset:26624
	ds_read_u16 v108, v156 offset:5120
	ds_read_b32 v110, v154 offset:12288
	ds_read_b32 v111, v154 offset:28672
	ds_read_u16 v113, v156 offset:6144
	ds_read_b32 v115, v154 offset:14336
	ds_read_b32 v116, v154 offset:30720
	ds_read_u16 v118, v156 offset:7168
	s_waitcnt lgkmcnt(0)
; __device__ __forceinline__ float bf2f(bf16 x) { return __uint_as_float(((unsigned)x) << 16); }
; __device__ __forceinline__ unsigned f2bf(float f) { return cvt_pk_bf16(f, 0.f) & 0xffffu; }
; __device__ __forceinline__ void rw_post(Frame& F) {
;     ...
;             for (int q = 0; q < 8; ++q) { const int row = rb0 + t0 + q;
;                 const float mean = wsum(y[q]) * (1.f / 64.f); const float dv = y[q] - mean; const float var = wsum(dv * dv) * (1.f / 64.f);
;                 const float yn = dv * (1.f / sqrtf(var + 64e-5f)) * g_ + b_;
;                 OB[(size_t)row * DH + col] = (bf16)f2bf((yn + rk[q] * vv[q]) * bf2f(gg[q])); }
	v_add_f32_e32 v80, v80, v16
	v_add_f32_e32 v85, v85, v17
	v_add_f32_e32 v90, v90, v18
	v_add_f32_e32 v95, v95, v19
	v_add_f32_dpp v168, v80, v80 quad_perm:[1,0,3,2] row_mask:0xf bank_mask:0xf bound_ctrl:1
	v_add_f32_dpp v174, v85, v85 quad_perm:[1,0,3,2] row_mask:0xf bank_mask:0xf bound_ctrl:1
	v_add_f32_dpp v241, v90, v90 quad_perm:[1,0,3,2] row_mask:0xf bank_mask:0xf bound_ctrl:1
	v_add_f32_dpp v247, v95, v95 quad_perm:[1,0,3,2] row_mask:0xf bank_mask:0xf bound_ctrl:1
	v_add_f32_dpp v168, v168, v168 quad_perm:[2,3,0,1] row_mask:0xf bank_mask:0xf bound_ctrl:1
	v_add_f32_dpp v174, v174, v174 quad_perm:[2,3,0,1] row_mask:0xf bank_mask:0xf bound_ctrl:1
	v_add_f32_dpp v241, v241, v241 quad_perm:[2,3,0,1] row_mask:0xf bank_mask:0xf bound_ctrl:1
	v_add_f32_dpp v247, v247, v247 quad_perm:[2,3,0,1] row_mask:0xf bank_mask:0xf bound_ctrl:1
	v_add_f32_dpp v168, v168, v168 row_half_mirror row_mask:0xf bank_mask:0xf bound_ctrl:1
	v_add_f32_dpp v174, v174, v174 row_half_mirror row_mask:0xf bank_mask:0xf bound_ctrl:1
	v_add_f32_dpp v241, v241, v241 row_half_mirror row_mask:0xf bank_mask:0xf bound_ctrl:1
	v_add_f32_dpp v247, v247, v247 row_half_mirror row_mask:0xf bank_mask:0xf bound_ctrl:1
	v_add_f32_dpp v168, v168, v168 row_mirror row_mask:0xf bank_mask:0xf bound_ctrl:1
	v_add_f32_dpp v174, v174, v174 row_mirror row_mask:0xf bank_mask:0xf bound_ctrl:1
	v_add_f32_dpp v241, v241, v241 row_mirror row_mask:0xf bank_mask:0xf bound_ctrl:1
	v_add_f32_dpp v247, v247, v247 row_mirror row_mask:0xf bank_mask:0xf bound_ctrl:1
	v_readlane_b32 s36, v168, 16
	v_readlane_b32 s40, v174, 16
	v_readlane_b32 s44, v241, 16
	v_readlane_b32 s48, v247, 16
	v_readlane_b32 s37, v168, 48
	v_readlane_b32 s41, v174, 48
	v_readlane_b32 s45, v241, 48
	v_readlane_b32 s49, v247, 48
	v_readlane_b32 s38, v168, 0
	v_readlane_b32 s42, v174, 0
	v_readlane_b32 s46, v241, 0
	v_readlane_b32 s50, v247, 0
	v_readlane_b32 s39, v168, 32
	v_readlane_b32 s43, v174, 32
	v_readlane_b32 s47, v241, 32
	v_readlane_b32 s51, v247, 32
	v_mov_b32_e32 v168, s36
	v_mov_b32_e32 v174, s40
	v_mov_b32_e32 v241, s44
	v_mov_b32_e32 v247, s48
	v_mov_b32_e32 v169, s37
	v_mov_b32_e32 v175, s41
	v_mov_b32_e32 v242, s45
	v_mov_b32_e32 v248, s49
	v_add_f32_e32 v168, s38, v168
	v_add_f32_e32 v174, s42, v174
	v_add_f32_e32 v241, s46, v241
	v_add_f32_e32 v247, s50, v247
	v_add_f32_e32 v169, s39, v169
	v_add_f32_e32 v175, s43, v175
	v_add_f32_e32 v242, s47, v242
	v_add_f32_e32 v248, s51, v248
	v_add_f32_e32 v168, v168, v169
	v_add_f32_e32 v174, v174, v175
	v_add_f32_e32 v241, v241, v242
	v_add_f32_e32 v247, v247, v248
	v_fmamk_f32 v80, v168, 0xbc800000, v80
	v_fmamk_f32 v85, v174, 0xbc800000, v85
	v_fmamk_f32 v90, v241, 0xbc800000, v90
	v_fmamk_f32 v95, v247, 0xbc800000, v95
	v_mul_f32_e32 v168, v80, v80
	v_mul_f32_e32 v174, v85, v85
	v_mul_f32_e32 v241, v90, v90
	v_mul_f32_e32 v247, v95, v95
	v_mov_b32_dpp v168, v168 quad_perm:[1,0,3,2] row_mask:0xf bank_mask:0xf bound_ctrl:1
	v_mov_b32_dpp v174, v174 quad_perm:[1,0,3,2] row_mask:0xf bank_mask:0xf bound_ctrl:1
	v_mov_b32_dpp v241, v241 quad_perm:[1,0,3,2] row_mask:0xf bank_mask:0xf bound_ctrl:1
	v_mov_b32_dpp v247, v247 quad_perm:[1,0,3,2] row_mask:0xf bank_mask:0xf bound_ctrl:1
	v_fmac_f32_e32 v168, v80, v80
	v_fmac_f32_e32 v174, v85, v85
	v_fmac_f32_e32 v241, v90, v90
	v_fmac_f32_e32 v247, v95, v95
	v_add_f32_dpp v168, v168, v168 quad_perm:[2,3,0,1] row_mask:0xf bank_mask:0xf bound_ctrl:1
	v_add_f32_dpp v174, v174, v174 quad_perm:[2,3,0,1] row_mask:0xf bank_mask:0xf bound_ctrl:1
	v_add_f32_dpp v241, v241, v241 quad_perm:[2,3,0,1] row_mask:0xf bank_mask:0xf bound_ctrl:1
	v_add_f32_dpp v247, v247, v247 quad_perm:[2,3,0,1] row_mask:0xf bank_mask:0xf bound_ctrl:1
	v_add_f32_dpp v168, v168, v168 row_half_mirror row_mask:0xf bank_mask:0xf bound_ctrl:1
	v_add_f32_dpp v174, v174, v174 row_half_mirror row_mask:0xf bank_mask:0xf bound_ctrl:1
	v_add_f32_dpp v241, v241, v241 row_half_mirror row_mask:0xf bank_mask:0xf bound_ctrl:1
	v_add_f32_dpp v247, v247, v247 row_half_mirror row_mask:0xf bank_mask:0xf bound_ctrl:1
	v_add_f32_dpp v168, v168, v168 row_mirror row_mask:0xf bank_mask:0xf bound_ctrl:1
	v_add_f32_dpp v174, v174, v174 row_mirror row_mask:0xf bank_mask:0xf bound_ctrl:1
	v_add_f32_dpp v241, v241, v241 row_mirror row_mask:0xf bank_mask:0xf bound_ctrl:1
	v_add_f32_dpp v247, v247, v247 row_mirror row_mask:0xf bank_mask:0xf bound_ctrl:1
	v_readlane_b32 s36, v168, 16
	v_readlane_b32 s40, v174, 16
	v_readlane_b32 s44, v241, 16
	v_readlane_b32 s48, v247, 16
	v_readlane_b32 s37, v168, 48
	v_readlane_b32 s41, v174, 48
	v_readlane_b32 s45, v241, 48
	v_readlane_b32 s49, v247, 48
	v_readlane_b32 s38, v168, 0
	v_readlane_b32 s42, v174, 0
	v_readlane_b32 s46, v241, 0
	v_readlane_b32 s50, v247, 0
	v_readlane_b32 s39, v168, 32
	v_readlane_b32 s43, v174, 32
	v_readlane_b32 s47, v241, 32
	v_readlane_b32 s51, v247, 32
	v_mov_b32_e32 v168, s36
	v_mov_b32_e32 v174, s40
	v_mov_b32_e32 v241, s44
	v_mov_b32_e32 v247, s48
	v_mov_b32_e32 v169, s37
	v_mov_b32_e32 v175, s41
	v_mov_b32_e32 v242, s45
	v_mov_b32_e32 v248, s49
	v_add_f32_e32 v168, s38, v168
	v_add_f32_e32 v174, s42, v174
	v_add_f32_e32 v241, s46, v241
	v_add_f32_e32 v247, s50, v247
	v_add_f32_e32 v169, s39, v169
	v_add_f32_e32 v175, s43, v175
	v_add_f32_e32 v242, s47, v242
	v_add_f32_e32 v248, s51, v248
	v_add_f32_e32 v168, v168, v169
	v_add_f32_e32 v174, v174, v175
	v_add_f32_e32 v241, v241, v242
	v_add_f32_e32 v247, v247, v248
	v_fmamk_f32 v168, v168, 0x3c800000, v9
	v_fmamk_f32 v174, v174, 0x3c800000, v9
	v_fmamk_f32 v241, v241, 0x3c800000, v9
	v_fmamk_f32 v247, v247, 0x3c800000, v9
	v_readfirstlane_b32 s40, v174
	v_readfirstlane_b32 s44, v241
; __device__ __forceinline__ float bf2f(bf16 x) { return __uint_as_float(((unsigned)x) << 16); }
; __device__ __forceinline__ unsigned f2bf(float f) { return cvt_pk_bf16(f, 0.f) & 0xffffu; }
; __device__ __forceinline__ void rw_post(Frame& F) {
;     ...
;             for (int q = 0; q < 8; ++q) { const int row = rb0 + t0 + q;
;                 const float mean = wsum(y[q]) * (1.f / 64.f); const float dv = y[q] - mean; const float var = wsum(dv * dv) * (1.f / 64.f);
;                 const float yn = dv * (1.f / sqrtf(var + 64e-5f)) * g_ + b_;
;                 OB[(size_t)row * DH + col] = (bf16)f2bf((yn + rk[q] * vv[q]) * bf2f(gg[q])); }
	v_readfirstlane_b32 s48, v247
	v_writelane_b32 v168, s40, 1
	v_writelane_b32 v168, s44, 2
	v_writelane_b32 v168, s48, 3
	v_mul_f32_e32 v169, 0x4f800000, v168
	v_cmp_gt_f32_e64 s[52:53], s68, v168
	v_mov_b32_e32 v170, v168
	s_nop 1
	v_cndmask_b32_e64 v168, v170, v169, s[52:53]
	v_sqrt_f32_e32 v169, v168
	s_nop 0
	v_add_u32_e32 v170, -1, v169
	v_fma_f32 v171, -v170, v169, v168
	v_cmp_ge_f32_e64 s[60:61], 0, v171
	v_add_u32_e32 v171, 1, v169
	s_nop 1
	v_cndmask_b32_e64 v170, v169, v170, s[60:61]
	v_fma_f32 v169, -v171, v169, v168
	v_cmp_lt_f32_e64 s[60:61], 0, v169
	s_nop 1
	v_cndmask_b32_e64 v169, v170, v171, s[60:61]
	v_mul_f32_e32 v170, 0x37800000, v169
	v_cndmask_b32_e64 v169, v169, v170, s[52:53]
	v_cmp_class_f32_e64 s[60:61], v168, v8
	s_nop 1
	v_cndmask_b32_e64 v168, v169, v168, s[60:61]
	v_div_scale_f32 v169, s[60:61], v168, v168, 1.0
	v_rcp_f32_e32 v170, v169
	s_nop 0
	v_fma_f32 v171, -v169, v170, 1.0
	v_fmac_f32_e32 v170, v171, v170
	v_div_scale_f32 v171, vcc, 1.0, v168, 1.0
	v_mul_f32_e32 v172, v171, v170
	v_fma_f32 v173, -v169, v172, v171
	v_fmac_f32_e32 v172, v173, v170
	v_fma_f32 v169, -v169, v172, v171
	v_div_fmas_f32 v169, v169, v170, v172
	v_div_fixup_f32 v168, v169, v168, 1.0
	s_nop 0
	v_readlane_b32 s37, v168, 0
	v_readlane_b32 s41, v168, 1
	v_readlane_b32 s45, v168, 2
	v_readlane_b32 s49, v168, 3
	v_mul_f32_e32 v80, s37, v80
	v_mul_f32_e32 v85, s41, v85
	v_mul_f32_e32 v90, s45, v90
	v_mul_f32_e32 v95, s49, v95
	v_lshlrev_b32_e32 v83, 16, v83
	v_lshlrev_b32_e32 v88, 16, v88
	v_lshlrev_b32_e32 v93, 16, v93
	v_lshlrev_b32_e32 v98, 16, v98
	v_fma_f32 v80, v6, v80, v7
	v_fma_f32 v85, v6, v85, v7
	v_fma_f32 v90, v6, v90, v7
	v_fma_f32 v95, v6, v95, v7
	v_fmac_f32_e32 v80, s69, v81
	v_fmac_f32_e32 v85, s70, v86
	v_fmac_f32_e32 v90, s71, v91
	v_fmac_f32_e32 v95, s72, v96
	v_mul_f32_e32 v80, v80, v83
	v_mul_f32_e32 v85, v85, v88
	v_mul_f32_e32 v90, v90, v93
	v_mul_f32_e32 v95, v95, v98
	v_cvt_pk_bf16_f32 v169, v80, v80
	v_cvt_pk_bf16_f32 v175, v85, v85
	v_cvt_pk_bf16_f32 v242, v90, v90
	v_cvt_pk_bf16_f32 v248, v95, v95
	global_store_short v2, v169, s[28:29]
	s_add_u32 s28, s28, 0x1000
	s_addc_u32 s29, s29, 0
	global_store_short v2, v175, s[28:29]
	s_add_u32 s28, s28, 0x1000
	s_addc_u32 s29, s29, 0
	global_store_short v2, v242, s[28:29]
	s_add_u32 s28, s28, 0x1000
	s_addc_u32 s29, s29, 0
	global_store_short v2, v248, s[28:29]
	s_add_u32 s28, s28, 0x1000
	s_addc_u32 s29, s29, 0
	v_add_f32_e32 v100, v100, v32
	v_add_f32_e32 v105, v105, v33
	v_add_f32_e32 v110, v110, v34
	v_add_f32_e32 v115, v115, v35
	v_add_f32_dpp v168, v100, v100 quad_perm:[1,0,3,2] row_mask:0xf bank_mask:0xf bound_ctrl:1
	v_add_f32_dpp v174, v105, v105 quad_perm:[1,0,3,2] row_mask:0xf bank_mask:0xf bound_ctrl:1
	v_add_f32_dpp v241, v110, v110 quad_perm:[1,0,3,2] row_mask:0xf bank_mask:0xf bound_ctrl:1
	v_add_f32_dpp v247, v115, v115 quad_perm:[1,0,3,2] row_mask:0xf bank_mask:0xf bound_ctrl:1
	v_add_f32_dpp v168, v168, v168 quad_perm:[2,3,0,1] row_mask:0xf bank_mask:0xf bound_ctrl:1
	v_add_f32_dpp v174, v174, v174 quad_perm:[2,3,0,1] row_mask:0xf bank_mask:0xf bound_ctrl:1
	v_add_f32_dpp v241, v241, v241 quad_perm:[2,3,0,1] row_mask:0xf bank_mask:0xf bound_ctrl:1
	v_add_f32_dpp v247, v247, v247 quad_perm:[2,3,0,1] row_mask:0xf bank_mask:0xf bound_ctrl:1
	v_add_f32_dpp v168, v168, v168 row_half_mirror row_mask:0xf bank_mask:0xf bound_ctrl:1
	v_add_f32_dpp v174, v174, v174 row_half_mirror row_mask:0xf bank_mask:0xf bound_ctrl:1
	v_add_f32_dpp v241, v241, v241 row_half_mirror row_mask:0xf bank_mask:0xf bound_ctrl:1
	v_add_f32_dpp v247, v247, v247 row_half_mirror row_mask:0xf bank_mask:0xf bound_ctrl:1
	v_add_f32_dpp v168, v168, v168 row_mirror row_mask:0xf bank_mask:0xf bound_ctrl:1
	v_add_f32_dpp v174, v174, v174 row_mirror row_mask:0xf bank_mask:0xf bound_ctrl:1
	v_add_f32_dpp v241, v241, v241 row_mirror row_mask:0xf bank_mask:0xf bound_ctrl:1
	v_add_f32_dpp v247, v247, v247 row_mirror row_mask:0xf bank_mask:0xf bound_ctrl:1
	v_readlane_b32 s36, v168, 16
	v_readlane_b32 s40, v174, 16
	v_readlane_b32 s44, v241, 16
	v_readlane_b32 s48, v247, 16
	v_readlane_b32 s37, v168, 48
	v_readlane_b32 s41, v174, 48
	v_readlane_b32 s45, v241, 48
	v_readlane_b32 s49, v247, 48
	v_readlane_b32 s38, v168, 0
	v_readlane_b32 s42, v174, 0
	v_readlane_b32 s46, v241, 0
	v_readlane_b32 s50, v247, 0
	v_readlane_b32 s39, v168, 32
	v_readlane_b32 s43, v174, 32
	v_readlane_b32 s47, v241, 32
	v_readlane_b32 s51, v247, 32
	v_mov_b32_e32 v168, s36
	v_mov_b32_e32 v174, s40
	v_mov_b32_e32 v241, s44
	v_mov_b32_e32 v247, s48
	v_mov_b32_e32 v169, s37
	v_mov_b32_e32 v175, s41
	v_mov_b32_e32 v242, s45
	v_mov_b32_e32 v248, s49
	v_add_f32_e32 v168, s38, v168
	v_add_f32_e32 v174, s42, v174
	v_add_f32_e32 v241, s46, v241
	v_add_f32_e32 v247, s50, v247
	v_add_f32_e32 v169, s39, v169
	v_add_f32_e32 v175, s43, v175
	v_add_f32_e32 v242, s47, v242
	v_add_f32_e32 v248, s51, v248
	v_add_f32_e32 v168, v168, v169
	v_add_f32_e32 v174, v174, v175
	v_add_f32_e32 v241, v241, v242
	v_add_f32_e32 v247, v247, v248
	v_fmamk_f32 v100, v168, 0xbc800000, v100
	v_fmamk_f32 v105, v174, 0xbc800000, v105
	v_fmamk_f32 v110, v241, 0xbc800000, v110
	v_fmamk_f32 v115, v247, 0xbc800000, v115
	v_mul_f32_e32 v168, v100, v100
	v_mul_f32_e32 v174, v105, v105
	v_mul_f32_e32 v241, v110, v110
	v_mul_f32_e32 v247, v115, v115
	v_mov_b32_dpp v168, v168 quad_perm:[1,0,3,2] row_mask:0xf bank_mask:0xf bound_ctrl:1
	v_mov_b32_dpp v174, v174 quad_perm:[1,0,3,2] row_mask:0xf bank_mask:0xf bound_ctrl:1
	v_mov_b32_dpp v241, v241 quad_perm:[1,0,3,2] row_mask:0xf bank_mask:0xf bound_ctrl:1
	v_mov_b32_dpp v247, v247 quad_perm:[1,0,3,2] row_mask:0xf bank_mask:0xf bound_ctrl:1
; __device__ __forceinline__ float bf2f(bf16 x) { return __uint_as_float(((unsigned)x) << 16); }
; __device__ __forceinline__ unsigned f2bf(float f) { return cvt_pk_bf16(f, 0.f) & 0xffffu; }
; __device__ __forceinline__ void rw_post(Frame& F) {
;     ...
;             for (int q = 0; q < 8; ++q) { const int row = rb0 + t0 + q;
;                 const float mean = wsum(y[q]) * (1.f / 64.f); const float dv = y[q] - mean; const float var = wsum(dv * dv) * (1.f / 64.f);
;                 const float yn = dv * (1.f / sqrtf(var + 64e-5f)) * g_ + b_;
;                 OB[(size_t)row * DH + col] = (bf16)f2bf((yn + rk[q] * vv[q]) * bf2f(gg[q])); }
	v_fmac_f32_e32 v168, v100, v100
	v_fmac_f32_e32 v174, v105, v105
	v_fmac_f32_e32 v241, v110, v110
	v_fmac_f32_e32 v247, v115, v115
	v_add_f32_dpp v168, v168, v168 quad_perm:[2,3,0,1] row_mask:0xf bank_mask:0xf bound_ctrl:1
	v_add_f32_dpp v174, v174, v174 quad_perm:[2,3,0,1] row_mask:0xf bank_mask:0xf bound_ctrl:1
	v_add_f32_dpp v241, v241, v241 quad_perm:[2,3,0,1] row_mask:0xf bank_mask:0xf bound_ctrl:1
	v_add_f32_dpp v247, v247, v247 quad_perm:[2,3,0,1] row_mask:0xf bank_mask:0xf bound_ctrl:1
	v_add_f32_dpp v168, v168, v168 row_half_mirror row_mask:0xf bank_mask:0xf bound_ctrl:1
	v_add_f32_dpp v174, v174, v174 row_half_mirror row_mask:0xf bank_mask:0xf bound_ctrl:1
	v_add_f32_dpp v241, v241, v241 row_half_mirror row_mask:0xf bank_mask:0xf bound_ctrl:1
	v_add_f32_dpp v247, v247, v247 row_half_mirror row_mask:0xf bank_mask:0xf bound_ctrl:1
	v_add_f32_dpp v168, v168, v168 row_mirror row_mask:0xf bank_mask:0xf bound_ctrl:1
	v_add_f32_dpp v174, v174, v174 row_mirror row_mask:0xf bank_mask:0xf bound_ctrl:1
	v_add_f32_dpp v241, v241, v241 row_mirror row_mask:0xf bank_mask:0xf bound_ctrl:1
	v_add_f32_dpp v247, v247, v247 row_mirror row_mask:0xf bank_mask:0xf bound_ctrl:1
	v_readlane_b32 s36, v168, 16
	v_readlane_b32 s40, v174, 16
	v_readlane_b32 s44, v241, 16
	v_readlane_b32 s48, v247, 16
	v_readlane_b32 s37, v168, 48
	v_readlane_b32 s41, v174, 48
	v_readlane_b32 s45, v241, 48
	v_readlane_b32 s49, v247, 48
	v_readlane_b32 s38, v168, 0
	v_readlane_b32 s42, v174, 0
	v_readlane_b32 s46, v241, 0
	v_readlane_b32 s50, v247, 0
	v_readlane_b32 s39, v168, 32
	v_readlane_b32 s43, v174, 32
	v_readlane_b32 s47, v241, 32
	v_readlane_b32 s51, v247, 32
	v_mov_b32_e32 v168, s36
	v_mov_b32_e32 v174, s40
	v_mov_b32_e32 v241, s44
	v_mov_b32_e32 v247, s48
	v_mov_b32_e32 v169, s37
	v_mov_b32_e32 v175, s41
	v_mov_b32_e32 v242, s45
	v_mov_b32_e32 v248, s49
	v_add_f32_e32 v168, s38, v168
	v_add_f32_e32 v174, s42, v174
	v_add_f32_e32 v241, s46, v241
	v_add_f32_e32 v247, s50, v247
	v_add_f32_e32 v169, s39, v169
	v_add_f32_e32 v175, s43, v175
	v_add_f32_e32 v242, s47, v242
	v_add_f32_e32 v248, s51, v248
	v_add_f32_e32 v168, v168, v169
	v_add_f32_e32 v174, v174, v175
	v_add_f32_e32 v241, v241, v242
	v_add_f32_e32 v247, v247, v248
	v_fmamk_f32 v168, v168, 0x3c800000, v9
	v_fmamk_f32 v174, v174, 0x3c800000, v9
	v_fmamk_f32 v241, v241, 0x3c800000, v9
	v_fmamk_f32 v247, v247, 0x3c800000, v9
	v_readfirstlane_b32 s40, v174
	v_readfirstlane_b32 s44, v241
	v_readfirstlane_b32 s48, v247
	v_writelane_b32 v168, s40, 1
	v_writelane_b32 v168, s44, 2
	v_writelane_b32 v168, s48, 3
	v_mul_f32_e32 v169, 0x4f800000, v168
	v_cmp_gt_f32_e64 s[52:53], s68, v168
	v_mov_b32_e32 v170, v168
	s_nop 1
	v_cndmask_b32_e64 v168, v170, v169, s[52:53]
	v_sqrt_f32_e32 v169, v168
	s_nop 0
	v_add_u32_e32 v170, -1, v169
	v_fma_f32 v171, -v170, v169, v168
	v_cmp_ge_f32_e64 s[60:61], 0, v171
	v_add_u32_e32 v171, 1, v169
	s_nop 1
	v_cndmask_b32_e64 v170, v169, v170, s[60:61]
	v_fma_f32 v169, -v171, v169, v168
	v_cmp_lt_f32_e64 s[60:61], 0, v169
	s_nop 1
	v_cndmask_b32_e64 v169, v170, v171, s[60:61]
	v_mul_f32_e32 v170, 0x37800000, v169
	v_cndmask_b32_e64 v169, v169, v170, s[52:53]
	v_cmp_class_f32_e64 s[60:61], v168, v8
	s_nop 1
	v_cndmask_b32_e64 v168, v169, v168, s[60:61]
	v_div_scale_f32 v169, s[60:61], v168, v168, 1.0
	v_rcp_f32_e32 v170, v169
	s_nop 0
	v_fma_f32 v171, -v169, v170, 1.0
	v_fmac_f32_e32 v170, v171, v170
	v_div_scale_f32 v171, vcc, 1.0, v168, 1.0
	v_mul_f32_e32 v172, v171, v170
	v_fma_f32 v173, -v169, v172, v171
	v_fmac_f32_e32 v172, v173, v170
	v_fma_f32 v169, -v169, v172, v171
	v_div_fmas_f32 v169, v169, v170, v172
	v_div_fixup_f32 v168, v169, v168, 1.0
	s_nop 0
	v_readlane_b32 s37, v168, 0
	v_readlane_b32 s41, v168, 1
	v_readlane_b32 s45, v168, 2
	v_readlane_b32 s49, v168, 3
	v_mul_f32_e32 v100, s37, v100
	v_mul_f32_e32 v105, s41, v105
	v_mul_f32_e32 v110, s45, v110
	v_mul_f32_e32 v115, s49, v115
	v_lshlrev_b32_e32 v103, 16, v103
	v_lshlrev_b32_e32 v108, 16, v108
	v_lshlrev_b32_e32 v113, 16, v113
	v_lshlrev_b32_e32 v118, 16, v118
	v_fma_f32 v100, v6, v100, v7
	v_fma_f32 v105, v6, v105, v7
	v_fma_f32 v110, v6, v110, v7
	v_fma_f32 v115, v6, v115, v7
	v_fmac_f32_e32 v100, s73, v101
	v_fmac_f32_e32 v105, s26, v106
	v_fmac_f32_e32 v110, s27, v111
	v_fmac_f32_e32 v115, s32, v116
	v_mul_f32_e32 v100, v100, v103
	v_mul_f32_e32 v105, v105, v108
	v_mul_f32_e32 v110, v110, v113
	v_mul_f32_e32 v115, v115, v118
	v_cvt_pk_bf16_f32 v169, v100, v100
	v_cvt_pk_bf16_f32 v175, v105, v105
	v_cvt_pk_bf16_f32 v242, v110, v110
	v_cvt_pk_bf16_f32 v248, v115, v115
	global_store_short v2, v169, s[28:29]
	s_add_u32 s28, s28, 0x1000
	s_addc_u32 s29, s29, 0
	global_store_short v2, v175, s[28:29]
	s_add_u32 s28, s28, 0x1000
	s_addc_u32 s29, s29, 0
	global_store_short v2, v242, s[28:29]
	s_add_u32 s28, s28, 0x1000
	s_addc_u32 s29, s29, 0
	global_store_short v2, v248, s[28:29]
	s_add_u32 s28, s28, 0x1000
	s_addc_u32 s29, s29, 0
; #define LAS __attribute__((address_space(3)))
;     if (ldw == 0) ldw = N;
;     LAS float* scr = (LAS float*)(F.lds + F.wave * 16384); const int lane = F.lane;
;     const int nblk = N / 32, nitems = (K / 64) * nblk;
;     for (int item = F.gw; item < nitems; item += F.NGW) { const int kb = item / nblk, nb = item % nblk, k0 = 64 * kb, n0 = 32 * nb;
;         int dr0 = n0; if (MAP == 1) { if (n0 < DFF) dr0 = (n0 >> 7) * 256 + (n0 & 127); else { const int uo = n0 - DFF; dr0 = (uo >> 7) * 256 + 128 + (uo & 127); } }
; #pragma unroll 8
;         for (int i = 0; i < 32; ++i) { const int kk = 2 * i + (lane >> 5); scr[kk * 33 + (lane & 31)] = W[(size_t)(k0 + kk) * ldw + n0 + (lane & 31)]; }
.Lpo_done:
.LBB0_1169:
	v_readlane_b32 s56, v240, 17
	v_readlane_b32 s57, v240, 18
.LBB0_1170:
	v_readlane_b32 s0, v240, 3
	v_readlane_b32 s1, v240, 4
	v_readlane_b32 s80, v240, 31
	s_andn2_b64 vcc, exec, s[0:1]
	v_lshlrev_b32_e32 v2, 2, v164
	v_readlane_b32 s81, v240, 32
	s_cbranch_vccnz .LBB0_1179
	s_barrier
	s_load_dwordx2 s[50:51], s[74:75], 0xf0
	v_readlane_b32 s16, v240, 2
	v_lshlrev_b32_e32 v212, 4, v178
	v_mov_b32_e32 v216, 0x42fe0000
	s_mov_b32 s36, 0x44fe0000
	s_mov_b32 s37, 0
	s_mov_b32 s38, 0x4b400000
	s_mov_b32 s39, 0
	s_mov_b32 s40, 0xc2fe0000
	s_mov_b32 s41, 0x0c0c0400
	s_mov_b32 s42, 0x05040100
	s_lshl_b32 s17, s16, 5
	s_and_b32 s18, s16, 4
	s_lshl_b32 s18, s18, 5
	s_add_i32 s17, s17, s18
	v_mul_u32_u24_e32 v213, 0x240, v178
	s_lshl_b32 s18, s16, 4
	v_add_u32_e32 v213, s18, v213
	v_lshrrev_b32_e32 v204, 3, v178
	v_and_b32_e32 v205, 7, v178
	s_lshl_b32 s18, s16, 5
	v_add_u32_e32 v206, s18, v204
	v_mul_u32_u24_e32 v214, 0x90, v206
	v_lshl_add_u32 v214, v205, 4, v214
	v_mul_u32_u24_e32 v215, 0x1000, v204
	v_lshl_add_u32 v215, v205, 4, v215
	s_lshl_b32 s16, s16, 4
	s_waitcnt lgkmcnt(0)
	s_add_u32 s44, s90, 0x8300000
	s_addc_u32 s45, s91, 0
	s_sub_i32 s19, 0xff, s2
	s_cmp_lt_u32 s19, 0xac0
	s_cbranch_scc0 .Lf8t_f2in0_end
	s_mul_hi_u32 s20, s19, 0x2fa0be9
	s_mul_i32 s21, s20, 86
	s_sub_i32 s21, s19, s21
	s_lshl_b32 s60, s20, 7
	s_lshl_b32 s61, s21, 8
	s_add_i32 s24, s60, s16
	s_mul_i32 s24, s24, 0x15800
	s_lshl_b32 s25, s61, 2
	s_add_u32 s24, s24, s25
	s_add_u32 s52, s50, s24
	s_addc_u32 s53, s51, 0
	global_load_dwordx4 v[80:83], v212, s[52:53]
	s_add_u32 s52, s52, 0x15800
	s_addc_u32 s53, s53, 0
	global_load_dwordx4 v[84:87], v212, s[52:53]
	s_add_u32 s52, s52, 0x15800
	s_addc_u32 s53, s53, 0
	global_load_dwordx4 v[88:91], v212, s[52:53]
	s_add_u32 s52, s52, 0x15800
	s_addc_u32 s53, s53, 0
	global_load_dwordx4 v[92:95], v212, s[52:53]
	s_add_u32 s52, s52, 0x15800
	s_addc_u32 s53, s53, 0
	global_load_dwordx4 v[96:99], v212, s[52:53]
	s_add_u32 s52, s52, 0x15800
	s_addc_u32 s53, s53, 0
	global_load_dwordx4 v[100:103], v212, s[52:53]
	s_add_u32 s52, s52, 0x15800
	s_addc_u32 s53, s53, 0
	global_load_dwordx4 v[104:107], v212, s[52:53]
	s_add_u32 s52, s52, 0x15800
	s_addc_u32 s53, s53, 0
	global_load_dwordx4 v[108:111], v212, s[52:53]
	s_add_u32 s52, s52, 0x15800
	s_addc_u32 s53, s53, 0
	global_load_dwordx4 v[112:115], v212, s[52:53]
	s_add_u32 s52, s52, 0x15800
	s_addc_u32 s53, s53, 0
	global_load_dwordx4 v[116:119], v212, s[52:53]
	s_add_u32 s52, s52, 0x15800
	s_addc_u32 s53, s53, 0
	global_load_dwordx4 v[120:123], v212, s[52:53]
	s_add_u32 s52, s52, 0x15800
	s_addc_u32 s53, s53, 0
	global_load_dwordx4 v[124:127], v212, s[52:53]
	s_add_u32 s52, s52, 0x15800
	s_addc_u32 s53, s53, 0
	global_load_dwordx4 v[128:131], v212, s[52:53]
	s_add_u32 s52, s52, 0x15800
	s_addc_u32 s53, s53, 0
	global_load_dwordx4 v[132:135], v212, s[52:53]
	s_add_u32 s52, s52, 0x15800
	s_addc_u32 s53, s53, 0
	global_load_dwordx4 v[136:139], v212, s[52:53]
	s_add_u32 s52, s52, 0x15800
	s_addc_u32 s53, s53, 0
	global_load_dwordx4 v[140:143], v212, s[52:53]
	s_mov_b32 s58, 1

; #define LAS __attribute__((address_space(3)))
;     if (ldw == 0) ldw = N;
;     LAS float* scr = (LAS float*)(F.lds + F.wave * 16384); const int lane = F.lane;
;     const int nblk = N / 32, nitems = (K / 64) * nblk;
;     for (int item = F.gw; item < nitems; item += F.NGW) { const int kb = item / nblk, nb = item % nblk, k0 = 64 * kb, n0 = 32 * nb;
;         int dr0 = n0; if (MAP == 1) { if (n0 < DFF) dr0 = (n0 >> 7) * 256 + (n0 & 127); else { const int uo = n0 - DFF; dr0 = (uo >> 7) * 256 + 128 + (uo & 127); } }
; #pragma unroll 8
;         for (int i = 0; i < 32; ++i) { const int kk = 2 * i + (lane >> 5); scr[kk * 33 + (lane & 31)] = W[(size_t)(k0 + kk) * ldw + n0 + (lane & 31)]; }
.LBB0_1179:
	v_readlane_b32 s0, v240, 5
	v_readlane_b32 s1, v240, 6
	s_andn2_b64 vcc, exec, s[0:1]
	s_cbranch_vccnz .LBB0_1184
	s_barrier
	s_load_dwordx2 s[50:51], s[74:75], 0xf8
	v_readlane_b32 s16, v240, 2
	v_lshlrev_b32_e32 v212, 4, v178
	v_mov_b32_e32 v216, 0x42fe0000
	s_mov_b32 s36, 0x43000000
	s_mov_b32 s37, 0
	s_mov_b32 s38, 0x4b400000
	s_mov_b32 s39, 0
	s_mov_b32 s40, 0xc2fe0000
	s_mov_b32 s41, 0x0c0c0400
	s_mov_b32 s42, 0x05040100
	s_lshl_b32 s17, s16, 5
	v_mul_u32_u24_e32 v213, 0x240, v178
	s_lshl_b32 s18, s16, 4
	v_add_u32_e32 v213, s18, v213
	v_lshrrev_b32_e32 v204, 3, v178
	v_and_b32_e32 v205, 7, v178
	s_lshl_b32 s18, s16, 5
	v_add_u32_e32 v206, s18, v204
	v_mul_u32_u24_e32 v214, 0x90, v206
	v_lshl_add_u32 v214, v205, 4, v214
	v_mul_u32_u24_e32 v215, 0x2b00, v204
	v_lshl_add_u32 v215, v205, 4, v215
	s_lshl_b32 s16, s16, 4
	s_waitcnt lgkmcnt(0)
	s_add_u32 s44, s90, 0x12f00000
	s_addc_u32 s45, s91, 0
	s_sub_i32 s19, 0xff, s2
	s_cmp_lt_u32 s19, 0x560
	s_cbranch_scc0 .Lf8t_f2dn0_end
	s_mul_hi_u32 s20, s19, 0x10000000
	s_mul_i32 s21, s20, 16
	s_sub_i32 s21, s19, s21
	s_lshl_b32 s60, s20, 7
	s_lshl_b32 s61, s21, 8
	s_add_i32 s24, s60, s16
	s_mul_i32 s24, s24, 0x4000
	s_lshl_b32 s25, s61, 2
	s_add_u32 s24, s24, s25
	s_add_u32 s52, s50, s24
	s_addc_u32 s53, s51, 0
	global_load_dwordx4 v[80:83], v212, s[52:53]
	s_add_u32 s52, s52, 0x4000
	s_addc_u32 s53, s53, 0
	global_load_dwordx4 v[84:87], v212, s[52:53]
	s_add_u32 s52, s52, 0x4000
	s_addc_u32 s53, s53, 0
	global_load_dwordx4 v[88:91], v212, s[52:53]
	s_add_u32 s52, s52, 0x4000
	s_addc_u32 s53, s53, 0
	global_load_dwordx4 v[92:95], v212, s[52:53]
	s_add_u32 s52, s52, 0x4000
	s_addc_u32 s53, s53, 0
	global_load_dwordx4 v[96:99], v212, s[52:53]
	s_add_u32 s52, s52, 0x4000
	s_addc_u32 s53, s53, 0
	global_load_dwordx4 v[100:103], v212, s[52:53]
	s_add_u32 s52, s52, 0x4000
	s_addc_u32 s53, s53, 0
	global_load_dwordx4 v[104:107], v212, s[52:53]
	s_add_u32 s52, s52, 0x4000
	s_addc_u32 s53, s53, 0
	global_load_dwordx4 v[108:111], v212, s[52:53]
	s_add_u32 s52, s52, 0x4000
	s_addc_u32 s53, s53, 0
	global_load_dwordx4 v[112:115], v212, s[52:53]
	s_add_u32 s52, s52, 0x4000
	s_addc_u32 s53, s53, 0
	global_load_dwordx4 v[116:119], v212, s[52:53]
	s_add_u32 s52, s52, 0x4000
	s_addc_u32 s53, s53, 0
	global_load_dwordx4 v[120:123], v212, s[52:53]
	s_add_u32 s52, s52, 0x4000
	s_addc_u32 s53, s53, 0
	global_load_dwordx4 v[124:127], v212, s[52:53]
	s_add_u32 s52, s52, 0x4000
	s_addc_u32 s53, s53, 0
	global_load_dwordx4 v[128:131], v212, s[52:53]
	s_add_u32 s52, s52, 0x4000
	s_addc_u32 s53, s53, 0
	global_load_dwordx4 v[132:135], v212, s[52:53]
	s_add_u32 s52, s52, 0x4000
	s_addc_u32 s53, s53, 0
	global_load_dwordx4 v[136:139], v212, s[52:53]
	s_add_u32 s52, s52, 0x4000
	s_addc_u32 s53, s53, 0
	global_load_dwordx4 v[140:143], v212, s[52:53]
	s_mov_b32 s58, 1
